# write-through stores for P0/P1/P2/P9 outputs and no L2 write-back in the four barriers that follow them
# baseline (speedup 1.0000x reference)
; __global__ void __launch_bounds__(NTHR, 2) fwd_kernel(Args a) {
;     ...
;             if (lane < 48) {
; #pragma unroll
;                 for (int r = 0; r < 5; ++r) red[(wave * 5 + r) * 48 + lane] = acc[r];
;             }
;             __syncthreads();
;             if (tid < 240) { const int r = tid / 48, c = tid % 48; float s = a.in[I_BADA][cb * 48 + c];
; #pragma unroll
;                 for (int w = 0; w < 8; ++w) s += red[(w * 5 + r) * 48 + c];
;                 mod[r * MODW + cb * 48 + c] = s; }
.LBB0_107:
	s_or_b64 exec, exec, s[4:5]
	s_waitcnt lgkmcnt(0)
	s_barrier
	s_and_saveexec_b64 s[4:5], s[2:3]
	s_cbranch_execz .LBB0_102
	v_mad_u64_u32 v[4:5], s[12:13], s31, 48, v[0:1]
	v_readlane_b32 s36, v254, 1
	v_ashrrev_i32_e32 v5, 31, v4
	v_readlane_b32 s46, v254, 11
	v_readlane_b32 s47, v254, 12
	v_add_u32_e32 v8, 0xa780, v13
	v_add_u32_e32 v10, 0xaf00, v13
	v_lshl_add_u64 v[6:7], v[4:5], 2, s[46:47]
	global_load_dword v3, v[6:7], off
	v_add_u32_e32 v5, 0xa000, v13
	v_add_u32_e32 v14, 0xb680, v13
	ds_read2_b32 v[6:7], v5 offset1:240
	ds_read2_b32 v[8:9], v8 offset1:240
	ds_read2_b32 v[10:11], v10 offset1:240
	ds_read2_b32 v[14:15], v14 offset1:240
	v_add_u32_e32 v4, v4, v1
	v_ashrrev_i32_e32 v5, 31, v4
	v_lshl_add_u64 v[4:5], v[4:5], 2, s[68:69]
	v_readlane_b32 s37, v254, 2
	v_readlane_b32 s38, v254, 3
	v_readlane_b32 s39, v254, 4
	v_readlane_b32 s40, v254, 5
	v_readlane_b32 s41, v254, 6
	v_readlane_b32 s42, v254, 7
	v_readlane_b32 s43, v254, 8
	v_readlane_b32 s44, v254, 9
	v_readlane_b32 s45, v254, 10
	v_readlane_b32 s48, v254, 13
	v_readlane_b32 s49, v254, 14
	v_readlane_b32 s50, v254, 15
	v_readlane_b32 s51, v254, 16
	s_waitcnt vmcnt(0) lgkmcnt(3)
	v_add_f32_e32 v3, v3, v6
	v_add_f32_e32 v3, v3, v7
	s_waitcnt lgkmcnt(2)
	v_add_f32_e32 v3, v3, v8
	v_add_f32_e32 v3, v3, v9
	s_waitcnt lgkmcnt(1)
	v_add_f32_e32 v3, v3, v10
	v_add_f32_e32 v3, v3, v11
	s_waitcnt lgkmcnt(0)
	v_add_f32_e32 v3, v3, v14
	v_add_f32_e32 v3, v3, v15
	global_store_dword v[4:5], v3, off sc1
	s_branch .LBB0_102

; __device__ __forceinline__ unsigned xb_add(unsigned* p, unsigned v) { return __hip_atomic_fetch_add(p, v, __ATOMIC_RELAXED, __HIP_MEMORY_SCOPE_AGENT); }
; __device__ __forceinline__ void xcd_barrier(const XcdBarrier& b) {
;     ...
;         if (old + 1u == (gen + 1u) * nloc) {
;             __builtin_amdgcn_fence(__ATOMIC_RELEASE, "agent");
;             asm volatile("s_waitcnt vmcnt(0)" ::: "memory");
;             const unsigned og = xb_add(&bar[XB_TOP], 1u);
.LBB0_141:
	s_andn2_saveexec_b64 s[4:5], s[4:5]
	s_cbranch_execz .LBB0_161
	s_mov_b64 s[4:5], exec
	s_waitcnt lgkmcnt(0)
	s_waitcnt vmcnt(0)
	v_mbcnt_lo_u32_b32 v1, s4, 0
	v_mbcnt_hi_u32_b32 v1, s5, v1
	v_cmp_eq_u32_e32 vcc, 0, v1
	s_and_saveexec_b64 s[12:13], vcc
	s_cbranch_execz .LBB0_144
	s_bcnt1_i32_b64 s4, s[4:5]
	v_mov_b32_e32 v2, 0x7000
	v_mov_b32_e32 v3, s4
	global_atomic_add v2, v2, v3, s[66:67] offset:1024 sc0

; __global__ void __launch_bounds__(NTHR, 2) fwd_kernel(Args a) {
;     ...
;     for (int m = gw; m < MT; m += NGW) {
;         const float* src = m < M ? a.in[I_X] + (size_t)m * DM : a.in[I_CTX] + (size_t)(m - M) * DM;
;         const float* md = mod + (m < M ? (m >> 11) : 4) * MODW;
;         f32x4 v[8]; float ss = 0.f;
; #pragma unroll
;         for (int j = 0; j < 8; ++j) { v[j] = *(const f32x4*)(src + j * 256 + lane * 4); ss += (v[j][0] * v[j][0] + v[j][1] * v[j][1]) + (v[j][2] * v[j][2] + v[j][3] * v[j][3]); }
;         const float rstd = rsqrtf(wave_sum(ss) * (1.0f / DM) + EPS);
.LBB0_163:
	global_load_dwordx4 v[48:51], v20, s[14:15]
	global_load_dwordx4 v[52:55], v20, s[14:15] offset:1024
	global_load_dwordx4 v[56:59], v20, s[14:15] offset:2048
	global_load_dwordx4 v[16:19], v20, s[14:15] offset:3072
	v_lshl_add_u64 v[0:1], s[14:15], 0, v[20:21]
	v_add_co_u32_e32 v4, vcc, s20, v0
	s_min_i32 s0, s2, 0x2000
	s_nop 0
	v_addc_co_u32_e32 v5, vcc, 0, v1, vcc
	global_load_dwordx4 v[8:11], v[4:5], off
	global_load_dwordx4 v[12:15], v[4:5], off offset:1024
	global_load_dwordx4 v[0:3], v[4:5], off offset:3072
	s_nop 0
	global_load_dwordx4 v[4:7], v[4:5], off offset:2048
	s_lshr_b32 s0, s0, 11
	s_mul_i32 s14, s0, 0x3000
	s_ashr_i32 s15, s14, 31
	s_lshl_b64 s[14:15], s[14:15], 2
	s_add_u32 s14, s68, s14
	s_addc_u32 s15, s69, s15
	s_add_u32 s16, s14, 0x2000
	global_load_dwordx4 v[60:63], v[22:23], off
	s_addc_u32 s17, s15, 0
	global_load_dwordx4 v[64:67], v20, s[14:15]
	global_load_dwordx4 v[68:71], v20, s[16:17]
	global_load_dwordx4 v[96:99], v[22:23], off offset:1024
	global_load_dwordx4 v[100:103], v41, s[16:17]
	global_load_dwordx4 v[104:107], v20, s[14:15] offset:1024
	global_load_dwordx4 v[108:111], v[22:23], off offset:2048
	global_load_dwordx4 v[112:115], v42, s[16:17]
	global_load_dwordx4 v[116:119], v20, s[14:15] offset:2048
	global_load_dwordx4 v[120:123], v[22:23], off offset:3072
	global_load_dwordx4 v[124:127], v43, s[16:17]
	global_load_dwordx4 v[128:131], v20, s[14:15] offset:3072
	global_load_dwordx4 v[132:135], v[24:25], off
	global_load_dwordx4 v[136:139], v44, s[16:17]
	global_load_dwordx4 v[140:143], v44, s[14:15]
	global_load_dwordx4 v[144:147], v[26:27], off
	global_load_dwordx4 v[148:151], v45, s[16:17]
	global_load_dwordx4 v[152:155], v45, s[14:15]
	global_load_dwordx4 v[156:159], v[28:29], off
	global_load_dwordx4 v[160:163], v46, s[16:17]
	global_load_dwordx4 v[164:167], v46, s[14:15]
	global_load_dwordx4 v[168:171], v[30:31], off
	global_load_dwordx4 v[172:175], v47, s[16:17]
	global_load_dwordx4 v[176:179], v47, s[14:15]
	s_lshl_b64 s[18:19], s[18:19], 12
	s_add_u32 s2, s2, s70
	s_addc_u32 s3, s3, s71
	s_add_u32 s4, s4, s12
	s_addc_u32 s5, s5, s13
	s_cmpk_gt_i32 s2, 0x23ff
	s_waitcnt vmcnt(31)
	v_mov_b32_e32 v74, v49
	s_waitcnt vmcnt(30)
	v_mov_b32_e32 v75, v53
	v_mov_b32_e32 v78, v51
	v_mov_b32_e32 v79, v55
	v_mov_b32_e32 v72, v48
	v_mov_b32_e32 v73, v52
	v_mov_b32_e32 v76, v50
	v_mov_b32_e32 v77, v54
	s_waitcnt vmcnt(29)
	v_pk_mul_f32 v[80:81], v[58:59], v[58:59]
	v_pk_mul_f32 v[82:83], v[56:57], v[56:57]
	v_pk_mul_f32 v[74:75], v[74:75], v[74:75]
	v_pk_mul_f32 v[78:79], v[78:79], v[78:79]
	v_pk_mov_b32 v[88:89], v[82:83], v[80:81] op_sel:[1,0]
	v_mov_b32_e32 v83, v81
	v_pk_fma_f32 v[72:73], v[72:73], v[72:73], v[74:75]
	v_pk_fma_f32 v[74:75], v[76:77], v[76:77], v[78:79]
	s_waitcnt vmcnt(28)
	v_mul_f32_e32 v84, v17, v17
	v_mul_f32_e32 v86, v19, v19
	v_pk_add_f32 v[76:77], v[88:89], v[82:83]
	v_pk_add_f32 v[72:73], v[72:73], v[74:75]
	v_pk_fma_f32 v[80:81], v[16:17], v[16:17], v[84:85] op_sel_hi:[1,1,0]
	v_pk_fma_f32 v[84:85], v[18:19], v[18:19], v[86:87] op_sel_hi:[1,1,0]
	s_waitcnt vmcnt(27)
	v_mul_f32_e32 v89, v8, v8
	v_mul_f32_e32 v90, v9, v9
	v_pk_add_f32 v[74:75], v[76:77], v[76:77] op_sel:[0,1] op_sel_hi:[1,0]
	v_pk_add_f32 v[72:73], v[72:73], v[72:73] op_sel:[0,1] op_sel_hi:[1,0]
	v_mul_f32_e32 v81, v10, v10
	v_mul_f32_e32 v85, v11, v11
	s_waitcnt vmcnt(26)
	v_pk_mul_f32 v[78:79], v[14:15], v[14:15]
	v_pk_mul_f32 v[82:83], v[12:13], v[12:13]
	v_mov_b32_e32 v75, v90
	v_mov_b32_e32 v73, v89
	v_pk_mov_b32 v[76:77], v[82:83], v[78:79] op_sel:[1,0]
	v_mov_b32_e32 v83, v79
	v_pk_add_f32 v[80:81], v[80:81], v[84:85]
	v_pk_add_f32 v[72:73], v[72:73], v[74:75]
	s_waitcnt vmcnt(24)
	v_mul_f32_e32 v86, v5, v5
	v_mul_f32_e32 v88, v7, v7
	v_pk_add_f32 v[76:77], v[76:77], v[82:83]
	v_pk_add_f32 v[72:73], v[72:73], v[80:81]
	v_mul_f32_e32 v91, v0, v0
	v_mul_f32_e32 v92, v1, v1
	v_mul_f32_e32 v93, v2, v2
	v_mul_f32_e32 v94, v3, v3
	v_pk_fma_f32 v[78:79], v[4:5], v[4:5], v[86:87] op_sel_hi:[1,1,0]
	v_pk_fma_f32 v[86:87], v[6:7], v[6:7], v[88:89] op_sel_hi:[1,1,0]
	v_pk_add_f32 v[76:77], v[76:77], v[76:77] op_sel:[0,1] op_sel_hi:[1,0]
	v_pk_add_f32 v[72:73], v[72:73], v[72:73] op_sel:[0,1] op_sel_hi:[1,0]
	v_mov_b32_e32 v79, v93
	v_mov_b32_e32 v87, v94
	v_mov_b32_e32 v77, v92
	v_mov_b32_e32 v73, v91
	v_pk_add_f32 v[78:79], v[78:79], v[86:87]
	v_pk_add_f32 v[72:73], v[72:73], v[76:77]
	s_waitcnt vmcnt(21)
	v_pk_add_f32 v[70:71], v[70:71], 1.0 op_sel_hi:[1,0]
	v_pk_add_f32 v[72:73], v[72:73], v[78:79]
	v_pk_add_f32 v[68:69], v[68:69], 1.0 op_sel_hi:[1,0]
	v_add_f32_e32 v72, v72, v73
	ds_bpermute_b32 v73, v34, v72
	s_waitcnt lgkmcnt(0)
	v_add_f32_e32 v72, v72, v73
	ds_bpermute_b32 v73, v35, v72
	s_waitcnt lgkmcnt(0)
	v_add_f32_e32 v72, v72, v73
	ds_bpermute_b32 v73, v36, v72
	s_waitcnt lgkmcnt(0)
	v_add_f32_e32 v72, v72, v73
	ds_bpermute_b32 v73, v37, v72
	s_waitcnt lgkmcnt(0)
	v_add_f32_e32 v72, v72, v73
	ds_bpermute_b32 v73, v38, v72
	s_waitcnt lgkmcnt(0)
	v_add_f32_e32 v72, v72, v73
	ds_bpermute_b32 v73, v39, v72
	s_waitcnt lgkmcnt(0)
; __device__ __forceinline__ void st_bf4(bf16_t* p, f32x4 v) { u32x2 w; w.x = pk2(v[0], v[1]); w.y = pk2(v[2], v[3]); *(u32x2*)p = w; }
; __global__ void __launch_bounds__(NTHR, 2) fwd_kernel(Args a) {
;     ...
;         const float rstd = rsqrtf(wave_sum(ss) * (1.0f / DM) + EPS);
; #pragma unroll
;         for (int j = 0; j < 8; ++j) { const int c = j * 256 + lane * 4;
;             const f32x4 g = *(const f32x4*)(a.in[I_G1] + c), sh = *(const f32x4*)(md + c), sc = *(const f32x4*)(md + DM + c);
;             st_bf4(H1 + (size_t)m * DM + c, (v[j] * rstd * g) * (sc + 1.0f) + sh); }
	v_add_f32_e32 v72, v72, v73
	v_fmamk_f32 v72, v72, 0x3a000000, v40
	v_mul_f32_e32 v73, 0x4b800000, v72
	v_cmp_gt_f32_e32 vcc, s21, v72
	s_nop 1
	v_cndmask_b32_e32 v72, v72, v73, vcc
	v_rsq_f32_e32 v74, v72
	v_lshl_add_u64 v[72:73], v[32:33], 0, s[18:19]
	v_mul_f32_e32 v75, 0x45800000, v74
	v_cndmask_b32_e32 v74, v74, v75, vcc
	v_pk_mul_f32 v[50:51], v[74:75], v[50:51] op_sel_hi:[0,1]
	v_pk_mul_f32 v[48:49], v[74:75], v[48:49] op_sel_hi:[0,1]
	v_pk_mul_f32 v[48:49], v[60:61], v[48:49]
	v_pk_mul_f32 v[50:51], v[62:63], v[50:51]
	v_pk_fma_f32 v[48:49], v[68:69], v[48:49], v[64:65]
	v_pk_fma_f32 v[50:51], v[70:71], v[50:51], v[66:67]
	v_cvt_pk_bf16_f32 v48, v48, v49
	v_cvt_pk_bf16_f32 v49, v50, v51
	global_store_dwordx2 v[72:73], v[48:49], off sc1
	s_nop 0
	v_pk_mul_f32 v[54:55], v[74:75], v[54:55] op_sel_hi:[0,1]
	v_pk_mul_f32 v[52:53], v[74:75], v[52:53] op_sel_hi:[0,1]
	v_pk_mul_f32 v[58:59], v[74:75], v[58:59] op_sel_hi:[0,1]
	v_pk_mul_f32 v[56:57], v[74:75], v[56:57] op_sel_hi:[0,1]
	v_pk_mul_f32 v[18:19], v[74:75], v[18:19] op_sel_hi:[0,1]
	v_pk_mul_f32 v[16:17], v[74:75], v[16:17] op_sel_hi:[0,1]
	v_pk_mul_f32 v[10:11], v[74:75], v[10:11] op_sel_hi:[0,1]
	v_pk_mul_f32 v[8:9], v[74:75], v[8:9] op_sel_hi:[0,1]
	v_pk_mul_f32 v[14:15], v[74:75], v[14:15] op_sel_hi:[0,1]
	v_pk_mul_f32 v[12:13], v[74:75], v[12:13] op_sel_hi:[0,1]
	v_pk_mul_f32 v[6:7], v[74:75], v[6:7] op_sel_hi:[0,1]
	v_pk_mul_f32 v[4:5], v[74:75], v[4:5] op_sel_hi:[0,1]
	v_pk_mul_f32 v[2:3], v[74:75], v[2:3] op_sel_hi:[0,1]
	v_pk_mul_f32 v[0:1], v[74:75], v[0:1] op_sel_hi:[0,1]
	s_waitcnt vmcnt(21)
	v_pk_mul_f32 v[48:49], v[96:97], v[52:53]
	v_pk_mul_f32 v[50:51], v[98:99], v[54:55]
	s_waitcnt vmcnt(20)
	v_pk_add_f32 v[52:53], v[102:103], 1.0 op_sel_hi:[1,0]
	v_pk_add_f32 v[54:55], v[100:101], 1.0 op_sel_hi:[1,0]
	s_waitcnt vmcnt(19)
	v_pk_fma_f32 v[50:51], v[52:53], v[50:51], v[106:107]
	v_pk_fma_f32 v[48:49], v[54:55], v[48:49], v[104:105]
	s_nop 0
	v_cvt_pk_bf16_f32 v48, v48, v49
	v_cvt_pk_bf16_f32 v49, v50, v51
	global_store_dwordx2 v[72:73], v[48:49], off offset:512 sc1
	s_nop 0
	s_waitcnt vmcnt(19)
	v_pk_mul_f32 v[48:49], v[108:109], v[56:57]
	v_pk_mul_f32 v[50:51], v[110:111], v[58:59]
	s_waitcnt vmcnt(18)
	v_pk_add_f32 v[54:55], v[114:115], 1.0 op_sel_hi:[1,0]
	v_pk_add_f32 v[52:53], v[112:113], 1.0 op_sel_hi:[1,0]
	s_waitcnt vmcnt(17)
	v_pk_fma_f32 v[50:51], v[54:55], v[50:51], v[118:119]
	v_pk_fma_f32 v[48:49], v[52:53], v[48:49], v[116:117]
	s_nop 0
	v_cvt_pk_bf16_f32 v48, v48, v49
	v_cvt_pk_bf16_f32 v49, v50, v51
	global_store_dwordx2 v[72:73], v[48:49], off offset:1024 sc1
	s_nop 0
	s_waitcnt vmcnt(17)
	v_pk_mul_f32 v[16:17], v[120:121], v[16:17]
	v_pk_mul_f32 v[18:19], v[122:123], v[18:19]
	s_waitcnt vmcnt(16)
	v_pk_add_f32 v[48:49], v[126:127], 1.0 op_sel_hi:[1,0]
	v_pk_add_f32 v[50:51], v[124:125], 1.0 op_sel_hi:[1,0]
	s_waitcnt vmcnt(15)
	v_pk_fma_f32 v[18:19], v[48:49], v[18:19], v[130:131]
	v_pk_fma_f32 v[16:17], v[50:51], v[16:17], v[128:129]
	s_nop 0
	v_cvt_pk_bf16_f32 v16, v16, v17
	v_cvt_pk_bf16_f32 v17, v18, v19
	global_store_dwordx2 v[72:73], v[16:17], off offset:1536 sc1
	s_nop 0
	s_waitcnt vmcnt(15)
	v_pk_mul_f32 v[8:9], v[132:133], v[8:9]
	v_pk_mul_f32 v[10:11], v[134:135], v[10:11]
	s_waitcnt vmcnt(14)
	v_pk_add_f32 v[16:17], v[138:139], 1.0 op_sel_hi:[1,0]
	v_pk_add_f32 v[18:19], v[136:137], 1.0 op_sel_hi:[1,0]
	s_waitcnt vmcnt(13)
	v_pk_fma_f32 v[10:11], v[16:17], v[10:11], v[142:143]
	v_pk_fma_f32 v[8:9], v[18:19], v[8:9], v[140:141]
	s_nop 0
	v_cvt_pk_bf16_f32 v8, v8, v9
	v_cvt_pk_bf16_f32 v9, v10, v11
	global_store_dwordx2 v[72:73], v[8:9], off offset:2048 sc1
	s_nop 0
	s_waitcnt vmcnt(13)
	v_pk_mul_f32 v[8:9], v[144:145], v[12:13]
	v_pk_mul_f32 v[10:11], v[146:147], v[14:15]
	s_waitcnt vmcnt(12)
	v_pk_add_f32 v[12:13], v[150:151], 1.0 op_sel_hi:[1,0]
	v_pk_add_f32 v[14:15], v[148:149], 1.0 op_sel_hi:[1,0]
	s_waitcnt vmcnt(11)
	v_pk_fma_f32 v[10:11], v[12:13], v[10:11], v[154:155]
	v_pk_fma_f32 v[8:9], v[14:15], v[8:9], v[152:153]
	s_nop 0
	v_cvt_pk_bf16_f32 v8, v8, v9
	v_cvt_pk_bf16_f32 v9, v10, v11
	global_store_dwordx2 v[72:73], v[8:9], off offset:2560 sc1
	s_nop 0
	s_waitcnt vmcnt(11)
	v_pk_mul_f32 v[4:5], v[156:157], v[4:5]
	v_pk_mul_f32 v[6:7], v[158:159], v[6:7]
	s_waitcnt vmcnt(10)
	v_pk_add_f32 v[8:9], v[162:163], 1.0 op_sel_hi:[1,0]
	v_pk_add_f32 v[10:11], v[160:161], 1.0 op_sel_hi:[1,0]
	s_waitcnt vmcnt(9)
	v_pk_fma_f32 v[6:7], v[8:9], v[6:7], v[166:167]
	v_pk_fma_f32 v[4:5], v[10:11], v[4:5], v[164:165]
	s_nop 0
	v_cvt_pk_bf16_f32 v4, v4, v5
	v_cvt_pk_bf16_f32 v5, v6, v7
	global_store_dwordx2 v[72:73], v[4:5], off offset:3072 sc1
	s_nop 0
	s_waitcnt vmcnt(9)
	v_pk_mul_f32 v[0:1], v[168:169], v[0:1]
	v_pk_mul_f32 v[2:3], v[170:171], v[2:3]
	s_waitcnt vmcnt(8)
	v_pk_add_f32 v[4:5], v[174:175], 1.0 op_sel_hi:[1,0]
	v_pk_add_f32 v[6:7], v[172:173], 1.0 op_sel_hi:[1,0]
	s_waitcnt vmcnt(7)
	v_pk_fma_f32 v[2:3], v[4:5], v[2:3], v[178:179]
	v_pk_fma_f32 v[0:1], v[6:7], v[0:1], v[176:177]
	s_nop 0
	v_cvt_pk_bf16_f32 v0, v0, v1
	v_cvt_pk_bf16_f32 v1, v2, v3
	global_store_dwordx2 v[72:73], v[0:1], off offset:3584 sc1
	s_cbranch_scc1 .LBB0_166

; __device__ __forceinline__ void st_bf4(bf16_t* p, f32x4 v) { u32x2 w; w.x = pk2(v[0], v[1]); w.y = pk2(v[2], v[3]); *(u32x2*)p = w; }
; __device__ __forceinline__ float sigmoidf_(float x) { return __builtin_amdgcn_rcpf(1.f + __expf(-x)); }
;     __device__ __forceinline__ void put(const Unit& u, int row, int col, f32x4 v) const {
;         const int pn = u.pn; bf16_t* base; int ldc, c0, act = 0;
;         if (pn < 2) { base = Q; ldc = 512; c0 = 0; act = 1; }
;         else if (pn < 4) { base = Kb; ldc = 512; c0 = 512; }
;         else if (pn < 8) { base = Vb; ldc = 1024; c0 = 1024; }
;         else if (pn < 12) { base = R; ldc = 1024; c0 = 2048; act = 2; }
;         else if (pn < 16) { base = F; ldc = 1024; c0 = 3072; }
;         else if (pn < 24) { base = GA; ldc = 2048; c0 = 4096; act = 3; }
;         else if (pn < 32) { base = GB; ldc = 2048; c0 = 6144; act = 3; }
;         else { base = LR; ldc = 256; c0 = 8192; }
;         if (act == 1) v = v * 0.08838834764831845f;
;         else if (act == 2) { v[0] *= sigmoidf_(v[0]); v[1] *= sigmoidf_(v[1]); v[2] *= sigmoidf_(v[2]); v[3] *= sigmoidf_(v[3]); }
;         else if (act == 3) { v[0] = sigmoidf_(v[0]); v[1] = sigmoidf_(v[1]); v[2] = sigmoidf_(v[2]); v[3] = sigmoidf_(v[3]); }
;         st_bf4(base + (size_t)row * ldc + (col - c0), v);
; template <class Epi, class Sched, bool DEFER>
; __device__ __forceinline__ void gemm_fast_core(LAS unsigned char* lds, const GemmP g, const Sched& S, const Epi& E, f32x4 (&acc)[2][2][4][2], Unit& cur) {
;     ...
;             const int row0 = cur.pm * BM + wr * 64 + fr, col0 = cur.pn * BM + wc * 32 + 4 * fq;
; #pragma unroll
;             for (int ai = 0; ai < 2; ++ai)
; #pragma unroll
;                 for (int m = 0; m < 4; ++m)
; #pragma unroll
;                     for (int bj = 0; bj < 2; ++bj)
; #pragma unroll
;                         for (int n = 0; n < 2; ++n) E.put(cur, row0 + ai * HALF + m * 16, col0 + bj * HALF + n * 16, acc[ai][bj][m][n]);
.Lp2e_v_none:
	v_cvt_pk_bf16_f32 v124, v124, v125
	v_cvt_pk_bf16_f32 v125, v126, v127
	v_cvt_pk_bf16_f32 v126, v120, v121
	v_cvt_pk_bf16_f32 v127, v122, v123
	s_nop 1
	v_permlane16_swap_b32_e32 v124, v126
	v_permlane16_swap_b32_e32 v125, v127
	global_store_dwordx4 v[150:151], v[124:127], off sc1
	v_cvt_pk_bf16_f32 v116, v116, v117
	v_cvt_pk_bf16_f32 v117, v118, v119
	v_cvt_pk_bf16_f32 v118, v112, v113
	v_cvt_pk_bf16_f32 v119, v114, v115
	s_nop 1
	v_permlane16_swap_b32_e32 v116, v118
	v_permlane16_swap_b32_e32 v117, v119
	global_store_dwordx4 v[150:151], v[116:119], off offset:256 sc1
	s_nop 0
	v_lshl_add_u64 v[150:151], v[150:151], 0, s[44:45]
	v_cvt_pk_bf16_f32 v108, v108, v109
	v_cvt_pk_bf16_f32 v109, v110, v111
	v_cvt_pk_bf16_f32 v110, v104, v105
	v_cvt_pk_bf16_f32 v111, v106, v107
	s_nop 1
	v_permlane16_swap_b32_e32 v108, v110
	v_permlane16_swap_b32_e32 v109, v111
	global_store_dwordx4 v[150:151], v[108:111], off sc1
	v_cvt_pk_bf16_f32 v100, v100, v101
	v_cvt_pk_bf16_f32 v101, v102, v103
	v_cvt_pk_bf16_f32 v102, v96, v97
	v_cvt_pk_bf16_f32 v103, v98, v99
	s_nop 1
	v_permlane16_swap_b32_e32 v100, v102
	v_permlane16_swap_b32_e32 v101, v103
	global_store_dwordx4 v[150:151], v[100:103], off offset:256 sc1
	s_nop 0
	v_lshl_add_u64 v[150:151], v[150:151], 0, s[44:45]
	v_cvt_pk_bf16_f32 v92, v92, v93
	v_cvt_pk_bf16_f32 v93, v94, v95
	v_cvt_pk_bf16_f32 v94, v88, v89
	v_cvt_pk_bf16_f32 v95, v90, v91
	s_nop 1
	v_permlane16_swap_b32_e32 v92, v94
	v_permlane16_swap_b32_e32 v93, v95
	global_store_dwordx4 v[150:151], v[92:95], off sc1
	v_cvt_pk_bf16_f32 v84, v84, v85
	v_cvt_pk_bf16_f32 v85, v86, v87
	v_cvt_pk_bf16_f32 v86, v80, v81
	v_cvt_pk_bf16_f32 v87, v82, v83
	s_nop 1
	v_permlane16_swap_b32_e32 v84, v86
	v_permlane16_swap_b32_e32 v85, v87
	global_store_dwordx4 v[150:151], v[84:87], off offset:256 sc1
	s_nop 0
	v_lshl_add_u64 v[150:151], v[150:151], 0, s[44:45]
	v_cvt_pk_bf16_f32 v76, v76, v77
	v_cvt_pk_bf16_f32 v77, v78, v79
	v_cvt_pk_bf16_f32 v78, v72, v73
	v_cvt_pk_bf16_f32 v79, v74, v75
	s_nop 1
	v_permlane16_swap_b32_e32 v76, v78
	v_permlane16_swap_b32_e32 v77, v79
	global_store_dwordx4 v[150:151], v[76:79], off sc1
	v_cvt_pk_bf16_f32 v68, v68, v69
	v_cvt_pk_bf16_f32 v69, v70, v71
	v_cvt_pk_bf16_f32 v70, v64, v65
	v_cvt_pk_bf16_f32 v71, v66, v67
	s_nop 1
	v_permlane16_swap_b32_e32 v68, v70
	v_permlane16_swap_b32_e32 v69, v71
	global_store_dwordx4 v[150:151], v[68:71], off offset:256 sc1
	s_nop 0
	v_lshl_add_u64 v[150:151], v[150:151], 0, s[44:45]
	v_lshl_add_u64 v[150:151], v[150:151], 0, s[46:47]
	v_cvt_pk_bf16_f32 v60, v60, v61
	v_cvt_pk_bf16_f32 v61, v62, v63
	v_cvt_pk_bf16_f32 v62, v56, v57
	v_cvt_pk_bf16_f32 v63, v58, v59
	s_nop 1
	v_permlane16_swap_b32_e32 v60, v62
	v_permlane16_swap_b32_e32 v61, v63
	global_store_dwordx4 v[150:151], v[60:63], off sc1
	v_cvt_pk_bf16_f32 v52, v52, v53
	v_cvt_pk_bf16_f32 v53, v54, v55
	v_cvt_pk_bf16_f32 v54, v48, v49
	v_cvt_pk_bf16_f32 v55, v50, v51
	s_nop 1
	v_permlane16_swap_b32_e32 v52, v54
	v_permlane16_swap_b32_e32 v53, v55
	global_store_dwordx4 v[150:151], v[52:55], off offset:256 sc1
	s_nop 0
	v_lshl_add_u64 v[150:151], v[150:151], 0, s[44:45]
	v_cvt_pk_bf16_f32 v44, v44, v45
	v_cvt_pk_bf16_f32 v45, v46, v47
	v_cvt_pk_bf16_f32 v46, v40, v41
	v_cvt_pk_bf16_f32 v47, v42, v43
	s_nop 1
	v_permlane16_swap_b32_e32 v44, v46
	v_permlane16_swap_b32_e32 v45, v47
	global_store_dwordx4 v[150:151], v[44:47], off sc1
	v_cvt_pk_bf16_f32 v36, v36, v37
	v_cvt_pk_bf16_f32 v37, v38, v39
	v_cvt_pk_bf16_f32 v38, v32, v33
	v_cvt_pk_bf16_f32 v39, v34, v35
	s_nop 1
	v_permlane16_swap_b32_e32 v36, v38
	v_permlane16_swap_b32_e32 v37, v39
	global_store_dwordx4 v[150:151], v[36:39], off offset:256 sc1
	s_nop 0
	v_lshl_add_u64 v[150:151], v[150:151], 0, s[44:45]
	v_cvt_pk_bf16_f32 v28, v28, v29
	v_cvt_pk_bf16_f32 v29, v30, v31
	v_cvt_pk_bf16_f32 v30, v24, v25
	v_cvt_pk_bf16_f32 v31, v26, v27
	s_nop 1
	v_permlane16_swap_b32_e32 v28, v30
	v_permlane16_swap_b32_e32 v29, v31
	global_store_dwordx4 v[150:151], v[28:31], off sc1
	v_cvt_pk_bf16_f32 v20, v20, v21
	v_cvt_pk_bf16_f32 v21, v22, v23
	v_cvt_pk_bf16_f32 v22, v16, v17
	v_cvt_pk_bf16_f32 v23, v18, v19
	s_nop 1
	v_permlane16_swap_b32_e32 v20, v22
	v_permlane16_swap_b32_e32 v21, v23
	global_store_dwordx4 v[150:151], v[20:23], off offset:256 sc1
	s_nop 0
	v_lshl_add_u64 v[150:151], v[150:151], 0, s[44:45]
	v_cvt_pk_bf16_f32 v12, v12, v13
	v_cvt_pk_bf16_f32 v13, v14, v15
	v_cvt_pk_bf16_f32 v14, v8, v9
	v_cvt_pk_bf16_f32 v15, v10, v11
	s_nop 1
	v_permlane16_swap_b32_e32 v12, v14
	v_permlane16_swap_b32_e32 v13, v15
	global_store_dwordx4 v[150:151], v[12:15], off sc1
	v_cvt_pk_bf16_f32 v4, v4, v5
	v_cvt_pk_bf16_f32 v5, v6, v7
	v_cvt_pk_bf16_f32 v6, v0, v1
	v_cvt_pk_bf16_f32 v7, v2, v3
	s_nop 1
	v_permlane16_swap_b32_e32 v4, v6
	v_permlane16_swap_b32_e32 v5, v7
	global_store_dwordx4 v[150:151], v[4:7], off offset:256 sc1
	s_branch .Lp2e_done
; __device__ __forceinline__ void st_bf4(bf16_t* p, f32x4 v) { u32x2 w; w.x = pk2(v[0], v[1]); w.y = pk2(v[2], v[3]); *(u32x2*)p = w; }
; __device__ __forceinline__ float sigmoidf_(float x) { return __builtin_amdgcn_rcpf(1.f + __expf(-x)); }
;     __device__ __forceinline__ void put(const Unit& u, int row, int col, f32x4 v) const {
;         const int pn = u.pn; bf16_t* base; int ldc, c0, act = 0;
;         if (pn < 2) { base = Q; ldc = 512; c0 = 0; act = 1; }
;         else if (pn < 4) { base = Kb; ldc = 512; c0 = 512; }
;         else if (pn < 8) { base = Vb; ldc = 1024; c0 = 1024; }
;         else if (pn < 12) { base = R; ldc = 1024; c0 = 2048; act = 2; }
;         else if (pn < 16) { base = F; ldc = 1024; c0 = 3072; }
;         else if (pn < 24) { base = GA; ldc = 2048; c0 = 4096; act = 3; }
;         else if (pn < 32) { base = GB; ldc = 2048; c0 = 6144; act = 3; }
;         else { base = LR; ldc = 256; c0 = 8192; }
;         if (act == 1) v = v * 0.08838834764831845f;
;         else if (act == 2) { v[0] *= sigmoidf_(v[0]); v[1] *= sigmoidf_(v[1]); v[2] *= sigmoidf_(v[2]); v[3] *= sigmoidf_(v[3]); }
;         else if (act == 3) { v[0] = sigmoidf_(v[0]); v[1] = sigmoidf_(v[1]); v[2] = sigmoidf_(v[2]); v[3] = sigmoidf_(v[3]); }
;         st_bf4(base + (size_t)row * ldc + (col - c0), v);
; template <class Epi, class Sched, bool DEFER>
; __device__ __forceinline__ void gemm_fast_core(LAS unsigned char* lds, const GemmP g, const Sched& S, const Epi& E, f32x4 (&acc)[2][2][4][2], Unit& cur) {
;     ...
;             const int row0 = cur.pm * BM + wr * 64 + fr, col0 = cur.pn * BM + wc * 32 + 4 * fq;
; #pragma unroll
;             for (int ai = 0; ai < 2; ++ai)
; #pragma unroll
;                 for (int m = 0; m < 4; ++m)
; #pragma unroll
;                     for (int bj = 0; bj < 2; ++bj)
; #pragma unroll
;                         for (int n = 0; n < 2; ++n) E.put(cur, row0 + ai * HALF + m * 16, col0 + bj * HALF + n * 16, acc[ai][bj][m][n]);
.Lp2e_v_scale:
	v_mul_f32_e32 v124, s20, v124
	v_mul_f32_e32 v125, s20, v125
	v_mul_f32_e32 v126, s20, v126
	v_mul_f32_e32 v127, s20, v127
	v_mul_f32_e32 v120, s20, v120
	v_mul_f32_e32 v121, s20, v121
	v_mul_f32_e32 v122, s20, v122
	v_mul_f32_e32 v123, s20, v123
	v_cvt_pk_bf16_f32 v124, v124, v125
	v_cvt_pk_bf16_f32 v125, v126, v127
	v_cvt_pk_bf16_f32 v126, v120, v121
	v_cvt_pk_bf16_f32 v127, v122, v123
	s_nop 1
	v_permlane16_swap_b32_e32 v124, v126
	v_permlane16_swap_b32_e32 v125, v127
	global_store_dwordx4 v[150:151], v[124:127], off sc1
	v_mul_f32_e32 v116, s20, v116
	v_mul_f32_e32 v117, s20, v117
	v_mul_f32_e32 v118, s20, v118
	v_mul_f32_e32 v119, s20, v119
	v_mul_f32_e32 v112, s20, v112
	v_mul_f32_e32 v113, s20, v113
	v_mul_f32_e32 v114, s20, v114
	v_mul_f32_e32 v115, s20, v115
	v_cvt_pk_bf16_f32 v116, v116, v117
	v_cvt_pk_bf16_f32 v117, v118, v119
	v_cvt_pk_bf16_f32 v118, v112, v113
	v_cvt_pk_bf16_f32 v119, v114, v115
	s_nop 1
	v_permlane16_swap_b32_e32 v116, v118
	v_permlane16_swap_b32_e32 v117, v119
	global_store_dwordx4 v[150:151], v[116:119], off offset:256 sc1
	s_nop 0
	v_lshl_add_u64 v[150:151], v[150:151], 0, s[44:45]
	v_mul_f32_e32 v108, s20, v108
	v_mul_f32_e32 v109, s20, v109
	v_mul_f32_e32 v110, s20, v110
	v_mul_f32_e32 v111, s20, v111
	v_mul_f32_e32 v104, s20, v104
	v_mul_f32_e32 v105, s20, v105
	v_mul_f32_e32 v106, s20, v106
	v_mul_f32_e32 v107, s20, v107
	v_cvt_pk_bf16_f32 v108, v108, v109
	v_cvt_pk_bf16_f32 v109, v110, v111
	v_cvt_pk_bf16_f32 v110, v104, v105
	v_cvt_pk_bf16_f32 v111, v106, v107
	s_nop 1
	v_permlane16_swap_b32_e32 v108, v110
	v_permlane16_swap_b32_e32 v109, v111
	global_store_dwordx4 v[150:151], v[108:111], off sc1
	v_mul_f32_e32 v100, s20, v100
	v_mul_f32_e32 v101, s20, v101
	v_mul_f32_e32 v102, s20, v102
	v_mul_f32_e32 v103, s20, v103
	v_mul_f32_e32 v96, s20, v96
	v_mul_f32_e32 v97, s20, v97
	v_mul_f32_e32 v98, s20, v98
	v_mul_f32_e32 v99, s20, v99
	v_cvt_pk_bf16_f32 v100, v100, v101
	v_cvt_pk_bf16_f32 v101, v102, v103
	v_cvt_pk_bf16_f32 v102, v96, v97
	v_cvt_pk_bf16_f32 v103, v98, v99
	s_nop 1
	v_permlane16_swap_b32_e32 v100, v102
	v_permlane16_swap_b32_e32 v101, v103
	global_store_dwordx4 v[150:151], v[100:103], off offset:256 sc1
	s_nop 0
	v_lshl_add_u64 v[150:151], v[150:151], 0, s[44:45]
	v_mul_f32_e32 v92, s20, v92
	v_mul_f32_e32 v93, s20, v93
	v_mul_f32_e32 v94, s20, v94
	v_mul_f32_e32 v95, s20, v95
	v_mul_f32_e32 v88, s20, v88
	v_mul_f32_e32 v89, s20, v89
	v_mul_f32_e32 v90, s20, v90
	v_mul_f32_e32 v91, s20, v91
	v_cvt_pk_bf16_f32 v92, v92, v93
	v_cvt_pk_bf16_f32 v93, v94, v95
	v_cvt_pk_bf16_f32 v94, v88, v89
	v_cvt_pk_bf16_f32 v95, v90, v91
	s_nop 1
	v_permlane16_swap_b32_e32 v92, v94
	v_permlane16_swap_b32_e32 v93, v95
	global_store_dwordx4 v[150:151], v[92:95], off sc1
	v_mul_f32_e32 v84, s20, v84
	v_mul_f32_e32 v85, s20, v85
	v_mul_f32_e32 v86, s20, v86
	v_mul_f32_e32 v87, s20, v87
	v_mul_f32_e32 v80, s20, v80
	v_mul_f32_e32 v81, s20, v81
	v_mul_f32_e32 v82, s20, v82
	v_mul_f32_e32 v83, s20, v83
	v_cvt_pk_bf16_f32 v84, v84, v85
	v_cvt_pk_bf16_f32 v85, v86, v87
	v_cvt_pk_bf16_f32 v86, v80, v81
	v_cvt_pk_bf16_f32 v87, v82, v83
	s_nop 1
	v_permlane16_swap_b32_e32 v84, v86
	v_permlane16_swap_b32_e32 v85, v87
	global_store_dwordx4 v[150:151], v[84:87], off offset:256 sc1
	s_nop 0
	v_lshl_add_u64 v[150:151], v[150:151], 0, s[44:45]
	v_mul_f32_e32 v76, s20, v76
	v_mul_f32_e32 v77, s20, v77
	v_mul_f32_e32 v78, s20, v78
	v_mul_f32_e32 v79, s20, v79
	v_mul_f32_e32 v72, s20, v72
	v_mul_f32_e32 v73, s20, v73
	v_mul_f32_e32 v74, s20, v74
	v_mul_f32_e32 v75, s20, v75
	v_cvt_pk_bf16_f32 v76, v76, v77
	v_cvt_pk_bf16_f32 v77, v78, v79
	v_cvt_pk_bf16_f32 v78, v72, v73
	v_cvt_pk_bf16_f32 v79, v74, v75
	s_nop 1
	v_permlane16_swap_b32_e32 v76, v78
	v_permlane16_swap_b32_e32 v77, v79
	global_store_dwordx4 v[150:151], v[76:79], off sc1
	v_mul_f32_e32 v68, s20, v68
	v_mul_f32_e32 v69, s20, v69
	v_mul_f32_e32 v70, s20, v70
	v_mul_f32_e32 v71, s20, v71
	v_mul_f32_e32 v64, s20, v64
	v_mul_f32_e32 v65, s20, v65
	v_mul_f32_e32 v66, s20, v66
	v_mul_f32_e32 v67, s20, v67
	v_cvt_pk_bf16_f32 v68, v68, v69
	v_cvt_pk_bf16_f32 v69, v70, v71
	v_cvt_pk_bf16_f32 v70, v64, v65
	v_cvt_pk_bf16_f32 v71, v66, v67
	s_nop 1
	v_permlane16_swap_b32_e32 v68, v70
	v_permlane16_swap_b32_e32 v69, v71
	global_store_dwordx4 v[150:151], v[68:71], off offset:256 sc1
	s_nop 0
	v_lshl_add_u64 v[150:151], v[150:151], 0, s[44:45]
	v_lshl_add_u64 v[150:151], v[150:151], 0, s[46:47]
	v_mul_f32_e32 v60, s20, v60
	v_mul_f32_e32 v61, s20, v61
	v_mul_f32_e32 v62, s20, v62
	v_mul_f32_e32 v63, s20, v63
	v_mul_f32_e32 v56, s20, v56
	v_mul_f32_e32 v57, s20, v57
	v_mul_f32_e32 v58, s20, v58
	v_mul_f32_e32 v59, s20, v59
	v_cvt_pk_bf16_f32 v60, v60, v61
	v_cvt_pk_bf16_f32 v61, v62, v63
	v_cvt_pk_bf16_f32 v62, v56, v57
	v_cvt_pk_bf16_f32 v63, v58, v59
	s_nop 1
	v_permlane16_swap_b32_e32 v60, v62
	v_permlane16_swap_b32_e32 v61, v63
	global_store_dwordx4 v[150:151], v[60:63], off sc1
	v_mul_f32_e32 v52, s20, v52
	v_mul_f32_e32 v53, s20, v53
	v_mul_f32_e32 v54, s20, v54
	v_mul_f32_e32 v55, s20, v55
	v_mul_f32_e32 v48, s20, v48
	v_mul_f32_e32 v49, s20, v49
	v_mul_f32_e32 v50, s20, v50
	v_mul_f32_e32 v51, s20, v51
	v_cvt_pk_bf16_f32 v52, v52, v53
	v_cvt_pk_bf16_f32 v53, v54, v55
	v_cvt_pk_bf16_f32 v54, v48, v49
	v_cvt_pk_bf16_f32 v55, v50, v51
	s_nop 1
	v_permlane16_swap_b32_e32 v52, v54
	v_permlane16_swap_b32_e32 v53, v55
	global_store_dwordx4 v[150:151], v[52:55], off offset:256 sc1
	s_nop 0
	v_lshl_add_u64 v[150:151], v[150:151], 0, s[44:45]
	v_mul_f32_e32 v44, s20, v44
	v_mul_f32_e32 v45, s20, v45
	v_mul_f32_e32 v46, s20, v46
	v_mul_f32_e32 v47, s20, v47
; __device__ __forceinline__ void st_bf4(bf16_t* p, f32x4 v) { u32x2 w; w.x = pk2(v[0], v[1]); w.y = pk2(v[2], v[3]); *(u32x2*)p = w; }
; __device__ __forceinline__ float sigmoidf_(float x) { return __builtin_amdgcn_rcpf(1.f + __expf(-x)); }
;     __device__ __forceinline__ void put(const Unit& u, int row, int col, f32x4 v) const {
;         const int pn = u.pn; bf16_t* base; int ldc, c0, act = 0;
;         if (pn < 2) { base = Q; ldc = 512; c0 = 0; act = 1; }
;         else if (pn < 4) { base = Kb; ldc = 512; c0 = 512; }
;         else if (pn < 8) { base = Vb; ldc = 1024; c0 = 1024; }
;         else if (pn < 12) { base = R; ldc = 1024; c0 = 2048; act = 2; }
;         else if (pn < 16) { base = F; ldc = 1024; c0 = 3072; }
;         else if (pn < 24) { base = GA; ldc = 2048; c0 = 4096; act = 3; }
;         else if (pn < 32) { base = GB; ldc = 2048; c0 = 6144; act = 3; }
;         else { base = LR; ldc = 256; c0 = 8192; }
;         if (act == 1) v = v * 0.08838834764831845f;
;         else if (act == 2) { v[0] *= sigmoidf_(v[0]); v[1] *= sigmoidf_(v[1]); v[2] *= sigmoidf_(v[2]); v[3] *= sigmoidf_(v[3]); }
;         else if (act == 3) { v[0] = sigmoidf_(v[0]); v[1] = sigmoidf_(v[1]); v[2] = sigmoidf_(v[2]); v[3] = sigmoidf_(v[3]); }
;         st_bf4(base + (size_t)row * ldc + (col - c0), v);
; template <class Epi, class Sched, bool DEFER>
; __device__ __forceinline__ void gemm_fast_core(LAS unsigned char* lds, const GemmP g, const Sched& S, const Epi& E, f32x4 (&acc)[2][2][4][2], Unit& cur) {
;     ...
;             const int row0 = cur.pm * BM + wr * 64 + fr, col0 = cur.pn * BM + wc * 32 + 4 * fq;
; #pragma unroll
;             for (int ai = 0; ai < 2; ++ai)
; #pragma unroll
;                 for (int m = 0; m < 4; ++m)
; #pragma unroll
;                     for (int bj = 0; bj < 2; ++bj)
; #pragma unroll
;                         for (int n = 0; n < 2; ++n) E.put(cur, row0 + ai * HALF + m * 16, col0 + bj * HALF + n * 16, acc[ai][bj][m][n]);
	v_mul_f32_e32 v40, s20, v40
	v_mul_f32_e32 v41, s20, v41
	v_mul_f32_e32 v42, s20, v42
	v_mul_f32_e32 v43, s20, v43
	v_cvt_pk_bf16_f32 v44, v44, v45
	v_cvt_pk_bf16_f32 v45, v46, v47
	v_cvt_pk_bf16_f32 v46, v40, v41
	v_cvt_pk_bf16_f32 v47, v42, v43
	s_nop 1
	v_permlane16_swap_b32_e32 v44, v46
	v_permlane16_swap_b32_e32 v45, v47
	global_store_dwordx4 v[150:151], v[44:47], off sc1
	v_mul_f32_e32 v36, s20, v36
	v_mul_f32_e32 v37, s20, v37
	v_mul_f32_e32 v38, s20, v38
	v_mul_f32_e32 v39, s20, v39
	v_mul_f32_e32 v32, s20, v32
	v_mul_f32_e32 v33, s20, v33
	v_mul_f32_e32 v34, s20, v34
	v_mul_f32_e32 v35, s20, v35
	v_cvt_pk_bf16_f32 v36, v36, v37
	v_cvt_pk_bf16_f32 v37, v38, v39
	v_cvt_pk_bf16_f32 v38, v32, v33
	v_cvt_pk_bf16_f32 v39, v34, v35
	s_nop 1
	v_permlane16_swap_b32_e32 v36, v38
	v_permlane16_swap_b32_e32 v37, v39
	global_store_dwordx4 v[150:151], v[36:39], off offset:256 sc1
	s_nop 0
	v_lshl_add_u64 v[150:151], v[150:151], 0, s[44:45]
	v_mul_f32_e32 v28, s20, v28
	v_mul_f32_e32 v29, s20, v29
	v_mul_f32_e32 v30, s20, v30
	v_mul_f32_e32 v31, s20, v31
	v_mul_f32_e32 v24, s20, v24
	v_mul_f32_e32 v25, s20, v25
	v_mul_f32_e32 v26, s20, v26
	v_mul_f32_e32 v27, s20, v27
	v_cvt_pk_bf16_f32 v28, v28, v29
	v_cvt_pk_bf16_f32 v29, v30, v31
	v_cvt_pk_bf16_f32 v30, v24, v25
	v_cvt_pk_bf16_f32 v31, v26, v27
	s_nop 1
	v_permlane16_swap_b32_e32 v28, v30
	v_permlane16_swap_b32_e32 v29, v31
	global_store_dwordx4 v[150:151], v[28:31], off sc1
	v_mul_f32_e32 v20, s20, v20
	v_mul_f32_e32 v21, s20, v21
	v_mul_f32_e32 v22, s20, v22
	v_mul_f32_e32 v23, s20, v23
	v_mul_f32_e32 v16, s20, v16
	v_mul_f32_e32 v17, s20, v17
	v_mul_f32_e32 v18, s20, v18
	v_mul_f32_e32 v19, s20, v19
	v_cvt_pk_bf16_f32 v20, v20, v21
	v_cvt_pk_bf16_f32 v21, v22, v23
	v_cvt_pk_bf16_f32 v22, v16, v17
	v_cvt_pk_bf16_f32 v23, v18, v19
	s_nop 1
	v_permlane16_swap_b32_e32 v20, v22
	v_permlane16_swap_b32_e32 v21, v23
	global_store_dwordx4 v[150:151], v[20:23], off offset:256 sc1
	s_nop 0
	v_lshl_add_u64 v[150:151], v[150:151], 0, s[44:45]
	v_mul_f32_e32 v12, s20, v12
	v_mul_f32_e32 v13, s20, v13
	v_mul_f32_e32 v14, s20, v14
	v_mul_f32_e32 v15, s20, v15
	v_mul_f32_e32 v8, s20, v8
	v_mul_f32_e32 v9, s20, v9
	v_mul_f32_e32 v10, s20, v10
	v_mul_f32_e32 v11, s20, v11
	v_cvt_pk_bf16_f32 v12, v12, v13
	v_cvt_pk_bf16_f32 v13, v14, v15
	v_cvt_pk_bf16_f32 v14, v8, v9
	v_cvt_pk_bf16_f32 v15, v10, v11
	s_nop 1
	v_permlane16_swap_b32_e32 v12, v14
	v_permlane16_swap_b32_e32 v13, v15
	global_store_dwordx4 v[150:151], v[12:15], off sc1
	v_mul_f32_e32 v4, s20, v4
	v_mul_f32_e32 v5, s20, v5
	v_mul_f32_e32 v6, s20, v6
	v_mul_f32_e32 v7, s20, v7
	v_mul_f32_e32 v0, s20, v0
	v_mul_f32_e32 v1, s20, v1
	v_mul_f32_e32 v2, s20, v2
	v_mul_f32_e32 v3, s20, v3
	v_cvt_pk_bf16_f32 v4, v4, v5
	v_cvt_pk_bf16_f32 v5, v6, v7
	v_cvt_pk_bf16_f32 v6, v0, v1
	v_cvt_pk_bf16_f32 v7, v2, v3
	s_nop 1
	v_permlane16_swap_b32_e32 v4, v6
	v_permlane16_swap_b32_e32 v5, v7
	global_store_dwordx4 v[150:151], v[4:7], off offset:256 sc1
	s_branch .Lp2e_done
.Lp2e_v_silu:
	v_mul_f32_e32 v152, 0xbfb8aa3b, v124
	v_mul_f32_e32 v153, 0xbfb8aa3b, v125
	v_mul_f32_e32 v154, 0xbfb8aa3b, v126
	v_mul_f32_e32 v155, 0xbfb8aa3b, v127
	v_mul_f32_e32 v156, 0xbfb8aa3b, v120
	v_mul_f32_e32 v157, 0xbfb8aa3b, v121
	v_mul_f32_e32 v158, 0xbfb8aa3b, v122
	v_mul_f32_e32 v159, 0xbfb8aa3b, v123
	v_exp_f32_e32 v152, v152
	v_exp_f32_e32 v153, v153
	v_exp_f32_e32 v154, v154
	v_exp_f32_e32 v155, v155
	v_exp_f32_e32 v156, v156
	v_exp_f32_e32 v157, v157
	v_exp_f32_e32 v158, v158
	v_exp_f32_e32 v159, v159
	v_add_f32_e32 v152, 1.0, v152
	v_add_f32_e32 v153, 1.0, v153
	v_add_f32_e32 v154, 1.0, v154
	v_add_f32_e32 v155, 1.0, v155
	v_add_f32_e32 v156, 1.0, v156
	v_add_f32_e32 v157, 1.0, v157
	v_add_f32_e32 v158, 1.0, v158
	v_add_f32_e32 v159, 1.0, v159
	v_rcp_f32_e32 v152, v152
	v_rcp_f32_e32 v153, v153
	v_rcp_f32_e32 v154, v154
	v_rcp_f32_e32 v155, v155
	v_rcp_f32_e32 v156, v156
	v_rcp_f32_e32 v157, v157
	v_rcp_f32_e32 v158, v158
	v_rcp_f32_e32 v159, v159
	v_mul_f32_e32 v124, v124, v152
	v_mul_f32_e32 v125, v125, v153
	v_mul_f32_e32 v126, v126, v154
	v_mul_f32_e32 v127, v127, v155
	v_mul_f32_e32 v120, v120, v156
	v_mul_f32_e32 v121, v121, v157
	v_mul_f32_e32 v122, v122, v158
	v_mul_f32_e32 v123, v123, v159
	v_cvt_pk_bf16_f32 v124, v124, v125
	v_cvt_pk_bf16_f32 v125, v126, v127
	v_cvt_pk_bf16_f32 v126, v120, v121
	v_cvt_pk_bf16_f32 v127, v122, v123
	s_nop 1
	v_permlane16_swap_b32_e32 v124, v126
	v_permlane16_swap_b32_e32 v125, v127
	global_store_dwordx4 v[150:151], v[124:127], off sc1
	v_mul_f32_e32 v152, 0xbfb8aa3b, v116
	v_mul_f32_e32 v153, 0xbfb8aa3b, v117
	v_mul_f32_e32 v154, 0xbfb8aa3b, v118
	v_mul_f32_e32 v155, 0xbfb8aa3b, v119
	v_mul_f32_e32 v156, 0xbfb8aa3b, v112
	v_mul_f32_e32 v157, 0xbfb8aa3b, v113
	v_mul_f32_e32 v158, 0xbfb8aa3b, v114
	v_mul_f32_e32 v159, 0xbfb8aa3b, v115
	v_exp_f32_e32 v152, v152
	v_exp_f32_e32 v153, v153
	v_exp_f32_e32 v154, v154
	v_exp_f32_e32 v155, v155
	v_exp_f32_e32 v156, v156
	v_exp_f32_e32 v157, v157
	v_exp_f32_e32 v158, v158
	v_exp_f32_e32 v159, v159
	v_add_f32_e32 v152, 1.0, v152
	v_add_f32_e32 v153, 1.0, v153
	v_add_f32_e32 v154, 1.0, v154
	v_add_f32_e32 v155, 1.0, v155
	v_add_f32_e32 v156, 1.0, v156
	v_add_f32_e32 v157, 1.0, v157
	v_add_f32_e32 v158, 1.0, v158
	v_add_f32_e32 v159, 1.0, v159
	v_rcp_f32_e32 v152, v152
	v_rcp_f32_e32 v153, v153
	v_rcp_f32_e32 v154, v154
	v_rcp_f32_e32 v155, v155
	v_rcp_f32_e32 v156, v156
	v_rcp_f32_e32 v157, v157
	v_rcp_f32_e32 v158, v158
	v_rcp_f32_e32 v159, v159
	v_mul_f32_e32 v116, v116, v152
	v_mul_f32_e32 v117, v117, v153
	v_mul_f32_e32 v118, v118, v154
	v_mul_f32_e32 v119, v119, v155
	v_mul_f32_e32 v112, v112, v156
; __device__ __forceinline__ void st_bf4(bf16_t* p, f32x4 v) { u32x2 w; w.x = pk2(v[0], v[1]); w.y = pk2(v[2], v[3]); *(u32x2*)p = w; }
; __device__ __forceinline__ float sigmoidf_(float x) { return __builtin_amdgcn_rcpf(1.f + __expf(-x)); }
;     __device__ __forceinline__ void put(const Unit& u, int row, int col, f32x4 v) const {
;         const int pn = u.pn; bf16_t* base; int ldc, c0, act = 0;
;         if (pn < 2) { base = Q; ldc = 512; c0 = 0; act = 1; }
;         else if (pn < 4) { base = Kb; ldc = 512; c0 = 512; }
;         else if (pn < 8) { base = Vb; ldc = 1024; c0 = 1024; }
;         else if (pn < 12) { base = R; ldc = 1024; c0 = 2048; act = 2; }
;         else if (pn < 16) { base = F; ldc = 1024; c0 = 3072; }
;         else if (pn < 24) { base = GA; ldc = 2048; c0 = 4096; act = 3; }
;         else if (pn < 32) { base = GB; ldc = 2048; c0 = 6144; act = 3; }
;         else { base = LR; ldc = 256; c0 = 8192; }
;         if (act == 1) v = v * 0.08838834764831845f;
;         else if (act == 2) { v[0] *= sigmoidf_(v[0]); v[1] *= sigmoidf_(v[1]); v[2] *= sigmoidf_(v[2]); v[3] *= sigmoidf_(v[3]); }
;         else if (act == 3) { v[0] = sigmoidf_(v[0]); v[1] = sigmoidf_(v[1]); v[2] = sigmoidf_(v[2]); v[3] = sigmoidf_(v[3]); }
;         st_bf4(base + (size_t)row * ldc + (col - c0), v);
	v_mul_f32_e32 v113, v113, v157
	v_mul_f32_e32 v114, v114, v158
	v_mul_f32_e32 v115, v115, v159
	v_cvt_pk_bf16_f32 v116, v116, v117
	v_cvt_pk_bf16_f32 v117, v118, v119
	v_cvt_pk_bf16_f32 v118, v112, v113
	v_cvt_pk_bf16_f32 v119, v114, v115
	s_nop 1
	v_permlane16_swap_b32_e32 v116, v118
	v_permlane16_swap_b32_e32 v117, v119
	global_store_dwordx4 v[150:151], v[116:119], off offset:256 sc1
	s_nop 0
	v_lshl_add_u64 v[150:151], v[150:151], 0, s[44:45]
	v_mul_f32_e32 v152, 0xbfb8aa3b, v108
	v_mul_f32_e32 v153, 0xbfb8aa3b, v109
	v_mul_f32_e32 v154, 0xbfb8aa3b, v110
	v_mul_f32_e32 v155, 0xbfb8aa3b, v111
	v_mul_f32_e32 v156, 0xbfb8aa3b, v104
	v_mul_f32_e32 v157, 0xbfb8aa3b, v105
	v_mul_f32_e32 v158, 0xbfb8aa3b, v106
	v_mul_f32_e32 v159, 0xbfb8aa3b, v107
	v_exp_f32_e32 v152, v152
	v_exp_f32_e32 v153, v153
	v_exp_f32_e32 v154, v154
	v_exp_f32_e32 v155, v155
	v_exp_f32_e32 v156, v156
	v_exp_f32_e32 v157, v157
	v_exp_f32_e32 v158, v158
	v_exp_f32_e32 v159, v159
	v_add_f32_e32 v152, 1.0, v152
	v_add_f32_e32 v153, 1.0, v153
	v_add_f32_e32 v154, 1.0, v154
	v_add_f32_e32 v155, 1.0, v155
	v_add_f32_e32 v156, 1.0, v156
	v_add_f32_e32 v157, 1.0, v157
	v_add_f32_e32 v158, 1.0, v158
	v_add_f32_e32 v159, 1.0, v159
	v_rcp_f32_e32 v152, v152
	v_rcp_f32_e32 v153, v153
	v_rcp_f32_e32 v154, v154
	v_rcp_f32_e32 v155, v155
	v_rcp_f32_e32 v156, v156
	v_rcp_f32_e32 v157, v157
	v_rcp_f32_e32 v158, v158
	v_rcp_f32_e32 v159, v159
	v_mul_f32_e32 v108, v108, v152
	v_mul_f32_e32 v109, v109, v153
	v_mul_f32_e32 v110, v110, v154
	v_mul_f32_e32 v111, v111, v155
	v_mul_f32_e32 v104, v104, v156
	v_mul_f32_e32 v105, v105, v157
	v_mul_f32_e32 v106, v106, v158
	v_mul_f32_e32 v107, v107, v159
	v_cvt_pk_bf16_f32 v108, v108, v109
	v_cvt_pk_bf16_f32 v109, v110, v111
	v_cvt_pk_bf16_f32 v110, v104, v105
	v_cvt_pk_bf16_f32 v111, v106, v107
	s_nop 1
	v_permlane16_swap_b32_e32 v108, v110
	v_permlane16_swap_b32_e32 v109, v111
	global_store_dwordx4 v[150:151], v[108:111], off sc1
	v_mul_f32_e32 v152, 0xbfb8aa3b, v100
	v_mul_f32_e32 v153, 0xbfb8aa3b, v101
	v_mul_f32_e32 v154, 0xbfb8aa3b, v102
	v_mul_f32_e32 v155, 0xbfb8aa3b, v103
	v_mul_f32_e32 v156, 0xbfb8aa3b, v96
	v_mul_f32_e32 v157, 0xbfb8aa3b, v97
	v_mul_f32_e32 v158, 0xbfb8aa3b, v98
	v_mul_f32_e32 v159, 0xbfb8aa3b, v99
	v_exp_f32_e32 v152, v152
	v_exp_f32_e32 v153, v153
	v_exp_f32_e32 v154, v154
	v_exp_f32_e32 v155, v155
	v_exp_f32_e32 v156, v156
	v_exp_f32_e32 v157, v157
	v_exp_f32_e32 v158, v158
	v_exp_f32_e32 v159, v159
	v_add_f32_e32 v152, 1.0, v152
	v_add_f32_e32 v153, 1.0, v153
	v_add_f32_e32 v154, 1.0, v154
	v_add_f32_e32 v155, 1.0, v155
	v_add_f32_e32 v156, 1.0, v156
	v_add_f32_e32 v157, 1.0, v157
	v_add_f32_e32 v158, 1.0, v158
	v_add_f32_e32 v159, 1.0, v159
	v_rcp_f32_e32 v152, v152
	v_rcp_f32_e32 v153, v153
	v_rcp_f32_e32 v154, v154
	v_rcp_f32_e32 v155, v155
	v_rcp_f32_e32 v156, v156
	v_rcp_f32_e32 v157, v157
	v_rcp_f32_e32 v158, v158
	v_rcp_f32_e32 v159, v159
	v_mul_f32_e32 v100, v100, v152
	v_mul_f32_e32 v101, v101, v153
	v_mul_f32_e32 v102, v102, v154
	v_mul_f32_e32 v103, v103, v155
	v_mul_f32_e32 v96, v96, v156
	v_mul_f32_e32 v97, v97, v157
	v_mul_f32_e32 v98, v98, v158
	v_mul_f32_e32 v99, v99, v159
	v_cvt_pk_bf16_f32 v100, v100, v101
	v_cvt_pk_bf16_f32 v101, v102, v103
	v_cvt_pk_bf16_f32 v102, v96, v97
	v_cvt_pk_bf16_f32 v103, v98, v99
	s_nop 1
	v_permlane16_swap_b32_e32 v100, v102
	v_permlane16_swap_b32_e32 v101, v103
	global_store_dwordx4 v[150:151], v[100:103], off offset:256 sc1
	s_nop 0
	v_lshl_add_u64 v[150:151], v[150:151], 0, s[44:45]
	v_mul_f32_e32 v152, 0xbfb8aa3b, v92
	v_mul_f32_e32 v153, 0xbfb8aa3b, v93
	v_mul_f32_e32 v154, 0xbfb8aa3b, v94
	v_mul_f32_e32 v155, 0xbfb8aa3b, v95
	v_mul_f32_e32 v156, 0xbfb8aa3b, v88
	v_mul_f32_e32 v157, 0xbfb8aa3b, v89
	v_mul_f32_e32 v158, 0xbfb8aa3b, v90
	v_mul_f32_e32 v159, 0xbfb8aa3b, v91
	v_exp_f32_e32 v152, v152
	v_exp_f32_e32 v153, v153
	v_exp_f32_e32 v154, v154
	v_exp_f32_e32 v155, v155
	v_exp_f32_e32 v156, v156
	v_exp_f32_e32 v157, v157
	v_exp_f32_e32 v158, v158
	v_exp_f32_e32 v159, v159
	v_add_f32_e32 v152, 1.0, v152
	v_add_f32_e32 v153, 1.0, v153
	v_add_f32_e32 v154, 1.0, v154
	v_add_f32_e32 v155, 1.0, v155
	v_add_f32_e32 v156, 1.0, v156
	v_add_f32_e32 v157, 1.0, v157
	v_add_f32_e32 v158, 1.0, v158
	v_add_f32_e32 v159, 1.0, v159
	v_rcp_f32_e32 v152, v152
	v_rcp_f32_e32 v153, v153
	v_rcp_f32_e32 v154, v154
	v_rcp_f32_e32 v155, v155
	v_rcp_f32_e32 v156, v156
	v_rcp_f32_e32 v157, v157
	v_rcp_f32_e32 v158, v158
	v_rcp_f32_e32 v159, v159
	v_mul_f32_e32 v92, v92, v152
	v_mul_f32_e32 v93, v93, v153
	v_mul_f32_e32 v94, v94, v154
	v_mul_f32_e32 v95, v95, v155
	v_mul_f32_e32 v88, v88, v156
	v_mul_f32_e32 v89, v89, v157
	v_mul_f32_e32 v90, v90, v158
	v_mul_f32_e32 v91, v91, v159
	v_cvt_pk_bf16_f32 v92, v92, v93
	v_cvt_pk_bf16_f32 v93, v94, v95
	v_cvt_pk_bf16_f32 v94, v88, v89
	v_cvt_pk_bf16_f32 v95, v90, v91
	s_nop 1
	v_permlane16_swap_b32_e32 v92, v94
	v_permlane16_swap_b32_e32 v93, v95
	global_store_dwordx4 v[150:151], v[92:95], off sc1
	v_mul_f32_e32 v152, 0xbfb8aa3b, v84
	v_mul_f32_e32 v153, 0xbfb8aa3b, v85
	v_mul_f32_e32 v154, 0xbfb8aa3b, v86
	v_mul_f32_e32 v155, 0xbfb8aa3b, v87
	v_mul_f32_e32 v156, 0xbfb8aa3b, v80
	v_mul_f32_e32 v157, 0xbfb8aa3b, v81
	v_mul_f32_e32 v158, 0xbfb8aa3b, v82
	v_mul_f32_e32 v159, 0xbfb8aa3b, v83
	v_exp_f32_e32 v152, v152
	v_exp_f32_e32 v153, v153
	v_exp_f32_e32 v154, v154
	v_exp_f32_e32 v155, v155
	v_exp_f32_e32 v156, v156
	v_exp_f32_e32 v157, v157
	v_exp_f32_e32 v158, v158
	v_exp_f32_e32 v159, v159
	v_add_f32_e32 v152, 1.0, v152
	v_add_f32_e32 v153, 1.0, v153
	v_add_f32_e32 v154, 1.0, v154
	v_add_f32_e32 v155, 1.0, v155
	v_add_f32_e32 v156, 1.0, v156
; __device__ __forceinline__ void st_bf4(bf16_t* p, f32x4 v) { u32x2 w; w.x = pk2(v[0], v[1]); w.y = pk2(v[2], v[3]); *(u32x2*)p = w; }
; __device__ __forceinline__ float sigmoidf_(float x) { return __builtin_amdgcn_rcpf(1.f + __expf(-x)); }
;     __device__ __forceinline__ void put(const Unit& u, int row, int col, f32x4 v) const {
;         const int pn = u.pn; bf16_t* base; int ldc, c0, act = 0;
;         if (pn < 2) { base = Q; ldc = 512; c0 = 0; act = 1; }
;         else if (pn < 4) { base = Kb; ldc = 512; c0 = 512; }
;         else if (pn < 8) { base = Vb; ldc = 1024; c0 = 1024; }
;         else if (pn < 12) { base = R; ldc = 1024; c0 = 2048; act = 2; }
;         else if (pn < 16) { base = F; ldc = 1024; c0 = 3072; }
;         else if (pn < 24) { base = GA; ldc = 2048; c0 = 4096; act = 3; }
;         else if (pn < 32) { base = GB; ldc = 2048; c0 = 6144; act = 3; }
;         else { base = LR; ldc = 256; c0 = 8192; }
;         if (act == 1) v = v * 0.08838834764831845f;
;         else if (act == 2) { v[0] *= sigmoidf_(v[0]); v[1] *= sigmoidf_(v[1]); v[2] *= sigmoidf_(v[2]); v[3] *= sigmoidf_(v[3]); }
;         else if (act == 3) { v[0] = sigmoidf_(v[0]); v[1] = sigmoidf_(v[1]); v[2] = sigmoidf_(v[2]); v[3] = sigmoidf_(v[3]); }
;         st_bf4(base + (size_t)row * ldc + (col - c0), v);
	v_add_f32_e32 v157, 1.0, v157
	v_add_f32_e32 v158, 1.0, v158
	v_add_f32_e32 v159, 1.0, v159
	v_rcp_f32_e32 v152, v152
	v_rcp_f32_e32 v153, v153
	v_rcp_f32_e32 v154, v154
	v_rcp_f32_e32 v155, v155
	v_rcp_f32_e32 v156, v156
	v_rcp_f32_e32 v157, v157
	v_rcp_f32_e32 v158, v158
	v_rcp_f32_e32 v159, v159
	v_mul_f32_e32 v84, v84, v152
	v_mul_f32_e32 v85, v85, v153
	v_mul_f32_e32 v86, v86, v154
	v_mul_f32_e32 v87, v87, v155
	v_mul_f32_e32 v80, v80, v156
	v_mul_f32_e32 v81, v81, v157
	v_mul_f32_e32 v82, v82, v158
	v_mul_f32_e32 v83, v83, v159
	v_cvt_pk_bf16_f32 v84, v84, v85
	v_cvt_pk_bf16_f32 v85, v86, v87
	v_cvt_pk_bf16_f32 v86, v80, v81
	v_cvt_pk_bf16_f32 v87, v82, v83
	s_nop 1
	v_permlane16_swap_b32_e32 v84, v86
	v_permlane16_swap_b32_e32 v85, v87
	global_store_dwordx4 v[150:151], v[84:87], off offset:256 sc1
	s_nop 0
	v_lshl_add_u64 v[150:151], v[150:151], 0, s[44:45]
	v_mul_f32_e32 v152, 0xbfb8aa3b, v76
	v_mul_f32_e32 v153, 0xbfb8aa3b, v77
	v_mul_f32_e32 v154, 0xbfb8aa3b, v78
	v_mul_f32_e32 v155, 0xbfb8aa3b, v79
	v_mul_f32_e32 v156, 0xbfb8aa3b, v72
	v_mul_f32_e32 v157, 0xbfb8aa3b, v73
	v_mul_f32_e32 v158, 0xbfb8aa3b, v74
	v_mul_f32_e32 v159, 0xbfb8aa3b, v75
	v_exp_f32_e32 v152, v152
	v_exp_f32_e32 v153, v153
	v_exp_f32_e32 v154, v154
	v_exp_f32_e32 v155, v155
	v_exp_f32_e32 v156, v156
	v_exp_f32_e32 v157, v157
	v_exp_f32_e32 v158, v158
	v_exp_f32_e32 v159, v159
	v_add_f32_e32 v152, 1.0, v152
	v_add_f32_e32 v153, 1.0, v153
	v_add_f32_e32 v154, 1.0, v154
	v_add_f32_e32 v155, 1.0, v155
	v_add_f32_e32 v156, 1.0, v156
	v_add_f32_e32 v157, 1.0, v157
	v_add_f32_e32 v158, 1.0, v158
	v_add_f32_e32 v159, 1.0, v159
	v_rcp_f32_e32 v152, v152
	v_rcp_f32_e32 v153, v153
	v_rcp_f32_e32 v154, v154
	v_rcp_f32_e32 v155, v155
	v_rcp_f32_e32 v156, v156
	v_rcp_f32_e32 v157, v157
	v_rcp_f32_e32 v158, v158
	v_rcp_f32_e32 v159, v159
	v_mul_f32_e32 v76, v76, v152
	v_mul_f32_e32 v77, v77, v153
	v_mul_f32_e32 v78, v78, v154
	v_mul_f32_e32 v79, v79, v155
	v_mul_f32_e32 v72, v72, v156
	v_mul_f32_e32 v73, v73, v157
	v_mul_f32_e32 v74, v74, v158
	v_mul_f32_e32 v75, v75, v159
	v_cvt_pk_bf16_f32 v76, v76, v77
	v_cvt_pk_bf16_f32 v77, v78, v79
	v_cvt_pk_bf16_f32 v78, v72, v73
	v_cvt_pk_bf16_f32 v79, v74, v75
	s_nop 1
	v_permlane16_swap_b32_e32 v76, v78
	v_permlane16_swap_b32_e32 v77, v79
	global_store_dwordx4 v[150:151], v[76:79], off sc1
	v_mul_f32_e32 v152, 0xbfb8aa3b, v68
	v_mul_f32_e32 v153, 0xbfb8aa3b, v69
	v_mul_f32_e32 v154, 0xbfb8aa3b, v70
	v_mul_f32_e32 v155, 0xbfb8aa3b, v71
	v_mul_f32_e32 v156, 0xbfb8aa3b, v64
	v_mul_f32_e32 v157, 0xbfb8aa3b, v65
	v_mul_f32_e32 v158, 0xbfb8aa3b, v66
	v_mul_f32_e32 v159, 0xbfb8aa3b, v67
	v_exp_f32_e32 v152, v152
	v_exp_f32_e32 v153, v153
	v_exp_f32_e32 v154, v154
	v_exp_f32_e32 v155, v155
	v_exp_f32_e32 v156, v156
	v_exp_f32_e32 v157, v157
	v_exp_f32_e32 v158, v158
	v_exp_f32_e32 v159, v159
	v_add_f32_e32 v152, 1.0, v152
	v_add_f32_e32 v153, 1.0, v153
	v_add_f32_e32 v154, 1.0, v154
	v_add_f32_e32 v155, 1.0, v155
	v_add_f32_e32 v156, 1.0, v156
	v_add_f32_e32 v157, 1.0, v157
	v_add_f32_e32 v158, 1.0, v158
	v_add_f32_e32 v159, 1.0, v159
	v_rcp_f32_e32 v152, v152
	v_rcp_f32_e32 v153, v153
	v_rcp_f32_e32 v154, v154
	v_rcp_f32_e32 v155, v155
	v_rcp_f32_e32 v156, v156
	v_rcp_f32_e32 v157, v157
	v_rcp_f32_e32 v158, v158
	v_rcp_f32_e32 v159, v159
	v_mul_f32_e32 v68, v68, v152
	v_mul_f32_e32 v69, v69, v153
	v_mul_f32_e32 v70, v70, v154
	v_mul_f32_e32 v71, v71, v155
	v_mul_f32_e32 v64, v64, v156
	v_mul_f32_e32 v65, v65, v157
	v_mul_f32_e32 v66, v66, v158
	v_mul_f32_e32 v67, v67, v159
	v_cvt_pk_bf16_f32 v68, v68, v69
	v_cvt_pk_bf16_f32 v69, v70, v71
	v_cvt_pk_bf16_f32 v70, v64, v65
	v_cvt_pk_bf16_f32 v71, v66, v67
	s_nop 1
	v_permlane16_swap_b32_e32 v68, v70
	v_permlane16_swap_b32_e32 v69, v71
	global_store_dwordx4 v[150:151], v[68:71], off offset:256 sc1
	s_nop 0
	v_lshl_add_u64 v[150:151], v[150:151], 0, s[44:45]
	v_lshl_add_u64 v[150:151], v[150:151], 0, s[46:47]
	v_mul_f32_e32 v152, 0xbfb8aa3b, v60
	v_mul_f32_e32 v153, 0xbfb8aa3b, v61
	v_mul_f32_e32 v154, 0xbfb8aa3b, v62
	v_mul_f32_e32 v155, 0xbfb8aa3b, v63
	v_mul_f32_e32 v156, 0xbfb8aa3b, v56
	v_mul_f32_e32 v157, 0xbfb8aa3b, v57
	v_mul_f32_e32 v158, 0xbfb8aa3b, v58
	v_mul_f32_e32 v159, 0xbfb8aa3b, v59
	v_exp_f32_e32 v152, v152
	v_exp_f32_e32 v153, v153
	v_exp_f32_e32 v154, v154
	v_exp_f32_e32 v155, v155
	v_exp_f32_e32 v156, v156
	v_exp_f32_e32 v157, v157
	v_exp_f32_e32 v158, v158
	v_exp_f32_e32 v159, v159
	v_add_f32_e32 v152, 1.0, v152
	v_add_f32_e32 v153, 1.0, v153
	v_add_f32_e32 v154, 1.0, v154
	v_add_f32_e32 v155, 1.0, v155
	v_add_f32_e32 v156, 1.0, v156
	v_add_f32_e32 v157, 1.0, v157
	v_add_f32_e32 v158, 1.0, v158
	v_add_f32_e32 v159, 1.0, v159
	v_rcp_f32_e32 v152, v152
	v_rcp_f32_e32 v153, v153
	v_rcp_f32_e32 v154, v154
	v_rcp_f32_e32 v155, v155
	v_rcp_f32_e32 v156, v156
	v_rcp_f32_e32 v157, v157
	v_rcp_f32_e32 v158, v158
	v_rcp_f32_e32 v159, v159
	v_mul_f32_e32 v60, v60, v152
	v_mul_f32_e32 v61, v61, v153
	v_mul_f32_e32 v62, v62, v154
	v_mul_f32_e32 v63, v63, v155
	v_mul_f32_e32 v56, v56, v156
	v_mul_f32_e32 v57, v57, v157
	v_mul_f32_e32 v58, v58, v158
	v_mul_f32_e32 v59, v59, v159
	v_cvt_pk_bf16_f32 v60, v60, v61
	v_cvt_pk_bf16_f32 v61, v62, v63
	v_cvt_pk_bf16_f32 v62, v56, v57
	v_cvt_pk_bf16_f32 v63, v58, v59
	s_nop 1
	v_permlane16_swap_b32_e32 v60, v62
	v_permlane16_swap_b32_e32 v61, v63
	global_store_dwordx4 v[150:151], v[60:63], off sc1
	v_mul_f32_e32 v152, 0xbfb8aa3b, v52
	v_mul_f32_e32 v153, 0xbfb8aa3b, v53
	v_mul_f32_e32 v154, 0xbfb8aa3b, v54
	v_mul_f32_e32 v155, 0xbfb8aa3b, v55
	v_mul_f32_e32 v156, 0xbfb8aa3b, v48
	v_mul_f32_e32 v157, 0xbfb8aa3b, v49
	v_mul_f32_e32 v158, 0xbfb8aa3b, v50
; __device__ __forceinline__ void st_bf4(bf16_t* p, f32x4 v) { u32x2 w; w.x = pk2(v[0], v[1]); w.y = pk2(v[2], v[3]); *(u32x2*)p = w; }
; __device__ __forceinline__ float sigmoidf_(float x) { return __builtin_amdgcn_rcpf(1.f + __expf(-x)); }
;     __device__ __forceinline__ void put(const Unit& u, int row, int col, f32x4 v) const {
;         const int pn = u.pn; bf16_t* base; int ldc, c0, act = 0;
;         if (pn < 2) { base = Q; ldc = 512; c0 = 0; act = 1; }
;         else if (pn < 4) { base = Kb; ldc = 512; c0 = 512; }
;         else if (pn < 8) { base = Vb; ldc = 1024; c0 = 1024; }
;         else if (pn < 12) { base = R; ldc = 1024; c0 = 2048; act = 2; }
;         else if (pn < 16) { base = F; ldc = 1024; c0 = 3072; }
;         else if (pn < 24) { base = GA; ldc = 2048; c0 = 4096; act = 3; }
;         else if (pn < 32) { base = GB; ldc = 2048; c0 = 6144; act = 3; }
;         else { base = LR; ldc = 256; c0 = 8192; }
;         if (act == 1) v = v * 0.08838834764831845f;
;         else if (act == 2) { v[0] *= sigmoidf_(v[0]); v[1] *= sigmoidf_(v[1]); v[2] *= sigmoidf_(v[2]); v[3] *= sigmoidf_(v[3]); }
;         else if (act == 3) { v[0] = sigmoidf_(v[0]); v[1] = sigmoidf_(v[1]); v[2] = sigmoidf_(v[2]); v[3] = sigmoidf_(v[3]); }
;         st_bf4(base + (size_t)row * ldc + (col - c0), v);
	v_mul_f32_e32 v159, 0xbfb8aa3b, v51
	v_exp_f32_e32 v152, v152
	v_exp_f32_e32 v153, v153
	v_exp_f32_e32 v154, v154
	v_exp_f32_e32 v155, v155
	v_exp_f32_e32 v156, v156
	v_exp_f32_e32 v157, v157
	v_exp_f32_e32 v158, v158
	v_exp_f32_e32 v159, v159
	v_add_f32_e32 v152, 1.0, v152
	v_add_f32_e32 v153, 1.0, v153
	v_add_f32_e32 v154, 1.0, v154
	v_add_f32_e32 v155, 1.0, v155
	v_add_f32_e32 v156, 1.0, v156
	v_add_f32_e32 v157, 1.0, v157
	v_add_f32_e32 v158, 1.0, v158
	v_add_f32_e32 v159, 1.0, v159
	v_rcp_f32_e32 v152, v152
	v_rcp_f32_e32 v153, v153
	v_rcp_f32_e32 v154, v154
	v_rcp_f32_e32 v155, v155
	v_rcp_f32_e32 v156, v156
	v_rcp_f32_e32 v157, v157
	v_rcp_f32_e32 v158, v158
	v_rcp_f32_e32 v159, v159
	v_mul_f32_e32 v52, v52, v152
	v_mul_f32_e32 v53, v53, v153
	v_mul_f32_e32 v54, v54, v154
	v_mul_f32_e32 v55, v55, v155
	v_mul_f32_e32 v48, v48, v156
	v_mul_f32_e32 v49, v49, v157
	v_mul_f32_e32 v50, v50, v158
	v_mul_f32_e32 v51, v51, v159
	v_cvt_pk_bf16_f32 v52, v52, v53
	v_cvt_pk_bf16_f32 v53, v54, v55
	v_cvt_pk_bf16_f32 v54, v48, v49
	v_cvt_pk_bf16_f32 v55, v50, v51
	s_nop 1
	v_permlane16_swap_b32_e32 v52, v54
	v_permlane16_swap_b32_e32 v53, v55
	global_store_dwordx4 v[150:151], v[52:55], off offset:256 sc1
	s_nop 0
	v_lshl_add_u64 v[150:151], v[150:151], 0, s[44:45]
	v_mul_f32_e32 v152, 0xbfb8aa3b, v44
	v_mul_f32_e32 v153, 0xbfb8aa3b, v45
	v_mul_f32_e32 v154, 0xbfb8aa3b, v46
	v_mul_f32_e32 v155, 0xbfb8aa3b, v47
	v_mul_f32_e32 v156, 0xbfb8aa3b, v40
	v_mul_f32_e32 v157, 0xbfb8aa3b, v41
	v_mul_f32_e32 v158, 0xbfb8aa3b, v42
	v_mul_f32_e32 v159, 0xbfb8aa3b, v43
	v_exp_f32_e32 v152, v152
	v_exp_f32_e32 v153, v153
	v_exp_f32_e32 v154, v154
	v_exp_f32_e32 v155, v155
	v_exp_f32_e32 v156, v156
	v_exp_f32_e32 v157, v157
	v_exp_f32_e32 v158, v158
	v_exp_f32_e32 v159, v159
	v_add_f32_e32 v152, 1.0, v152
	v_add_f32_e32 v153, 1.0, v153
	v_add_f32_e32 v154, 1.0, v154
	v_add_f32_e32 v155, 1.0, v155
	v_add_f32_e32 v156, 1.0, v156
	v_add_f32_e32 v157, 1.0, v157
	v_add_f32_e32 v158, 1.0, v158
	v_add_f32_e32 v159, 1.0, v159
	v_rcp_f32_e32 v152, v152
	v_rcp_f32_e32 v153, v153
	v_rcp_f32_e32 v154, v154
	v_rcp_f32_e32 v155, v155
	v_rcp_f32_e32 v156, v156
	v_rcp_f32_e32 v157, v157
	v_rcp_f32_e32 v158, v158
	v_rcp_f32_e32 v159, v159
	v_mul_f32_e32 v44, v44, v152
	v_mul_f32_e32 v45, v45, v153
	v_mul_f32_e32 v46, v46, v154
	v_mul_f32_e32 v47, v47, v155
	v_mul_f32_e32 v40, v40, v156
	v_mul_f32_e32 v41, v41, v157
	v_mul_f32_e32 v42, v42, v158
	v_mul_f32_e32 v43, v43, v159
	v_cvt_pk_bf16_f32 v44, v44, v45
	v_cvt_pk_bf16_f32 v45, v46, v47
	v_cvt_pk_bf16_f32 v46, v40, v41
	v_cvt_pk_bf16_f32 v47, v42, v43
	s_nop 1
	v_permlane16_swap_b32_e32 v44, v46
	v_permlane16_swap_b32_e32 v45, v47
	global_store_dwordx4 v[150:151], v[44:47], off sc1
	v_mul_f32_e32 v152, 0xbfb8aa3b, v36
	v_mul_f32_e32 v153, 0xbfb8aa3b, v37
	v_mul_f32_e32 v154, 0xbfb8aa3b, v38
	v_mul_f32_e32 v155, 0xbfb8aa3b, v39
	v_mul_f32_e32 v156, 0xbfb8aa3b, v32
	v_mul_f32_e32 v157, 0xbfb8aa3b, v33
	v_mul_f32_e32 v158, 0xbfb8aa3b, v34
	v_mul_f32_e32 v159, 0xbfb8aa3b, v35
	v_exp_f32_e32 v152, v152
	v_exp_f32_e32 v153, v153
	v_exp_f32_e32 v154, v154
	v_exp_f32_e32 v155, v155
	v_exp_f32_e32 v156, v156
	v_exp_f32_e32 v157, v157
	v_exp_f32_e32 v158, v158
	v_exp_f32_e32 v159, v159
	v_add_f32_e32 v152, 1.0, v152
	v_add_f32_e32 v153, 1.0, v153
	v_add_f32_e32 v154, 1.0, v154
	v_add_f32_e32 v155, 1.0, v155
	v_add_f32_e32 v156, 1.0, v156
	v_add_f32_e32 v157, 1.0, v157
	v_add_f32_e32 v158, 1.0, v158
	v_add_f32_e32 v159, 1.0, v159
	v_rcp_f32_e32 v152, v152
	v_rcp_f32_e32 v153, v153
	v_rcp_f32_e32 v154, v154
	v_rcp_f32_e32 v155, v155
	v_rcp_f32_e32 v156, v156
	v_rcp_f32_e32 v157, v157
	v_rcp_f32_e32 v158, v158
	v_rcp_f32_e32 v159, v159
	v_mul_f32_e32 v36, v36, v152
	v_mul_f32_e32 v37, v37, v153
	v_mul_f32_e32 v38, v38, v154
	v_mul_f32_e32 v39, v39, v155
	v_mul_f32_e32 v32, v32, v156
	v_mul_f32_e32 v33, v33, v157
	v_mul_f32_e32 v34, v34, v158
	v_mul_f32_e32 v35, v35, v159
	v_cvt_pk_bf16_f32 v36, v36, v37
	v_cvt_pk_bf16_f32 v37, v38, v39
	v_cvt_pk_bf16_f32 v38, v32, v33
	v_cvt_pk_bf16_f32 v39, v34, v35
	s_nop 1
	v_permlane16_swap_b32_e32 v36, v38
	v_permlane16_swap_b32_e32 v37, v39
	global_store_dwordx4 v[150:151], v[36:39], off offset:256 sc1
	s_nop 0
	v_lshl_add_u64 v[150:151], v[150:151], 0, s[44:45]
	v_mul_f32_e32 v152, 0xbfb8aa3b, v28
	v_mul_f32_e32 v153, 0xbfb8aa3b, v29
	v_mul_f32_e32 v154, 0xbfb8aa3b, v30
	v_mul_f32_e32 v155, 0xbfb8aa3b, v31
	v_mul_f32_e32 v156, 0xbfb8aa3b, v24
	v_mul_f32_e32 v157, 0xbfb8aa3b, v25
	v_mul_f32_e32 v158, 0xbfb8aa3b, v26
	v_mul_f32_e32 v159, 0xbfb8aa3b, v27
	v_exp_f32_e32 v152, v152
	v_exp_f32_e32 v153, v153
	v_exp_f32_e32 v154, v154
	v_exp_f32_e32 v155, v155
	v_exp_f32_e32 v156, v156
	v_exp_f32_e32 v157, v157
	v_exp_f32_e32 v158, v158
	v_exp_f32_e32 v159, v159
	v_add_f32_e32 v152, 1.0, v152
	v_add_f32_e32 v153, 1.0, v153
	v_add_f32_e32 v154, 1.0, v154
	v_add_f32_e32 v155, 1.0, v155
	v_add_f32_e32 v156, 1.0, v156
	v_add_f32_e32 v157, 1.0, v157
	v_add_f32_e32 v158, 1.0, v158
	v_add_f32_e32 v159, 1.0, v159
	v_rcp_f32_e32 v152, v152
	v_rcp_f32_e32 v153, v153
	v_rcp_f32_e32 v154, v154
	v_rcp_f32_e32 v155, v155
	v_rcp_f32_e32 v156, v156
	v_rcp_f32_e32 v157, v157
	v_rcp_f32_e32 v158, v158
	v_rcp_f32_e32 v159, v159
	v_mul_f32_e32 v28, v28, v152
	v_mul_f32_e32 v29, v29, v153
	v_mul_f32_e32 v30, v30, v154
	v_mul_f32_e32 v31, v31, v155
	v_mul_f32_e32 v24, v24, v156
	v_mul_f32_e32 v25, v25, v157
	v_mul_f32_e32 v26, v26, v158
	v_mul_f32_e32 v27, v27, v159
	v_cvt_pk_bf16_f32 v28, v28, v29
	v_cvt_pk_bf16_f32 v29, v30, v31
	v_cvt_pk_bf16_f32 v30, v24, v25
	v_cvt_pk_bf16_f32 v31, v26, v27
	s_nop 1
	v_permlane16_swap_b32_e32 v28, v30
; __device__ __forceinline__ void st_bf4(bf16_t* p, f32x4 v) { u32x2 w; w.x = pk2(v[0], v[1]); w.y = pk2(v[2], v[3]); *(u32x2*)p = w; }
; __device__ __forceinline__ float sigmoidf_(float x) { return __builtin_amdgcn_rcpf(1.f + __expf(-x)); }
;     __device__ __forceinline__ void put(const Unit& u, int row, int col, f32x4 v) const {
;         const int pn = u.pn; bf16_t* base; int ldc, c0, act = 0;
;         if (pn < 2) { base = Q; ldc = 512; c0 = 0; act = 1; }
;         else if (pn < 4) { base = Kb; ldc = 512; c0 = 512; }
;         else if (pn < 8) { base = Vb; ldc = 1024; c0 = 1024; }
;         else if (pn < 12) { base = R; ldc = 1024; c0 = 2048; act = 2; }
;         else if (pn < 16) { base = F; ldc = 1024; c0 = 3072; }
;         else if (pn < 24) { base = GA; ldc = 2048; c0 = 4096; act = 3; }
;         else if (pn < 32) { base = GB; ldc = 2048; c0 = 6144; act = 3; }
;         else { base = LR; ldc = 256; c0 = 8192; }
;         if (act == 1) v = v * 0.08838834764831845f;
;         else if (act == 2) { v[0] *= sigmoidf_(v[0]); v[1] *= sigmoidf_(v[1]); v[2] *= sigmoidf_(v[2]); v[3] *= sigmoidf_(v[3]); }
;         else if (act == 3) { v[0] = sigmoidf_(v[0]); v[1] = sigmoidf_(v[1]); v[2] = sigmoidf_(v[2]); v[3] = sigmoidf_(v[3]); }
;         st_bf4(base + (size_t)row * ldc + (col - c0), v);
	v_permlane16_swap_b32_e32 v29, v31
	global_store_dwordx4 v[150:151], v[28:31], off sc1
	v_mul_f32_e32 v152, 0xbfb8aa3b, v20
	v_mul_f32_e32 v153, 0xbfb8aa3b, v21
	v_mul_f32_e32 v154, 0xbfb8aa3b, v22
	v_mul_f32_e32 v155, 0xbfb8aa3b, v23
	v_mul_f32_e32 v156, 0xbfb8aa3b, v16
	v_mul_f32_e32 v157, 0xbfb8aa3b, v17
	v_mul_f32_e32 v158, 0xbfb8aa3b, v18
	v_mul_f32_e32 v159, 0xbfb8aa3b, v19
	v_exp_f32_e32 v152, v152
	v_exp_f32_e32 v153, v153
	v_exp_f32_e32 v154, v154
	v_exp_f32_e32 v155, v155
	v_exp_f32_e32 v156, v156
	v_exp_f32_e32 v157, v157
	v_exp_f32_e32 v158, v158
	v_exp_f32_e32 v159, v159
	v_add_f32_e32 v152, 1.0, v152
	v_add_f32_e32 v153, 1.0, v153
	v_add_f32_e32 v154, 1.0, v154
	v_add_f32_e32 v155, 1.0, v155
	v_add_f32_e32 v156, 1.0, v156
	v_add_f32_e32 v157, 1.0, v157
	v_add_f32_e32 v158, 1.0, v158
	v_add_f32_e32 v159, 1.0, v159
	v_rcp_f32_e32 v152, v152
	v_rcp_f32_e32 v153, v153
	v_rcp_f32_e32 v154, v154
	v_rcp_f32_e32 v155, v155
	v_rcp_f32_e32 v156, v156
	v_rcp_f32_e32 v157, v157
	v_rcp_f32_e32 v158, v158
	v_rcp_f32_e32 v159, v159
	v_mul_f32_e32 v20, v20, v152
	v_mul_f32_e32 v21, v21, v153
	v_mul_f32_e32 v22, v22, v154
	v_mul_f32_e32 v23, v23, v155
	v_mul_f32_e32 v16, v16, v156
	v_mul_f32_e32 v17, v17, v157
	v_mul_f32_e32 v18, v18, v158
	v_mul_f32_e32 v19, v19, v159
	v_cvt_pk_bf16_f32 v20, v20, v21
	v_cvt_pk_bf16_f32 v21, v22, v23
	v_cvt_pk_bf16_f32 v22, v16, v17
	v_cvt_pk_bf16_f32 v23, v18, v19
	s_nop 1
	v_permlane16_swap_b32_e32 v20, v22
	v_permlane16_swap_b32_e32 v21, v23
	global_store_dwordx4 v[150:151], v[20:23], off offset:256 sc1
	s_nop 0
	v_lshl_add_u64 v[150:151], v[150:151], 0, s[44:45]
	v_mul_f32_e32 v152, 0xbfb8aa3b, v12
	v_mul_f32_e32 v153, 0xbfb8aa3b, v13
	v_mul_f32_e32 v154, 0xbfb8aa3b, v14
	v_mul_f32_e32 v155, 0xbfb8aa3b, v15
	v_mul_f32_e32 v156, 0xbfb8aa3b, v8
	v_mul_f32_e32 v157, 0xbfb8aa3b, v9
	v_mul_f32_e32 v158, 0xbfb8aa3b, v10
	v_mul_f32_e32 v159, 0xbfb8aa3b, v11
	v_exp_f32_e32 v152, v152
	v_exp_f32_e32 v153, v153
	v_exp_f32_e32 v154, v154
	v_exp_f32_e32 v155, v155
	v_exp_f32_e32 v156, v156
	v_exp_f32_e32 v157, v157
	v_exp_f32_e32 v158, v158
	v_exp_f32_e32 v159, v159
	v_add_f32_e32 v152, 1.0, v152
	v_add_f32_e32 v153, 1.0, v153
	v_add_f32_e32 v154, 1.0, v154
	v_add_f32_e32 v155, 1.0, v155
	v_add_f32_e32 v156, 1.0, v156
	v_add_f32_e32 v157, 1.0, v157
	v_add_f32_e32 v158, 1.0, v158
	v_add_f32_e32 v159, 1.0, v159
	v_rcp_f32_e32 v152, v152
	v_rcp_f32_e32 v153, v153
	v_rcp_f32_e32 v154, v154
	v_rcp_f32_e32 v155, v155
	v_rcp_f32_e32 v156, v156
	v_rcp_f32_e32 v157, v157
	v_rcp_f32_e32 v158, v158
	v_rcp_f32_e32 v159, v159
	v_mul_f32_e32 v12, v12, v152
	v_mul_f32_e32 v13, v13, v153
	v_mul_f32_e32 v14, v14, v154
	v_mul_f32_e32 v15, v15, v155
	v_mul_f32_e32 v8, v8, v156
	v_mul_f32_e32 v9, v9, v157
	v_mul_f32_e32 v10, v10, v158
	v_mul_f32_e32 v11, v11, v159
	v_cvt_pk_bf16_f32 v12, v12, v13
	v_cvt_pk_bf16_f32 v13, v14, v15
	v_cvt_pk_bf16_f32 v14, v8, v9
	v_cvt_pk_bf16_f32 v15, v10, v11
	s_nop 1
	v_permlane16_swap_b32_e32 v12, v14
	v_permlane16_swap_b32_e32 v13, v15
	global_store_dwordx4 v[150:151], v[12:15], off sc1
	v_mul_f32_e32 v152, 0xbfb8aa3b, v4
	v_mul_f32_e32 v153, 0xbfb8aa3b, v5
	v_mul_f32_e32 v154, 0xbfb8aa3b, v6
	v_mul_f32_e32 v155, 0xbfb8aa3b, v7
	v_mul_f32_e32 v156, 0xbfb8aa3b, v0
	v_mul_f32_e32 v157, 0xbfb8aa3b, v1
	v_mul_f32_e32 v158, 0xbfb8aa3b, v2
	v_mul_f32_e32 v159, 0xbfb8aa3b, v3
	v_exp_f32_e32 v152, v152
	v_exp_f32_e32 v153, v153
	v_exp_f32_e32 v154, v154
	v_exp_f32_e32 v155, v155
	v_exp_f32_e32 v156, v156
	v_exp_f32_e32 v157, v157
	v_exp_f32_e32 v158, v158
	v_exp_f32_e32 v159, v159
	v_add_f32_e32 v152, 1.0, v152
	v_add_f32_e32 v153, 1.0, v153
	v_add_f32_e32 v154, 1.0, v154
	v_add_f32_e32 v155, 1.0, v155
	v_add_f32_e32 v156, 1.0, v156
	v_add_f32_e32 v157, 1.0, v157
	v_add_f32_e32 v158, 1.0, v158
	v_add_f32_e32 v159, 1.0, v159
	v_rcp_f32_e32 v152, v152
	v_rcp_f32_e32 v153, v153
	v_rcp_f32_e32 v154, v154
	v_rcp_f32_e32 v155, v155
	v_rcp_f32_e32 v156, v156
	v_rcp_f32_e32 v157, v157
	v_rcp_f32_e32 v158, v158
	v_rcp_f32_e32 v159, v159
	v_mul_f32_e32 v4, v4, v152
	v_mul_f32_e32 v5, v5, v153
	v_mul_f32_e32 v6, v6, v154
	v_mul_f32_e32 v7, v7, v155
	v_mul_f32_e32 v0, v0, v156
	v_mul_f32_e32 v1, v1, v157
	v_mul_f32_e32 v2, v2, v158
	v_mul_f32_e32 v3, v3, v159
	v_cvt_pk_bf16_f32 v4, v4, v5
	v_cvt_pk_bf16_f32 v5, v6, v7
	v_cvt_pk_bf16_f32 v6, v0, v1
	v_cvt_pk_bf16_f32 v7, v2, v3
	s_nop 1
	v_permlane16_swap_b32_e32 v4, v6
	v_permlane16_swap_b32_e32 v5, v7
	global_store_dwordx4 v[150:151], v[4:7], off offset:256 sc1
	s_branch .Lp2e_done
; __device__ __forceinline__ void st_bf4(bf16_t* p, f32x4 v) { u32x2 w; w.x = pk2(v[0], v[1]); w.y = pk2(v[2], v[3]); *(u32x2*)p = w; }
; __device__ __forceinline__ float sigmoidf_(float x) { return __builtin_amdgcn_rcpf(1.f + __expf(-x)); }
;     __device__ __forceinline__ void put(const Unit& u, int row, int col, f32x4 v) const {
;         const int pn = u.pn; bf16_t* base; int ldc, c0, act = 0;
;         if (pn < 2) { base = Q; ldc = 512; c0 = 0; act = 1; }
;         else if (pn < 4) { base = Kb; ldc = 512; c0 = 512; }
;         else if (pn < 8) { base = Vb; ldc = 1024; c0 = 1024; }
;         else if (pn < 12) { base = R; ldc = 1024; c0 = 2048; act = 2; }
;         else if (pn < 16) { base = F; ldc = 1024; c0 = 3072; }
;         else if (pn < 24) { base = GA; ldc = 2048; c0 = 4096; act = 3; }
;         else if (pn < 32) { base = GB; ldc = 2048; c0 = 6144; act = 3; }
;         else { base = LR; ldc = 256; c0 = 8192; }
;         if (act == 1) v = v * 0.08838834764831845f;
;         else if (act == 2) { v[0] *= sigmoidf_(v[0]); v[1] *= sigmoidf_(v[1]); v[2] *= sigmoidf_(v[2]); v[3] *= sigmoidf_(v[3]); }
;         else if (act == 3) { v[0] = sigmoidf_(v[0]); v[1] = sigmoidf_(v[1]); v[2] = sigmoidf_(v[2]); v[3] = sigmoidf_(v[3]); }
;         st_bf4(base + (size_t)row * ldc + (col - c0), v);
.Lp2e_v_sigm:
	v_mul_f32_e32 v152, 0xbfb8aa3b, v124
	v_mul_f32_e32 v153, 0xbfb8aa3b, v125
	v_mul_f32_e32 v154, 0xbfb8aa3b, v126
	v_mul_f32_e32 v155, 0xbfb8aa3b, v127
	v_mul_f32_e32 v156, 0xbfb8aa3b, v120
	v_mul_f32_e32 v157, 0xbfb8aa3b, v121
	v_mul_f32_e32 v158, 0xbfb8aa3b, v122
	v_mul_f32_e32 v159, 0xbfb8aa3b, v123
	v_exp_f32_e32 v152, v152
	v_exp_f32_e32 v153, v153
	v_exp_f32_e32 v154, v154
	v_exp_f32_e32 v155, v155
	v_exp_f32_e32 v156, v156
	v_exp_f32_e32 v157, v157
	v_exp_f32_e32 v158, v158
	v_exp_f32_e32 v159, v159
	v_add_f32_e32 v152, 1.0, v152
	v_add_f32_e32 v153, 1.0, v153
	v_add_f32_e32 v154, 1.0, v154
	v_add_f32_e32 v155, 1.0, v155
	v_add_f32_e32 v156, 1.0, v156
	v_add_f32_e32 v157, 1.0, v157
	v_add_f32_e32 v158, 1.0, v158
	v_add_f32_e32 v159, 1.0, v159
	v_rcp_f32_e32 v152, v152
	v_rcp_f32_e32 v153, v153
	v_rcp_f32_e32 v154, v154
	v_rcp_f32_e32 v155, v155
	v_rcp_f32_e32 v156, v156
	v_rcp_f32_e32 v157, v157
	v_rcp_f32_e32 v158, v158
	v_rcp_f32_e32 v159, v159
	v_cvt_pk_bf16_f32 v124, v152, v153
	v_cvt_pk_bf16_f32 v125, v154, v155
	v_cvt_pk_bf16_f32 v126, v156, v157
	v_cvt_pk_bf16_f32 v127, v158, v159
	s_nop 1
	v_permlane16_swap_b32_e32 v124, v126
	v_permlane16_swap_b32_e32 v125, v127
	global_store_dwordx4 v[150:151], v[124:127], off sc1
	v_mul_f32_e32 v152, 0xbfb8aa3b, v116
	v_mul_f32_e32 v153, 0xbfb8aa3b, v117
	v_mul_f32_e32 v154, 0xbfb8aa3b, v118
	v_mul_f32_e32 v155, 0xbfb8aa3b, v119
	v_mul_f32_e32 v156, 0xbfb8aa3b, v112
	v_mul_f32_e32 v157, 0xbfb8aa3b, v113
	v_mul_f32_e32 v158, 0xbfb8aa3b, v114
	v_mul_f32_e32 v159, 0xbfb8aa3b, v115
	v_exp_f32_e32 v152, v152
	v_exp_f32_e32 v153, v153
	v_exp_f32_e32 v154, v154
	v_exp_f32_e32 v155, v155
	v_exp_f32_e32 v156, v156
	v_exp_f32_e32 v157, v157
	v_exp_f32_e32 v158, v158
	v_exp_f32_e32 v159, v159
	v_add_f32_e32 v152, 1.0, v152
	v_add_f32_e32 v153, 1.0, v153
	v_add_f32_e32 v154, 1.0, v154
	v_add_f32_e32 v155, 1.0, v155
	v_add_f32_e32 v156, 1.0, v156
	v_add_f32_e32 v157, 1.0, v157
	v_add_f32_e32 v158, 1.0, v158
	v_add_f32_e32 v159, 1.0, v159
	v_rcp_f32_e32 v152, v152
	v_rcp_f32_e32 v153, v153
	v_rcp_f32_e32 v154, v154
	v_rcp_f32_e32 v155, v155
	v_rcp_f32_e32 v156, v156
	v_rcp_f32_e32 v157, v157
	v_rcp_f32_e32 v158, v158
	v_rcp_f32_e32 v159, v159
	v_cvt_pk_bf16_f32 v116, v152, v153
	v_cvt_pk_bf16_f32 v117, v154, v155
	v_cvt_pk_bf16_f32 v118, v156, v157
	v_cvt_pk_bf16_f32 v119, v158, v159
	s_nop 1
	v_permlane16_swap_b32_e32 v116, v118
	v_permlane16_swap_b32_e32 v117, v119
	global_store_dwordx4 v[150:151], v[116:119], off offset:256 sc1
	s_nop 0
	v_lshl_add_u64 v[150:151], v[150:151], 0, s[44:45]
	v_mul_f32_e32 v152, 0xbfb8aa3b, v108
	v_mul_f32_e32 v153, 0xbfb8aa3b, v109
	v_mul_f32_e32 v154, 0xbfb8aa3b, v110
	v_mul_f32_e32 v155, 0xbfb8aa3b, v111
	v_mul_f32_e32 v156, 0xbfb8aa3b, v104
	v_mul_f32_e32 v157, 0xbfb8aa3b, v105
	v_mul_f32_e32 v158, 0xbfb8aa3b, v106
	v_mul_f32_e32 v159, 0xbfb8aa3b, v107
	v_exp_f32_e32 v152, v152
	v_exp_f32_e32 v153, v153
	v_exp_f32_e32 v154, v154
	v_exp_f32_e32 v155, v155
	v_exp_f32_e32 v156, v156
	v_exp_f32_e32 v157, v157
	v_exp_f32_e32 v158, v158
	v_exp_f32_e32 v159, v159
	v_add_f32_e32 v152, 1.0, v152
	v_add_f32_e32 v153, 1.0, v153
	v_add_f32_e32 v154, 1.0, v154
	v_add_f32_e32 v155, 1.0, v155
	v_add_f32_e32 v156, 1.0, v156
	v_add_f32_e32 v157, 1.0, v157
	v_add_f32_e32 v158, 1.0, v158
	v_add_f32_e32 v159, 1.0, v159
	v_rcp_f32_e32 v152, v152
	v_rcp_f32_e32 v153, v153
	v_rcp_f32_e32 v154, v154
	v_rcp_f32_e32 v155, v155
	v_rcp_f32_e32 v156, v156
	v_rcp_f32_e32 v157, v157
	v_rcp_f32_e32 v158, v158
	v_rcp_f32_e32 v159, v159
	v_cvt_pk_bf16_f32 v108, v152, v153
	v_cvt_pk_bf16_f32 v109, v154, v155
	v_cvt_pk_bf16_f32 v110, v156, v157
	v_cvt_pk_bf16_f32 v111, v158, v159
	s_nop 1
	v_permlane16_swap_b32_e32 v108, v110
	v_permlane16_swap_b32_e32 v109, v111
	global_store_dwordx4 v[150:151], v[108:111], off sc1
	v_mul_f32_e32 v152, 0xbfb8aa3b, v100
	v_mul_f32_e32 v153, 0xbfb8aa3b, v101
	v_mul_f32_e32 v154, 0xbfb8aa3b, v102
	v_mul_f32_e32 v155, 0xbfb8aa3b, v103
	v_mul_f32_e32 v156, 0xbfb8aa3b, v96
	v_mul_f32_e32 v157, 0xbfb8aa3b, v97
	v_mul_f32_e32 v158, 0xbfb8aa3b, v98
	v_mul_f32_e32 v159, 0xbfb8aa3b, v99
	v_exp_f32_e32 v152, v152
	v_exp_f32_e32 v153, v153
	v_exp_f32_e32 v154, v154
	v_exp_f32_e32 v155, v155
	v_exp_f32_e32 v156, v156
	v_exp_f32_e32 v157, v157
	v_exp_f32_e32 v158, v158
	v_exp_f32_e32 v159, v159
	v_add_f32_e32 v152, 1.0, v152
	v_add_f32_e32 v153, 1.0, v153
	v_add_f32_e32 v154, 1.0, v154
	v_add_f32_e32 v155, 1.0, v155
	v_add_f32_e32 v156, 1.0, v156
	v_add_f32_e32 v157, 1.0, v157
	v_add_f32_e32 v158, 1.0, v158
	v_add_f32_e32 v159, 1.0, v159
	v_rcp_f32_e32 v152, v152
	v_rcp_f32_e32 v153, v153
	v_rcp_f32_e32 v154, v154
	v_rcp_f32_e32 v155, v155
	v_rcp_f32_e32 v156, v156
	v_rcp_f32_e32 v157, v157
	v_rcp_f32_e32 v158, v158
	v_rcp_f32_e32 v159, v159
	v_cvt_pk_bf16_f32 v100, v152, v153
	v_cvt_pk_bf16_f32 v101, v154, v155
	v_cvt_pk_bf16_f32 v102, v156, v157
	v_cvt_pk_bf16_f32 v103, v158, v159
	s_nop 1
	v_permlane16_swap_b32_e32 v100, v102
	v_permlane16_swap_b32_e32 v101, v103
	global_store_dwordx4 v[150:151], v[100:103], off offset:256 sc1
	s_nop 0
	v_lshl_add_u64 v[150:151], v[150:151], 0, s[44:45]
	v_mul_f32_e32 v152, 0xbfb8aa3b, v92
	v_mul_f32_e32 v153, 0xbfb8aa3b, v93
	v_mul_f32_e32 v154, 0xbfb8aa3b, v94
	v_mul_f32_e32 v155, 0xbfb8aa3b, v95
	v_mul_f32_e32 v156, 0xbfb8aa3b, v88
	v_mul_f32_e32 v157, 0xbfb8aa3b, v89
	v_mul_f32_e32 v158, 0xbfb8aa3b, v90
	v_mul_f32_e32 v159, 0xbfb8aa3b, v91
	v_exp_f32_e32 v152, v152
	v_exp_f32_e32 v153, v153
	v_exp_f32_e32 v154, v154
	v_exp_f32_e32 v155, v155
	v_exp_f32_e32 v156, v156
	v_exp_f32_e32 v157, v157
	v_exp_f32_e32 v158, v158
; __device__ __forceinline__ void st_bf4(bf16_t* p, f32x4 v) { u32x2 w; w.x = pk2(v[0], v[1]); w.y = pk2(v[2], v[3]); *(u32x2*)p = w; }
; __device__ __forceinline__ float sigmoidf_(float x) { return __builtin_amdgcn_rcpf(1.f + __expf(-x)); }
;     __device__ __forceinline__ void put(const Unit& u, int row, int col, f32x4 v) const {
;         const int pn = u.pn; bf16_t* base; int ldc, c0, act = 0;
;         if (pn < 2) { base = Q; ldc = 512; c0 = 0; act = 1; }
;         else if (pn < 4) { base = Kb; ldc = 512; c0 = 512; }
;         else if (pn < 8) { base = Vb; ldc = 1024; c0 = 1024; }
;         else if (pn < 12) { base = R; ldc = 1024; c0 = 2048; act = 2; }
;         else if (pn < 16) { base = F; ldc = 1024; c0 = 3072; }
;         else if (pn < 24) { base = GA; ldc = 2048; c0 = 4096; act = 3; }
;         else if (pn < 32) { base = GB; ldc = 2048; c0 = 6144; act = 3; }
;         else { base = LR; ldc = 256; c0 = 8192; }
;         if (act == 1) v = v * 0.08838834764831845f;
;         else if (act == 2) { v[0] *= sigmoidf_(v[0]); v[1] *= sigmoidf_(v[1]); v[2] *= sigmoidf_(v[2]); v[3] *= sigmoidf_(v[3]); }
;         else if (act == 3) { v[0] = sigmoidf_(v[0]); v[1] = sigmoidf_(v[1]); v[2] = sigmoidf_(v[2]); v[3] = sigmoidf_(v[3]); }
;         st_bf4(base + (size_t)row * ldc + (col - c0), v);
	v_exp_f32_e32 v159, v159
	v_add_f32_e32 v152, 1.0, v152
	v_add_f32_e32 v153, 1.0, v153
	v_add_f32_e32 v154, 1.0, v154
	v_add_f32_e32 v155, 1.0, v155
	v_add_f32_e32 v156, 1.0, v156
	v_add_f32_e32 v157, 1.0, v157
	v_add_f32_e32 v158, 1.0, v158
	v_add_f32_e32 v159, 1.0, v159
	v_rcp_f32_e32 v152, v152
	v_rcp_f32_e32 v153, v153
	v_rcp_f32_e32 v154, v154
	v_rcp_f32_e32 v155, v155
	v_rcp_f32_e32 v156, v156
	v_rcp_f32_e32 v157, v157
	v_rcp_f32_e32 v158, v158
	v_rcp_f32_e32 v159, v159
	v_cvt_pk_bf16_f32 v92, v152, v153
	v_cvt_pk_bf16_f32 v93, v154, v155
	v_cvt_pk_bf16_f32 v94, v156, v157
	v_cvt_pk_bf16_f32 v95, v158, v159
	s_nop 1
	v_permlane16_swap_b32_e32 v92, v94
	v_permlane16_swap_b32_e32 v93, v95
	global_store_dwordx4 v[150:151], v[92:95], off sc1
	v_mul_f32_e32 v152, 0xbfb8aa3b, v84
	v_mul_f32_e32 v153, 0xbfb8aa3b, v85
	v_mul_f32_e32 v154, 0xbfb8aa3b, v86
	v_mul_f32_e32 v155, 0xbfb8aa3b, v87
	v_mul_f32_e32 v156, 0xbfb8aa3b, v80
	v_mul_f32_e32 v157, 0xbfb8aa3b, v81
	v_mul_f32_e32 v158, 0xbfb8aa3b, v82
	v_mul_f32_e32 v159, 0xbfb8aa3b, v83
	v_exp_f32_e32 v152, v152
	v_exp_f32_e32 v153, v153
	v_exp_f32_e32 v154, v154
	v_exp_f32_e32 v155, v155
	v_exp_f32_e32 v156, v156
	v_exp_f32_e32 v157, v157
	v_exp_f32_e32 v158, v158
	v_exp_f32_e32 v159, v159
	v_add_f32_e32 v152, 1.0, v152
	v_add_f32_e32 v153, 1.0, v153
	v_add_f32_e32 v154, 1.0, v154
	v_add_f32_e32 v155, 1.0, v155
	v_add_f32_e32 v156, 1.0, v156
	v_add_f32_e32 v157, 1.0, v157
	v_add_f32_e32 v158, 1.0, v158
	v_add_f32_e32 v159, 1.0, v159
	v_rcp_f32_e32 v152, v152
	v_rcp_f32_e32 v153, v153
	v_rcp_f32_e32 v154, v154
	v_rcp_f32_e32 v155, v155
	v_rcp_f32_e32 v156, v156
	v_rcp_f32_e32 v157, v157
	v_rcp_f32_e32 v158, v158
	v_rcp_f32_e32 v159, v159
	v_cvt_pk_bf16_f32 v84, v152, v153
	v_cvt_pk_bf16_f32 v85, v154, v155
	v_cvt_pk_bf16_f32 v86, v156, v157
	v_cvt_pk_bf16_f32 v87, v158, v159
	s_nop 1
	v_permlane16_swap_b32_e32 v84, v86
	v_permlane16_swap_b32_e32 v85, v87
	global_store_dwordx4 v[150:151], v[84:87], off offset:256 sc1
	s_nop 0
	v_lshl_add_u64 v[150:151], v[150:151], 0, s[44:45]
	v_mul_f32_e32 v152, 0xbfb8aa3b, v76
	v_mul_f32_e32 v153, 0xbfb8aa3b, v77
	v_mul_f32_e32 v154, 0xbfb8aa3b, v78
	v_mul_f32_e32 v155, 0xbfb8aa3b, v79
	v_mul_f32_e32 v156, 0xbfb8aa3b, v72
	v_mul_f32_e32 v157, 0xbfb8aa3b, v73
	v_mul_f32_e32 v158, 0xbfb8aa3b, v74
	v_mul_f32_e32 v159, 0xbfb8aa3b, v75
	v_exp_f32_e32 v152, v152
	v_exp_f32_e32 v153, v153
	v_exp_f32_e32 v154, v154
	v_exp_f32_e32 v155, v155
	v_exp_f32_e32 v156, v156
	v_exp_f32_e32 v157, v157
	v_exp_f32_e32 v158, v158
	v_exp_f32_e32 v159, v159
	v_add_f32_e32 v152, 1.0, v152
	v_add_f32_e32 v153, 1.0, v153
	v_add_f32_e32 v154, 1.0, v154
	v_add_f32_e32 v155, 1.0, v155
	v_add_f32_e32 v156, 1.0, v156
	v_add_f32_e32 v157, 1.0, v157
	v_add_f32_e32 v158, 1.0, v158
	v_add_f32_e32 v159, 1.0, v159
	v_rcp_f32_e32 v152, v152
	v_rcp_f32_e32 v153, v153
	v_rcp_f32_e32 v154, v154
	v_rcp_f32_e32 v155, v155
	v_rcp_f32_e32 v156, v156
	v_rcp_f32_e32 v157, v157
	v_rcp_f32_e32 v158, v158
	v_rcp_f32_e32 v159, v159
	v_cvt_pk_bf16_f32 v76, v152, v153
	v_cvt_pk_bf16_f32 v77, v154, v155
	v_cvt_pk_bf16_f32 v78, v156, v157
	v_cvt_pk_bf16_f32 v79, v158, v159
	s_nop 1
	v_permlane16_swap_b32_e32 v76, v78
	v_permlane16_swap_b32_e32 v77, v79
	global_store_dwordx4 v[150:151], v[76:79], off sc1
	v_mul_f32_e32 v152, 0xbfb8aa3b, v68
	v_mul_f32_e32 v153, 0xbfb8aa3b, v69
	v_mul_f32_e32 v154, 0xbfb8aa3b, v70
	v_mul_f32_e32 v155, 0xbfb8aa3b, v71
	v_mul_f32_e32 v156, 0xbfb8aa3b, v64
	v_mul_f32_e32 v157, 0xbfb8aa3b, v65
	v_mul_f32_e32 v158, 0xbfb8aa3b, v66
	v_mul_f32_e32 v159, 0xbfb8aa3b, v67
	v_exp_f32_e32 v152, v152
	v_exp_f32_e32 v153, v153
	v_exp_f32_e32 v154, v154
	v_exp_f32_e32 v155, v155
	v_exp_f32_e32 v156, v156
	v_exp_f32_e32 v157, v157
	v_exp_f32_e32 v158, v158
	v_exp_f32_e32 v159, v159
	v_add_f32_e32 v152, 1.0, v152
	v_add_f32_e32 v153, 1.0, v153
	v_add_f32_e32 v154, 1.0, v154
	v_add_f32_e32 v155, 1.0, v155
	v_add_f32_e32 v156, 1.0, v156
	v_add_f32_e32 v157, 1.0, v157
	v_add_f32_e32 v158, 1.0, v158
	v_add_f32_e32 v159, 1.0, v159
	v_rcp_f32_e32 v152, v152
	v_rcp_f32_e32 v153, v153
	v_rcp_f32_e32 v154, v154
	v_rcp_f32_e32 v155, v155
	v_rcp_f32_e32 v156, v156
	v_rcp_f32_e32 v157, v157
	v_rcp_f32_e32 v158, v158
	v_rcp_f32_e32 v159, v159
	v_cvt_pk_bf16_f32 v68, v152, v153
	v_cvt_pk_bf16_f32 v69, v154, v155
	v_cvt_pk_bf16_f32 v70, v156, v157
	v_cvt_pk_bf16_f32 v71, v158, v159
	s_nop 1
	v_permlane16_swap_b32_e32 v68, v70
	v_permlane16_swap_b32_e32 v69, v71
	global_store_dwordx4 v[150:151], v[68:71], off offset:256 sc1
	s_nop 0
	v_lshl_add_u64 v[150:151], v[150:151], 0, s[44:45]
	v_lshl_add_u64 v[150:151], v[150:151], 0, s[46:47]
	v_mul_f32_e32 v152, 0xbfb8aa3b, v60
	v_mul_f32_e32 v153, 0xbfb8aa3b, v61
	v_mul_f32_e32 v154, 0xbfb8aa3b, v62
	v_mul_f32_e32 v155, 0xbfb8aa3b, v63
	v_mul_f32_e32 v156, 0xbfb8aa3b, v56
	v_mul_f32_e32 v157, 0xbfb8aa3b, v57
	v_mul_f32_e32 v158, 0xbfb8aa3b, v58
	v_mul_f32_e32 v159, 0xbfb8aa3b, v59
	v_exp_f32_e32 v152, v152
	v_exp_f32_e32 v153, v153
	v_exp_f32_e32 v154, v154
	v_exp_f32_e32 v155, v155
	v_exp_f32_e32 v156, v156
	v_exp_f32_e32 v157, v157
	v_exp_f32_e32 v158, v158
	v_exp_f32_e32 v159, v159
	v_add_f32_e32 v152, 1.0, v152
	v_add_f32_e32 v153, 1.0, v153
	v_add_f32_e32 v154, 1.0, v154
	v_add_f32_e32 v155, 1.0, v155
	v_add_f32_e32 v156, 1.0, v156
	v_add_f32_e32 v157, 1.0, v157
	v_add_f32_e32 v158, 1.0, v158
	v_add_f32_e32 v159, 1.0, v159
	v_rcp_f32_e32 v152, v152
	v_rcp_f32_e32 v153, v153
	v_rcp_f32_e32 v154, v154
	v_rcp_f32_e32 v155, v155
	v_rcp_f32_e32 v156, v156
	v_rcp_f32_e32 v157, v157
	v_rcp_f32_e32 v158, v158
	v_rcp_f32_e32 v159, v159
	v_cvt_pk_bf16_f32 v60, v152, v153
; __device__ __forceinline__ void st_bf4(bf16_t* p, f32x4 v) { u32x2 w; w.x = pk2(v[0], v[1]); w.y = pk2(v[2], v[3]); *(u32x2*)p = w; }
; __device__ __forceinline__ float sigmoidf_(float x) { return __builtin_amdgcn_rcpf(1.f + __expf(-x)); }
;     __device__ __forceinline__ void put(const Unit& u, int row, int col, f32x4 v) const {
;         const int pn = u.pn; bf16_t* base; int ldc, c0, act = 0;
;         if (pn < 2) { base = Q; ldc = 512; c0 = 0; act = 1; }
;         else if (pn < 4) { base = Kb; ldc = 512; c0 = 512; }
;         else if (pn < 8) { base = Vb; ldc = 1024; c0 = 1024; }
;         else if (pn < 12) { base = R; ldc = 1024; c0 = 2048; act = 2; }
;         else if (pn < 16) { base = F; ldc = 1024; c0 = 3072; }
;         else if (pn < 24) { base = GA; ldc = 2048; c0 = 4096; act = 3; }
;         else if (pn < 32) { base = GB; ldc = 2048; c0 = 6144; act = 3; }
;         else { base = LR; ldc = 256; c0 = 8192; }
;         if (act == 1) v = v * 0.08838834764831845f;
;         else if (act == 2) { v[0] *= sigmoidf_(v[0]); v[1] *= sigmoidf_(v[1]); v[2] *= sigmoidf_(v[2]); v[3] *= sigmoidf_(v[3]); }
;         else if (act == 3) { v[0] = sigmoidf_(v[0]); v[1] = sigmoidf_(v[1]); v[2] = sigmoidf_(v[2]); v[3] = sigmoidf_(v[3]); }
;         st_bf4(base + (size_t)row * ldc + (col - c0), v);
	v_cvt_pk_bf16_f32 v61, v154, v155
	v_cvt_pk_bf16_f32 v62, v156, v157
	v_cvt_pk_bf16_f32 v63, v158, v159
	s_nop 1
	v_permlane16_swap_b32_e32 v60, v62
	v_permlane16_swap_b32_e32 v61, v63
	global_store_dwordx4 v[150:151], v[60:63], off sc1
	v_mul_f32_e32 v152, 0xbfb8aa3b, v52
	v_mul_f32_e32 v153, 0xbfb8aa3b, v53
	v_mul_f32_e32 v154, 0xbfb8aa3b, v54
	v_mul_f32_e32 v155, 0xbfb8aa3b, v55
	v_mul_f32_e32 v156, 0xbfb8aa3b, v48
	v_mul_f32_e32 v157, 0xbfb8aa3b, v49
	v_mul_f32_e32 v158, 0xbfb8aa3b, v50
	v_mul_f32_e32 v159, 0xbfb8aa3b, v51
	v_exp_f32_e32 v152, v152
	v_exp_f32_e32 v153, v153
	v_exp_f32_e32 v154, v154
	v_exp_f32_e32 v155, v155
	v_exp_f32_e32 v156, v156
	v_exp_f32_e32 v157, v157
	v_exp_f32_e32 v158, v158
	v_exp_f32_e32 v159, v159
	v_add_f32_e32 v152, 1.0, v152
	v_add_f32_e32 v153, 1.0, v153
	v_add_f32_e32 v154, 1.0, v154
	v_add_f32_e32 v155, 1.0, v155
	v_add_f32_e32 v156, 1.0, v156
	v_add_f32_e32 v157, 1.0, v157
	v_add_f32_e32 v158, 1.0, v158
	v_add_f32_e32 v159, 1.0, v159
	v_rcp_f32_e32 v152, v152
	v_rcp_f32_e32 v153, v153
	v_rcp_f32_e32 v154, v154
	v_rcp_f32_e32 v155, v155
	v_rcp_f32_e32 v156, v156
	v_rcp_f32_e32 v157, v157
	v_rcp_f32_e32 v158, v158
	v_rcp_f32_e32 v159, v159
	v_cvt_pk_bf16_f32 v52, v152, v153
	v_cvt_pk_bf16_f32 v53, v154, v155
	v_cvt_pk_bf16_f32 v54, v156, v157
	v_cvt_pk_bf16_f32 v55, v158, v159
	s_nop 1
	v_permlane16_swap_b32_e32 v52, v54
	v_permlane16_swap_b32_e32 v53, v55
	global_store_dwordx4 v[150:151], v[52:55], off offset:256 sc1
	s_nop 0
	v_lshl_add_u64 v[150:151], v[150:151], 0, s[44:45]
	v_mul_f32_e32 v152, 0xbfb8aa3b, v44
	v_mul_f32_e32 v153, 0xbfb8aa3b, v45
	v_mul_f32_e32 v154, 0xbfb8aa3b, v46
	v_mul_f32_e32 v155, 0xbfb8aa3b, v47
	v_mul_f32_e32 v156, 0xbfb8aa3b, v40
	v_mul_f32_e32 v157, 0xbfb8aa3b, v41
	v_mul_f32_e32 v158, 0xbfb8aa3b, v42
	v_mul_f32_e32 v159, 0xbfb8aa3b, v43
	v_exp_f32_e32 v152, v152
	v_exp_f32_e32 v153, v153
	v_exp_f32_e32 v154, v154
	v_exp_f32_e32 v155, v155
	v_exp_f32_e32 v156, v156
	v_exp_f32_e32 v157, v157
	v_exp_f32_e32 v158, v158
	v_exp_f32_e32 v159, v159
	v_add_f32_e32 v152, 1.0, v152
	v_add_f32_e32 v153, 1.0, v153
	v_add_f32_e32 v154, 1.0, v154
	v_add_f32_e32 v155, 1.0, v155
	v_add_f32_e32 v156, 1.0, v156
	v_add_f32_e32 v157, 1.0, v157
	v_add_f32_e32 v158, 1.0, v158
	v_add_f32_e32 v159, 1.0, v159
	v_rcp_f32_e32 v152, v152
	v_rcp_f32_e32 v153, v153
	v_rcp_f32_e32 v154, v154
	v_rcp_f32_e32 v155, v155
	v_rcp_f32_e32 v156, v156
	v_rcp_f32_e32 v157, v157
	v_rcp_f32_e32 v158, v158
	v_rcp_f32_e32 v159, v159
	v_cvt_pk_bf16_f32 v44, v152, v153
	v_cvt_pk_bf16_f32 v45, v154, v155
	v_cvt_pk_bf16_f32 v46, v156, v157
	v_cvt_pk_bf16_f32 v47, v158, v159
	s_nop 1
	v_permlane16_swap_b32_e32 v44, v46
	v_permlane16_swap_b32_e32 v45, v47
	global_store_dwordx4 v[150:151], v[44:47], off sc1
	v_mul_f32_e32 v152, 0xbfb8aa3b, v36
	v_mul_f32_e32 v153, 0xbfb8aa3b, v37
	v_mul_f32_e32 v154, 0xbfb8aa3b, v38
	v_mul_f32_e32 v155, 0xbfb8aa3b, v39
	v_mul_f32_e32 v156, 0xbfb8aa3b, v32
	v_mul_f32_e32 v157, 0xbfb8aa3b, v33
	v_mul_f32_e32 v158, 0xbfb8aa3b, v34
	v_mul_f32_e32 v159, 0xbfb8aa3b, v35
	v_exp_f32_e32 v152, v152
	v_exp_f32_e32 v153, v153
	v_exp_f32_e32 v154, v154
	v_exp_f32_e32 v155, v155
	v_exp_f32_e32 v156, v156
	v_exp_f32_e32 v157, v157
	v_exp_f32_e32 v158, v158
	v_exp_f32_e32 v159, v159
	v_add_f32_e32 v152, 1.0, v152
	v_add_f32_e32 v153, 1.0, v153
	v_add_f32_e32 v154, 1.0, v154
	v_add_f32_e32 v155, 1.0, v155
	v_add_f32_e32 v156, 1.0, v156
	v_add_f32_e32 v157, 1.0, v157
	v_add_f32_e32 v158, 1.0, v158
	v_add_f32_e32 v159, 1.0, v159
	v_rcp_f32_e32 v152, v152
	v_rcp_f32_e32 v153, v153
	v_rcp_f32_e32 v154, v154
	v_rcp_f32_e32 v155, v155
	v_rcp_f32_e32 v156, v156
	v_rcp_f32_e32 v157, v157
	v_rcp_f32_e32 v158, v158
	v_rcp_f32_e32 v159, v159
	v_cvt_pk_bf16_f32 v36, v152, v153
	v_cvt_pk_bf16_f32 v37, v154, v155
	v_cvt_pk_bf16_f32 v38, v156, v157
	v_cvt_pk_bf16_f32 v39, v158, v159
	s_nop 1
	v_permlane16_swap_b32_e32 v36, v38
	v_permlane16_swap_b32_e32 v37, v39
	global_store_dwordx4 v[150:151], v[36:39], off offset:256 sc1
	s_nop 0
	v_lshl_add_u64 v[150:151], v[150:151], 0, s[44:45]
	v_mul_f32_e32 v152, 0xbfb8aa3b, v28
	v_mul_f32_e32 v153, 0xbfb8aa3b, v29
	v_mul_f32_e32 v154, 0xbfb8aa3b, v30
	v_mul_f32_e32 v155, 0xbfb8aa3b, v31
	v_mul_f32_e32 v156, 0xbfb8aa3b, v24
	v_mul_f32_e32 v157, 0xbfb8aa3b, v25
	v_mul_f32_e32 v158, 0xbfb8aa3b, v26
	v_mul_f32_e32 v159, 0xbfb8aa3b, v27
	v_exp_f32_e32 v152, v152
	v_exp_f32_e32 v153, v153
	v_exp_f32_e32 v154, v154
	v_exp_f32_e32 v155, v155
	v_exp_f32_e32 v156, v156
	v_exp_f32_e32 v157, v157
	v_exp_f32_e32 v158, v158
; __device__ __forceinline__ void st_bf4(bf16_t* p, f32x4 v) { u32x2 w; w.x = pk2(v[0], v[1]); w.y = pk2(v[2], v[3]); *(u32x2*)p = w; }
; __device__ __forceinline__ float sigmoidf_(float x) { return __builtin_amdgcn_rcpf(1.f + __expf(-x)); }
;     __device__ __forceinline__ void put(const Unit& u, int row, int col, f32x4 v) const {
;         const int pn = u.pn; bf16_t* base; int ldc, c0, act = 0;
;         if (pn < 2) { base = Q; ldc = 512; c0 = 0; act = 1; }
;         else if (pn < 4) { base = Kb; ldc = 512; c0 = 512; }
;         else if (pn < 8) { base = Vb; ldc = 1024; c0 = 1024; }
;         else if (pn < 12) { base = R; ldc = 1024; c0 = 2048; act = 2; }
;         else if (pn < 16) { base = F; ldc = 1024; c0 = 3072; }
;         else if (pn < 24) { base = GA; ldc = 2048; c0 = 4096; act = 3; }
;         else if (pn < 32) { base = GB; ldc = 2048; c0 = 6144; act = 3; }
;         else { base = LR; ldc = 256; c0 = 8192; }
;         if (act == 1) v = v * 0.08838834764831845f;
;         else if (act == 2) { v[0] *= sigmoidf_(v[0]); v[1] *= sigmoidf_(v[1]); v[2] *= sigmoidf_(v[2]); v[3] *= sigmoidf_(v[3]); }
;         else if (act == 3) { v[0] = sigmoidf_(v[0]); v[1] = sigmoidf_(v[1]); v[2] = sigmoidf_(v[2]); v[3] = sigmoidf_(v[3]); }
;         st_bf4(base + (size_t)row * ldc + (col - c0), v);
	v_exp_f32_e32 v159, v159
	v_add_f32_e32 v152, 1.0, v152
	v_add_f32_e32 v153, 1.0, v153
	v_add_f32_e32 v154, 1.0, v154
	v_add_f32_e32 v155, 1.0, v155
	v_add_f32_e32 v156, 1.0, v156
	v_add_f32_e32 v157, 1.0, v157
	v_add_f32_e32 v158, 1.0, v158
	v_add_f32_e32 v159, 1.0, v159
	v_rcp_f32_e32 v152, v152
	v_rcp_f32_e32 v153, v153
	v_rcp_f32_e32 v154, v154
	v_rcp_f32_e32 v155, v155
	v_rcp_f32_e32 v156, v156
	v_rcp_f32_e32 v157, v157
	v_rcp_f32_e32 v158, v158
	v_rcp_f32_e32 v159, v159
	v_cvt_pk_bf16_f32 v28, v152, v153
	v_cvt_pk_bf16_f32 v29, v154, v155
	v_cvt_pk_bf16_f32 v30, v156, v157
	v_cvt_pk_bf16_f32 v31, v158, v159
	s_nop 1
	v_permlane16_swap_b32_e32 v28, v30
	v_permlane16_swap_b32_e32 v29, v31
	global_store_dwordx4 v[150:151], v[28:31], off sc1
	v_mul_f32_e32 v152, 0xbfb8aa3b, v20
	v_mul_f32_e32 v153, 0xbfb8aa3b, v21
	v_mul_f32_e32 v154, 0xbfb8aa3b, v22
	v_mul_f32_e32 v155, 0xbfb8aa3b, v23
	v_mul_f32_e32 v156, 0xbfb8aa3b, v16
	v_mul_f32_e32 v157, 0xbfb8aa3b, v17
	v_mul_f32_e32 v158, 0xbfb8aa3b, v18
	v_mul_f32_e32 v159, 0xbfb8aa3b, v19
	v_exp_f32_e32 v152, v152
	v_exp_f32_e32 v153, v153
	v_exp_f32_e32 v154, v154
	v_exp_f32_e32 v155, v155
	v_exp_f32_e32 v156, v156
	v_exp_f32_e32 v157, v157
	v_exp_f32_e32 v158, v158
	v_exp_f32_e32 v159, v159
	v_add_f32_e32 v152, 1.0, v152
	v_add_f32_e32 v153, 1.0, v153
	v_add_f32_e32 v154, 1.0, v154
	v_add_f32_e32 v155, 1.0, v155
	v_add_f32_e32 v156, 1.0, v156
	v_add_f32_e32 v157, 1.0, v157
	v_add_f32_e32 v158, 1.0, v158
	v_add_f32_e32 v159, 1.0, v159
	v_rcp_f32_e32 v152, v152
	v_rcp_f32_e32 v153, v153
	v_rcp_f32_e32 v154, v154
	v_rcp_f32_e32 v155, v155
	v_rcp_f32_e32 v156, v156
	v_rcp_f32_e32 v157, v157
	v_rcp_f32_e32 v158, v158
	v_rcp_f32_e32 v159, v159
	v_cvt_pk_bf16_f32 v20, v152, v153
	v_cvt_pk_bf16_f32 v21, v154, v155
	v_cvt_pk_bf16_f32 v22, v156, v157
	v_cvt_pk_bf16_f32 v23, v158, v159
	s_nop 1
	v_permlane16_swap_b32_e32 v20, v22
	v_permlane16_swap_b32_e32 v21, v23
	global_store_dwordx4 v[150:151], v[20:23], off offset:256 sc1
	s_nop 0
	v_lshl_add_u64 v[150:151], v[150:151], 0, s[44:45]
	v_mul_f32_e32 v152, 0xbfb8aa3b, v12
	v_mul_f32_e32 v153, 0xbfb8aa3b, v13
	v_mul_f32_e32 v154, 0xbfb8aa3b, v14
	v_mul_f32_e32 v155, 0xbfb8aa3b, v15
	v_mul_f32_e32 v156, 0xbfb8aa3b, v8
	v_mul_f32_e32 v157, 0xbfb8aa3b, v9
	v_mul_f32_e32 v158, 0xbfb8aa3b, v10
	v_mul_f32_e32 v159, 0xbfb8aa3b, v11
	v_exp_f32_e32 v152, v152
	v_exp_f32_e32 v153, v153
	v_exp_f32_e32 v154, v154
	v_exp_f32_e32 v155, v155
	v_exp_f32_e32 v156, v156
	v_exp_f32_e32 v157, v157
	v_exp_f32_e32 v158, v158
	v_exp_f32_e32 v159, v159
	v_add_f32_e32 v152, 1.0, v152
	v_add_f32_e32 v153, 1.0, v153
	v_add_f32_e32 v154, 1.0, v154
	v_add_f32_e32 v155, 1.0, v155
	v_add_f32_e32 v156, 1.0, v156
	v_add_f32_e32 v157, 1.0, v157
	v_add_f32_e32 v158, 1.0, v158
	v_add_f32_e32 v159, 1.0, v159
	v_rcp_f32_e32 v152, v152
	v_rcp_f32_e32 v153, v153
	v_rcp_f32_e32 v154, v154
	v_rcp_f32_e32 v155, v155
	v_rcp_f32_e32 v156, v156
	v_rcp_f32_e32 v157, v157
	v_rcp_f32_e32 v158, v158
	v_rcp_f32_e32 v159, v159
	v_cvt_pk_bf16_f32 v12, v152, v153
	v_cvt_pk_bf16_f32 v13, v154, v155
	v_cvt_pk_bf16_f32 v14, v156, v157
	v_cvt_pk_bf16_f32 v15, v158, v159
	s_nop 1
	v_permlane16_swap_b32_e32 v12, v14
	v_permlane16_swap_b32_e32 v13, v15
	global_store_dwordx4 v[150:151], v[12:15], off sc1
	v_mul_f32_e32 v152, 0xbfb8aa3b, v4
	v_mul_f32_e32 v153, 0xbfb8aa3b, v5
	v_mul_f32_e32 v154, 0xbfb8aa3b, v6
	v_mul_f32_e32 v155, 0xbfb8aa3b, v7
	v_mul_f32_e32 v156, 0xbfb8aa3b, v0
	v_mul_f32_e32 v157, 0xbfb8aa3b, v1
	v_mul_f32_e32 v158, 0xbfb8aa3b, v2
	v_mul_f32_e32 v159, 0xbfb8aa3b, v3
	v_exp_f32_e32 v152, v152
	v_exp_f32_e32 v153, v153
	v_exp_f32_e32 v154, v154
	v_exp_f32_e32 v155, v155
	v_exp_f32_e32 v156, v156
	v_exp_f32_e32 v157, v157
	v_exp_f32_e32 v158, v158
	v_exp_f32_e32 v159, v159
	v_add_f32_e32 v152, 1.0, v152
	v_add_f32_e32 v153, 1.0, v153
	v_add_f32_e32 v154, 1.0, v154
	v_add_f32_e32 v155, 1.0, v155
	v_add_f32_e32 v156, 1.0, v156
	v_add_f32_e32 v157, 1.0, v157
	v_add_f32_e32 v158, 1.0, v158
	v_add_f32_e32 v159, 1.0, v159
	v_rcp_f32_e32 v152, v152
	v_rcp_f32_e32 v153, v153
	v_rcp_f32_e32 v154, v154
	v_rcp_f32_e32 v155, v155
	v_rcp_f32_e32 v156, v156
	v_rcp_f32_e32 v157, v157
	v_rcp_f32_e32 v158, v158
	v_rcp_f32_e32 v159, v159
	v_cvt_pk_bf16_f32 v4, v152, v153
	v_cvt_pk_bf16_f32 v5, v154, v155
	v_cvt_pk_bf16_f32 v6, v156, v157
	v_cvt_pk_bf16_f32 v7, v158, v159
	s_nop 1
	v_permlane16_swap_b32_e32 v4, v6
	v_permlane16_swap_b32_e32 v5, v7
	global_store_dwordx4 v[150:151], v[4:7], off offset:256 sc1
	s_branch .Lp2e_done

; __device__ __forceinline__ unsigned xb_add(unsigned* p, unsigned v) { return __hip_atomic_fetch_add(p, v, __ATOMIC_RELAXED, __HIP_MEMORY_SCOPE_AGENT); }
; __device__ __forceinline__ void xcd_barrier(const XcdBarrier& b) {
;     ...
;         if (old + 1u == (gen + 1u) * nloc) {
;             __builtin_amdgcn_fence(__ATOMIC_RELEASE, "agent");
;             asm volatile("s_waitcnt vmcnt(0)" ::: "memory");
;             const unsigned og = xb_add(&bar[XB_TOP], 1u);
.LBB0_1002:
	s_andn2_saveexec_b64 s[10:11], s[10:11]
	s_cbranch_execz .LBB0_1022
	s_mov_b64 s[10:11], exec
	s_waitcnt lgkmcnt(0)
	s_waitcnt vmcnt(0)
	v_mbcnt_lo_u32_b32 v1, s10, 0
	v_mbcnt_hi_u32_b32 v1, s11, v1
	v_cmp_eq_u32_e32 vcc, 0, v1
	s_and_saveexec_b64 s[16:17], vcc
	s_cbranch_execz .LBB0_1005
	s_bcnt1_i32_b64 s10, s[10:11]
	v_mov_b32_e32 v2, 0x7000
	v_mov_b32_e32 v3, s10
	global_atomic_add v2, v2, v3, s[66:67] offset:1024 sc0

; __device__ __forceinline__ void st_bf4(bf16_t* p, f32x4 v) { u32x2 w; w.x = pk2(v[0], v[1]); w.y = pk2(v[2], v[3]); *(u32x2*)p = w; }
; __device__ __forceinline__ float sigmoidf_(float x) { return __builtin_amdgcn_rcpf(1.f + __expf(-x)); }
; __device__ __forceinline__ float dpp_ror1(float v) { return __int_as_float(__builtin_amdgcn_update_dpp(0, __float_as_int(v), 0x121, 0xf, 0xf, false)); }
; __device__ __forceinline__ float dpp_rol1(float v) { return __int_as_float(__builtin_amdgcn_update_dpp(0, __float_as_int(v), 0x12F, 0xf, 0xf, false)); }
;     __device__ __forceinline__ void tile(const f32x4 (&acc)[2][2][4][2], const Unit& u, int wr, int wc, int fr, int fq) const {
; #pragma unroll
;         for (int n = 0; n < 2; ++n) {
;             const int cv = 128 * u.pn + 32 * wc + 16 * n + 4 * fq, cg = FF + cv;
;             const f32x4 wv0 = *(const f32x4*)(cw + cv), wv1 = *(const f32x4*)(cw + F2 + cv), wv2 = *(const f32x4*)(cw + 2 * F2 + cv), bv = *(const f32x4*)(cb + cv);
;             const f32x4 wg0 = *(const f32x4*)(cw + cg), wg1 = *(const f32x4*)(cw + F2 + cg), wg2 = *(const f32x4*)(cw + 2 * F2 + cg), bg = *(const f32x4*)(cb + cg);
; #pragma unroll
;             for (int ai = 0; ai < 2; ++ai)
; #pragma unroll
;                 for (int m = 0; m < 4; ++m) {
;                     f32x4 r;
; #pragma unroll
;                     for (int i = 0; i < 4; ++i) {
;                         const float xv = acc[ai][0][m][n][i], xg = acc[ai][1][m][n][i];
;                         const float uv = m > 0 ? acc[ai][0][m > 0 ? m - 1 : 0][n][i] : 0.f, ug = m > 0 ? acc[ai][1][m > 0 ? m - 1 : 0][n][i] : 0.f;
;                         const float dv = m < 3 ? acc[ai][0][m < 3 ? m + 1 : 3][n][i] : 0.f, dg = m < 3 ? acc[ai][1][m < 3 ? m + 1 : 3][n][i] : 0.f;
;                         const float pv = dpp_ror1(fr == 15 ? uv : xv), pg = dpp_ror1(fr == 15 ? ug : xg);
;                         const float nv = dpp_rol1(fr == 0 ? dv : xv), ng = dpp_rol1(fr == 0 ? dg : xg);
;                         const float yv = wv0[i] * pv + wv1[i] * xv + wv2[i] * nv + bv[i];
;                         const float yg = wg0[i] * pg + wg1[i] * xg + wg2[i] * ng + bg[i];
;                         r[i] = yg * sigmoidf_(yg) * yv;
;                     }
;                     st_bf4(ACT + (size_t)(u.pm * BM + ai * HALF + wr * 64 + m * 16 + fr) * FF + cv, r);
;                 }
;         }
.Lp9c_nowait:
	v_mov_b32_dpp v216, v96 row_shr:1 row_mask:0xf bank_mask:0xf bound_ctrl:1
	v_mov_b32_dpp v217, v97 row_shr:1 row_mask:0xf bank_mask:0xf bound_ctrl:1
	v_mov_b32_dpp v218, v98 row_shr:1 row_mask:0xf bank_mask:0xf bound_ctrl:1
	v_mov_b32_dpp v219, v99 row_shr:1 row_mask:0xf bank_mask:0xf bound_ctrl:1
	v_mov_b32_dpp v220, v152 row_shl:1 row_mask:0xf bank_mask:0xf bound_ctrl:1
	v_mov_b32_dpp v221, v153 row_shl:1 row_mask:0xf bank_mask:0xf bound_ctrl:1
	v_mov_b32_dpp v222, v154 row_shl:1 row_mask:0xf bank_mask:0xf bound_ctrl:1
	v_mov_b32_dpp v223, v155 row_shl:1 row_mask:0xf bank_mask:0xf bound_ctrl:1
	v_pk_mul_f32 v[176:177], v[152:153], v[234:235]
	v_pk_mul_f32 v[178:179], v[154:155], v[236:237]
	v_pk_mul_f32 v[180:181], v[112:113], v[234:235]
	v_pk_mul_f32 v[182:183], v[114:115], v[236:237]
	v_pk_mul_f32 v[184:185], v[104:105], v[234:235]
	v_pk_mul_f32 v[186:187], v[106:107], v[236:237]
	v_pk_mul_f32 v[224:225], v[96:97], v[234:235]
	v_pk_mul_f32 v[226:227], v[98:99], v[236:237]
	v_pk_fma_f32 v[176:177], v[230:231], v[216:217], v[176:177]
	v_pk_fma_f32 v[178:179], v[232:233], v[218:219], v[178:179]
	v_pk_fma_f32 v[180:181], v[230:231], v[152:153], v[180:181]
	v_pk_fma_f32 v[182:183], v[232:233], v[154:155], v[182:183]
	v_pk_fma_f32 v[184:185], v[230:231], v[112:113], v[184:185]
	v_pk_fma_f32 v[186:187], v[232:233], v[114:115], v[186:187]
	v_pk_fma_f32 v[224:225], v[230:231], v[104:105], v[224:225]
	v_pk_fma_f32 v[226:227], v[232:233], v[106:107], v[226:227]
	v_pk_fma_f32 v[176:177], v[238:239], v[112:113], v[176:177]
	v_pk_fma_f32 v[178:179], v[240:241], v[114:115], v[178:179]
	v_pk_fma_f32 v[180:181], v[238:239], v[104:105], v[180:181]
	v_pk_fma_f32 v[182:183], v[240:241], v[106:107], v[182:183]
	v_pk_fma_f32 v[184:185], v[238:239], v[96:97], v[184:185]
	v_pk_fma_f32 v[186:187], v[240:241], v[98:99], v[186:187]
	v_pk_fma_f32 v[224:225], v[238:239], v[220:221], v[224:225]
	v_pk_fma_f32 v[226:227], v[240:241], v[222:223], v[226:227]
	v_pk_add_f32 v[176:177], v[242:243], v[176:177]
	v_pk_add_f32 v[178:179], v[244:245], v[178:179]
	v_pk_add_f32 v[180:181], v[242:243], v[180:181]
	v_pk_add_f32 v[182:183], v[244:245], v[182:183]
	v_pk_add_f32 v[184:185], v[242:243], v[184:185]
	v_pk_add_f32 v[186:187], v[244:245], v[186:187]
	v_pk_add_f32 v[224:225], v[242:243], v[224:225]
	v_pk_add_f32 v[226:227], v[244:245], v[226:227]
	v_mov_b32_dpp v216, v100 row_shr:1 row_mask:0xf bank_mask:0xf bound_ctrl:1
	v_mov_b32_dpp v217, v101 row_shr:1 row_mask:0xf bank_mask:0xf bound_ctrl:1
	v_mov_b32_dpp v218, v102 row_shr:1 row_mask:0xf bank_mask:0xf bound_ctrl:1
	v_mov_b32_dpp v219, v103 row_shr:1 row_mask:0xf bank_mask:0xf bound_ctrl:1
	v_mov_b32_dpp v220, v156 row_shl:1 row_mask:0xf bank_mask:0xf bound_ctrl:1
	v_mov_b32_dpp v221, v157 row_shl:1 row_mask:0xf bank_mask:0xf bound_ctrl:1
	v_mov_b32_dpp v222, v158 row_shl:1 row_mask:0xf bank_mask:0xf bound_ctrl:1
	v_mov_b32_dpp v223, v159 row_shl:1 row_mask:0xf bank_mask:0xf bound_ctrl:1
	v_pk_mul_f32 v[152:153], v[156:157], v[250:251]
	v_pk_mul_f32 v[154:155], v[158:159], v[252:253]
	v_pk_mul_f32 v[112:113], v[116:117], v[250:251]
	v_pk_mul_f32 v[114:115], v[118:119], v[252:253]
	v_pk_mul_f32 v[104:105], v[108:109], v[250:251]
	v_pk_mul_f32 v[106:107], v[110:111], v[252:253]
	v_pk_mul_f32 v[96:97], v[100:101], v[250:251]
	v_pk_mul_f32 v[98:99], v[102:103], v[252:253]
	v_pk_fma_f32 v[152:153], v[246:247], v[216:217], v[152:153]
	v_pk_fma_f32 v[154:155], v[248:249], v[218:219], v[154:155]
	v_pk_fma_f32 v[112:113], v[246:247], v[156:157], v[112:113]
	v_pk_fma_f32 v[114:115], v[248:249], v[158:159], v[114:115]
	v_pk_fma_f32 v[104:105], v[246:247], v[116:117], v[104:105]
	v_pk_fma_f32 v[106:107], v[248:249], v[118:119], v[106:107]
	v_pk_fma_f32 v[96:97], v[246:247], v[108:109], v[96:97]
	v_pk_fma_f32 v[98:99], v[248:249], v[110:111], v[98:99]
	s_waitcnt vmcnt(8)
	v_pk_fma_f32 v[152:153], v[120:121], v[116:117], v[152:153]
	v_pk_fma_f32 v[154:155], v[122:123], v[118:119], v[154:155]
	v_pk_fma_f32 v[112:113], v[120:121], v[108:109], v[112:113]
	v_pk_fma_f32 v[114:115], v[122:123], v[110:111], v[114:115]
	v_pk_fma_f32 v[104:105], v[120:121], v[100:101], v[104:105]
	v_pk_fma_f32 v[106:107], v[122:123], v[102:103], v[106:107]
	v_pk_fma_f32 v[96:97], v[120:121], v[220:221], v[96:97]
	v_pk_fma_f32 v[98:99], v[122:123], v[222:223], v[98:99]
	v_pk_add_f32 v[152:153], v[124:125], v[152:153]
	v_pk_add_f32 v[154:155], v[126:127], v[154:155]
	v_pk_add_f32 v[112:113], v[124:125], v[112:113]
	v_pk_add_f32 v[114:115], v[126:127], v[114:115]
	v_pk_add_f32 v[104:105], v[124:125], v[104:105]
	v_pk_add_f32 v[106:107], v[126:127], v[106:107]
	v_pk_add_f32 v[96:97], v[124:125], v[96:97]
	v_pk_add_f32 v[98:99], v[126:127], v[98:99]
	v_mul_f32_e32 v156, 0xbfb8aa3b, v176
	v_mul_f32_e32 v157, 0xbfb8aa3b, v177
	v_mul_f32_e32 v158, 0xbfb8aa3b, v178
	v_mul_f32_e32 v159, 0xbfb8aa3b, v179
	v_mul_f32_e32 v116, 0xbfb8aa3b, v180
	v_mul_f32_e32 v117, 0xbfb8aa3b, v181
	v_mul_f32_e32 v118, 0xbfb8aa3b, v182
	v_mul_f32_e32 v119, 0xbfb8aa3b, v183
	v_mul_f32_e32 v108, 0xbfb8aa3b, v184
	v_mul_f32_e32 v109, 0xbfb8aa3b, v185
	v_mul_f32_e32 v110, 0xbfb8aa3b, v186
	v_mul_f32_e32 v111, 0xbfb8aa3b, v187
	v_mul_f32_e32 v100, 0xbfb8aa3b, v224
	v_mul_f32_e32 v101, 0xbfb8aa3b, v225
	v_mul_f32_e32 v102, 0xbfb8aa3b, v226
	v_mul_f32_e32 v103, 0xbfb8aa3b, v227
	v_exp_f32_e32 v156, v156
	v_exp_f32_e32 v157, v157
	v_exp_f32_e32 v158, v158
	v_exp_f32_e32 v159, v159
	v_exp_f32_e32 v116, v116
	v_exp_f32_e32 v117, v117
	v_exp_f32_e32 v118, v118
	v_exp_f32_e32 v119, v119
	v_exp_f32_e32 v108, v108
	v_exp_f32_e32 v109, v109
	v_exp_f32_e32 v110, v110
	v_exp_f32_e32 v111, v111
; __device__ __forceinline__ void st_bf4(bf16_t* p, f32x4 v) { u32x2 w; w.x = pk2(v[0], v[1]); w.y = pk2(v[2], v[3]); *(u32x2*)p = w; }
; __device__ __forceinline__ float sigmoidf_(float x) { return __builtin_amdgcn_rcpf(1.f + __expf(-x)); }
; __device__ __forceinline__ float dpp_ror1(float v) { return __int_as_float(__builtin_amdgcn_update_dpp(0, __float_as_int(v), 0x121, 0xf, 0xf, false)); }
; __device__ __forceinline__ float dpp_rol1(float v) { return __int_as_float(__builtin_amdgcn_update_dpp(0, __float_as_int(v), 0x12F, 0xf, 0xf, false)); }
;     __device__ __forceinline__ void tile(const f32x4 (&acc)[2][2][4][2], const Unit& u, int wr, int wc, int fr, int fq) const {
; #pragma unroll
;         for (int n = 0; n < 2; ++n) {
;             const int cv = 128 * u.pn + 32 * wc + 16 * n + 4 * fq, cg = FF + cv;
;             const f32x4 wv0 = *(const f32x4*)(cw + cv), wv1 = *(const f32x4*)(cw + F2 + cv), wv2 = *(const f32x4*)(cw + 2 * F2 + cv), bv = *(const f32x4*)(cb + cv);
;             const f32x4 wg0 = *(const f32x4*)(cw + cg), wg1 = *(const f32x4*)(cw + F2 + cg), wg2 = *(const f32x4*)(cw + 2 * F2 + cg), bg = *(const f32x4*)(cb + cg);
; #pragma unroll
;             for (int ai = 0; ai < 2; ++ai)
; #pragma unroll
;                 for (int m = 0; m < 4; ++m) {
;                     f32x4 r;
; #pragma unroll
;                     for (int i = 0; i < 4; ++i) {
;                         const float xv = acc[ai][0][m][n][i], xg = acc[ai][1][m][n][i];
;                         const float uv = m > 0 ? acc[ai][0][m > 0 ? m - 1 : 0][n][i] : 0.f, ug = m > 0 ? acc[ai][1][m > 0 ? m - 1 : 0][n][i] : 0.f;
;                         const float dv = m < 3 ? acc[ai][0][m < 3 ? m + 1 : 3][n][i] : 0.f, dg = m < 3 ? acc[ai][1][m < 3 ? m + 1 : 3][n][i] : 0.f;
;                         const float pv = dpp_ror1(fr == 15 ? uv : xv), pg = dpp_ror1(fr == 15 ? ug : xg);
;                         const float nv = dpp_rol1(fr == 0 ? dv : xv), ng = dpp_rol1(fr == 0 ? dg : xg);
;                         const float yv = wv0[i] * pv + wv1[i] * xv + wv2[i] * nv + bv[i];
;                         const float yg = wg0[i] * pg + wg1[i] * xg + wg2[i] * ng + bg[i];
;                         r[i] = yg * sigmoidf_(yg) * yv;
;                     }
;                     st_bf4(ACT + (size_t)(u.pm * BM + ai * HALF + wr * 64 + m * 16 + fr) * FF + cv, r);
;                 }
;         }
	v_exp_f32_e32 v100, v100
	v_exp_f32_e32 v101, v101
	v_exp_f32_e32 v102, v102
	v_exp_f32_e32 v103, v103
	v_add_f32_e32 v156, 1.0, v156
	v_add_f32_e32 v157, 1.0, v157
	v_add_f32_e32 v158, 1.0, v158
	v_add_f32_e32 v159, 1.0, v159
	v_add_f32_e32 v116, 1.0, v116
	v_add_f32_e32 v117, 1.0, v117
	v_add_f32_e32 v118, 1.0, v118
	v_add_f32_e32 v119, 1.0, v119
	v_add_f32_e32 v108, 1.0, v108
	v_add_f32_e32 v109, 1.0, v109
	v_add_f32_e32 v110, 1.0, v110
	v_add_f32_e32 v111, 1.0, v111
	v_add_f32_e32 v100, 1.0, v100
	v_add_f32_e32 v101, 1.0, v101
	v_add_f32_e32 v102, 1.0, v102
	v_add_f32_e32 v103, 1.0, v103
	v_rcp_f32_e32 v156, v156
	v_rcp_f32_e32 v157, v157
	v_rcp_f32_e32 v158, v158
	v_rcp_f32_e32 v159, v159
	v_rcp_f32_e32 v116, v116
	v_rcp_f32_e32 v117, v117
	v_rcp_f32_e32 v118, v118
	v_rcp_f32_e32 v119, v119
	v_rcp_f32_e32 v108, v108
	v_rcp_f32_e32 v109, v109
	v_rcp_f32_e32 v110, v110
	v_rcp_f32_e32 v111, v111
	v_rcp_f32_e32 v100, v100
	v_rcp_f32_e32 v101, v101
	v_rcp_f32_e32 v102, v102
	v_rcp_f32_e32 v103, v103
	v_pk_mul_f32 v[176:177], v[176:177], v[156:157]
	v_pk_mul_f32 v[178:179], v[178:179], v[158:159]
	v_pk_mul_f32 v[180:181], v[180:181], v[116:117]
	v_pk_mul_f32 v[182:183], v[182:183], v[118:119]
	v_pk_mul_f32 v[184:185], v[184:185], v[108:109]
	v_pk_mul_f32 v[186:187], v[186:187], v[110:111]
	v_pk_mul_f32 v[224:225], v[224:225], v[100:101]
	v_pk_mul_f32 v[226:227], v[226:227], v[102:103]
	v_pk_mul_f32 v[176:177], v[152:153], v[176:177]
	v_pk_mul_f32 v[178:179], v[154:155], v[178:179]
	v_pk_mul_f32 v[180:181], v[112:113], v[180:181]
	v_pk_mul_f32 v[182:183], v[114:115], v[182:183]
	v_pk_mul_f32 v[184:185], v[104:105], v[184:185]
	v_pk_mul_f32 v[186:187], v[106:107], v[186:187]
	v_pk_mul_f32 v[224:225], v[96:97], v[224:225]
	v_pk_mul_f32 v[226:227], v[98:99], v[226:227]
	v_cvt_pk_bf16_f32 v156, v176, v177
	v_cvt_pk_bf16_f32 v157, v178, v179
	v_cvt_pk_bf16_f32 v116, v180, v181
	v_cvt_pk_bf16_f32 v117, v182, v183
	v_cvt_pk_bf16_f32 v108, v184, v185
	v_cvt_pk_bf16_f32 v109, v186, v187
	v_cvt_pk_bf16_f32 v100, v224, v225
	v_cvt_pk_bf16_f32 v101, v226, v227
	s_waitcnt vmcnt(4)
	v_mov_b32_dpp v216, v32 row_shr:1 row_mask:0xf bank_mask:0xf bound_ctrl:1
	v_mov_b32_dpp v217, v33 row_shr:1 row_mask:0xf bank_mask:0xf bound_ctrl:1
	v_mov_b32_dpp v218, v34 row_shr:1 row_mask:0xf bank_mask:0xf bound_ctrl:1
	v_mov_b32_dpp v219, v35 row_shr:1 row_mask:0xf bank_mask:0xf bound_ctrl:1
	v_mov_b32_dpp v220, v56 row_shl:1 row_mask:0xf bank_mask:0xf bound_ctrl:1
	v_mov_b32_dpp v221, v57 row_shl:1 row_mask:0xf bank_mask:0xf bound_ctrl:1
	v_mov_b32_dpp v222, v58 row_shl:1 row_mask:0xf bank_mask:0xf bound_ctrl:1
	v_mov_b32_dpp v223, v59 row_shl:1 row_mask:0xf bank_mask:0xf bound_ctrl:1
	v_pk_mul_f32 v[176:177], v[56:57], v[132:133]
	v_pk_mul_f32 v[178:179], v[58:59], v[134:135]
	v_pk_mul_f32 v[180:181], v[48:49], v[132:133]
	v_pk_mul_f32 v[182:183], v[50:51], v[134:135]
	v_pk_mul_f32 v[184:185], v[40:41], v[132:133]
	v_pk_mul_f32 v[186:187], v[42:43], v[134:135]
	v_pk_mul_f32 v[224:225], v[32:33], v[132:133]
	v_pk_mul_f32 v[226:227], v[34:35], v[134:135]
	v_pk_fma_f32 v[176:177], v[128:129], v[216:217], v[176:177]
	v_pk_fma_f32 v[178:179], v[130:131], v[218:219], v[178:179]
	v_pk_fma_f32 v[180:181], v[128:129], v[56:57], v[180:181]
	v_pk_fma_f32 v[182:183], v[130:131], v[58:59], v[182:183]
	v_pk_fma_f32 v[184:185], v[128:129], v[48:49], v[184:185]
	v_pk_fma_f32 v[186:187], v[130:131], v[50:51], v[186:187]
	v_pk_fma_f32 v[224:225], v[128:129], v[40:41], v[224:225]
	v_pk_fma_f32 v[226:227], v[130:131], v[42:43], v[226:227]
	v_pk_fma_f32 v[176:177], v[136:137], v[48:49], v[176:177]
	v_pk_fma_f32 v[178:179], v[138:139], v[50:51], v[178:179]
	v_pk_fma_f32 v[180:181], v[136:137], v[40:41], v[180:181]
	v_pk_fma_f32 v[182:183], v[138:139], v[42:43], v[182:183]
	v_pk_fma_f32 v[184:185], v[136:137], v[32:33], v[184:185]
	v_pk_fma_f32 v[186:187], v[138:139], v[34:35], v[186:187]
	v_pk_fma_f32 v[224:225], v[136:137], v[220:221], v[224:225]
	v_pk_fma_f32 v[226:227], v[138:139], v[222:223], v[226:227]
	v_pk_add_f32 v[176:177], v[140:141], v[176:177]
	v_pk_add_f32 v[178:179], v[142:143], v[178:179]
	v_pk_add_f32 v[180:181], v[140:141], v[180:181]
	v_pk_add_f32 v[182:183], v[142:143], v[182:183]
	v_pk_add_f32 v[184:185], v[140:141], v[184:185]
	v_pk_add_f32 v[186:187], v[142:143], v[186:187]
	v_pk_add_f32 v[224:225], v[140:141], v[224:225]
	v_pk_add_f32 v[226:227], v[142:143], v[226:227]
	s_waitcnt vmcnt(0)
; __device__ __forceinline__ void st_bf4(bf16_t* p, f32x4 v) { u32x2 w; w.x = pk2(v[0], v[1]); w.y = pk2(v[2], v[3]); *(u32x2*)p = w; }
; __device__ __forceinline__ float sigmoidf_(float x) { return __builtin_amdgcn_rcpf(1.f + __expf(-x)); }
; __device__ __forceinline__ float dpp_ror1(float v) { return __int_as_float(__builtin_amdgcn_update_dpp(0, __float_as_int(v), 0x121, 0xf, 0xf, false)); }
; __device__ __forceinline__ float dpp_rol1(float v) { return __int_as_float(__builtin_amdgcn_update_dpp(0, __float_as_int(v), 0x12F, 0xf, 0xf, false)); }
;     __device__ __forceinline__ void tile(const f32x4 (&acc)[2][2][4][2], const Unit& u, int wr, int wc, int fr, int fq) const {
; #pragma unroll
;         for (int n = 0; n < 2; ++n) {
;             const int cv = 128 * u.pn + 32 * wc + 16 * n + 4 * fq, cg = FF + cv;
;             const f32x4 wv0 = *(const f32x4*)(cw + cv), wv1 = *(const f32x4*)(cw + F2 + cv), wv2 = *(const f32x4*)(cw + 2 * F2 + cv), bv = *(const f32x4*)(cb + cv);
;             const f32x4 wg0 = *(const f32x4*)(cw + cg), wg1 = *(const f32x4*)(cw + F2 + cg), wg2 = *(const f32x4*)(cw + 2 * F2 + cg), bg = *(const f32x4*)(cb + cg);
; #pragma unroll
;             for (int ai = 0; ai < 2; ++ai)
; #pragma unroll
;                 for (int m = 0; m < 4; ++m) {
;                     f32x4 r;
; #pragma unroll
;                     for (int i = 0; i < 4; ++i) {
;                         const float xv = acc[ai][0][m][n][i], xg = acc[ai][1][m][n][i];
;                         const float uv = m > 0 ? acc[ai][0][m > 0 ? m - 1 : 0][n][i] : 0.f, ug = m > 0 ? acc[ai][1][m > 0 ? m - 1 : 0][n][i] : 0.f;
;                         const float dv = m < 3 ? acc[ai][0][m < 3 ? m + 1 : 3][n][i] : 0.f, dg = m < 3 ? acc[ai][1][m < 3 ? m + 1 : 3][n][i] : 0.f;
;                         const float pv = dpp_ror1(fr == 15 ? uv : xv), pg = dpp_ror1(fr == 15 ? ug : xg);
;                         const float nv = dpp_rol1(fr == 0 ? dv : xv), ng = dpp_rol1(fr == 0 ? dg : xg);
;                         const float yv = wv0[i] * pv + wv1[i] * xv + wv2[i] * nv + bv[i];
;                         const float yg = wg0[i] * pg + wg1[i] * xg + wg2[i] * ng + bg[i];
;                         r[i] = yg * sigmoidf_(yg) * yv;
;                     }
;                     st_bf4(ACT + (size_t)(u.pm * BM + ai * HALF + wr * 64 + m * 16 + fr) * FF + cv, r);
;                 }
;         }
	v_mov_b32_dpp v216, v36 row_shr:1 row_mask:0xf bank_mask:0xf bound_ctrl:1
	v_mov_b32_dpp v217, v37 row_shr:1 row_mask:0xf bank_mask:0xf bound_ctrl:1
	v_mov_b32_dpp v218, v38 row_shr:1 row_mask:0xf bank_mask:0xf bound_ctrl:1
	v_mov_b32_dpp v219, v39 row_shr:1 row_mask:0xf bank_mask:0xf bound_ctrl:1
	v_mov_b32_dpp v220, v60 row_shl:1 row_mask:0xf bank_mask:0xf bound_ctrl:1
	v_mov_b32_dpp v221, v61 row_shl:1 row_mask:0xf bank_mask:0xf bound_ctrl:1
	v_mov_b32_dpp v222, v62 row_shl:1 row_mask:0xf bank_mask:0xf bound_ctrl:1
	v_mov_b32_dpp v223, v63 row_shl:1 row_mask:0xf bank_mask:0xf bound_ctrl:1
	v_pk_mul_f32 v[56:57], v[60:61], v[148:149]
	v_pk_mul_f32 v[58:59], v[62:63], v[150:151]
	v_pk_mul_f32 v[48:49], v[52:53], v[148:149]
	v_pk_mul_f32 v[50:51], v[54:55], v[150:151]
	v_pk_mul_f32 v[40:41], v[44:45], v[148:149]
	v_pk_mul_f32 v[42:43], v[46:47], v[150:151]
	v_pk_mul_f32 v[32:33], v[36:37], v[148:149]
	v_pk_mul_f32 v[34:35], v[38:39], v[150:151]
	v_pk_fma_f32 v[56:57], v[144:145], v[216:217], v[56:57]
	v_pk_fma_f32 v[58:59], v[146:147], v[218:219], v[58:59]
	v_pk_fma_f32 v[48:49], v[144:145], v[60:61], v[48:49]
	v_pk_fma_f32 v[50:51], v[146:147], v[62:63], v[50:51]
	v_pk_fma_f32 v[40:41], v[144:145], v[52:53], v[40:41]
	v_pk_fma_f32 v[42:43], v[146:147], v[54:55], v[42:43]
	v_pk_fma_f32 v[32:33], v[144:145], v[44:45], v[32:33]
	v_pk_fma_f32 v[34:35], v[146:147], v[46:47], v[34:35]
	v_pk_fma_f32 v[56:57], v[208:209], v[52:53], v[56:57]
	v_pk_fma_f32 v[58:59], v[210:211], v[54:55], v[58:59]
	v_pk_fma_f32 v[48:49], v[208:209], v[44:45], v[48:49]
	v_pk_fma_f32 v[50:51], v[210:211], v[46:47], v[50:51]
	v_pk_fma_f32 v[40:41], v[208:209], v[36:37], v[40:41]
	v_pk_fma_f32 v[42:43], v[210:211], v[38:39], v[42:43]
	v_pk_fma_f32 v[32:33], v[208:209], v[220:221], v[32:33]
	v_pk_fma_f32 v[34:35], v[210:211], v[222:223], v[34:35]
	v_pk_add_f32 v[56:57], v[212:213], v[56:57]
	v_pk_add_f32 v[58:59], v[214:215], v[58:59]
	v_pk_add_f32 v[48:49], v[212:213], v[48:49]
	v_pk_add_f32 v[50:51], v[214:215], v[50:51]
	v_pk_add_f32 v[40:41], v[212:213], v[40:41]
	v_pk_add_f32 v[42:43], v[214:215], v[42:43]
	v_pk_add_f32 v[32:33], v[212:213], v[32:33]
	v_pk_add_f32 v[34:35], v[214:215], v[34:35]
	v_mul_f32_e32 v60, 0xbfb8aa3b, v176
	v_mul_f32_e32 v61, 0xbfb8aa3b, v177
	v_mul_f32_e32 v62, 0xbfb8aa3b, v178
	v_mul_f32_e32 v63, 0xbfb8aa3b, v179
	v_mul_f32_e32 v52, 0xbfb8aa3b, v180
	v_mul_f32_e32 v53, 0xbfb8aa3b, v181
	v_mul_f32_e32 v54, 0xbfb8aa3b, v182
	v_mul_f32_e32 v55, 0xbfb8aa3b, v183
	v_mul_f32_e32 v44, 0xbfb8aa3b, v184
	v_mul_f32_e32 v45, 0xbfb8aa3b, v185
	v_mul_f32_e32 v46, 0xbfb8aa3b, v186
	v_mul_f32_e32 v47, 0xbfb8aa3b, v187
	v_mul_f32_e32 v36, 0xbfb8aa3b, v224
	v_mul_f32_e32 v37, 0xbfb8aa3b, v225
	v_mul_f32_e32 v38, 0xbfb8aa3b, v226
	v_mul_f32_e32 v39, 0xbfb8aa3b, v227
	v_exp_f32_e32 v60, v60
	v_exp_f32_e32 v61, v61
	v_exp_f32_e32 v62, v62
	v_exp_f32_e32 v63, v63
	v_exp_f32_e32 v52, v52
	v_exp_f32_e32 v53, v53
	v_exp_f32_e32 v54, v54
	v_exp_f32_e32 v55, v55
	v_exp_f32_e32 v44, v44
	v_exp_f32_e32 v45, v45
	v_exp_f32_e32 v46, v46
	v_exp_f32_e32 v47, v47
	v_exp_f32_e32 v36, v36
	v_exp_f32_e32 v37, v37
	v_exp_f32_e32 v38, v38
	v_exp_f32_e32 v39, v39
	v_add_f32_e32 v60, 1.0, v60
	v_add_f32_e32 v61, 1.0, v61
	v_add_f32_e32 v62, 1.0, v62
	v_add_f32_e32 v63, 1.0, v63
	v_add_f32_e32 v52, 1.0, v52
	v_add_f32_e32 v53, 1.0, v53
	v_add_f32_e32 v54, 1.0, v54
	v_add_f32_e32 v55, 1.0, v55
	v_add_f32_e32 v44, 1.0, v44
	v_add_f32_e32 v45, 1.0, v45
	v_add_f32_e32 v46, 1.0, v46
	v_add_f32_e32 v47, 1.0, v47
	v_add_f32_e32 v36, 1.0, v36
	v_add_f32_e32 v37, 1.0, v37
	v_add_f32_e32 v38, 1.0, v38
	v_add_f32_e32 v39, 1.0, v39
	v_rcp_f32_e32 v60, v60
	v_rcp_f32_e32 v61, v61
	v_rcp_f32_e32 v62, v62
	v_rcp_f32_e32 v63, v63
	v_rcp_f32_e32 v52, v52
	v_rcp_f32_e32 v53, v53
	v_rcp_f32_e32 v54, v54
	v_rcp_f32_e32 v55, v55
	v_rcp_f32_e32 v44, v44
	v_rcp_f32_e32 v45, v45
	v_rcp_f32_e32 v46, v46
	v_rcp_f32_e32 v47, v47
	v_rcp_f32_e32 v36, v36
	v_rcp_f32_e32 v37, v37
	v_rcp_f32_e32 v38, v38
	v_rcp_f32_e32 v39, v39
	v_pk_mul_f32 v[176:177], v[176:177], v[60:61]
	v_pk_mul_f32 v[178:179], v[178:179], v[62:63]
	v_pk_mul_f32 v[180:181], v[180:181], v[52:53]
	v_pk_mul_f32 v[182:183], v[182:183], v[54:55]
	v_pk_mul_f32 v[184:185], v[184:185], v[44:45]
	v_pk_mul_f32 v[186:187], v[186:187], v[46:47]
	v_pk_mul_f32 v[224:225], v[224:225], v[36:37]
	v_pk_mul_f32 v[226:227], v[226:227], v[38:39]
	v_pk_mul_f32 v[176:177], v[56:57], v[176:177]
	v_pk_mul_f32 v[178:179], v[58:59], v[178:179]
	v_pk_mul_f32 v[180:181], v[48:49], v[180:181]
	v_pk_mul_f32 v[182:183], v[50:51], v[182:183]
	v_pk_mul_f32 v[184:185], v[40:41], v[184:185]
	v_pk_mul_f32 v[186:187], v[42:43], v[186:187]
	v_pk_mul_f32 v[224:225], v[32:33], v[224:225]
	v_pk_mul_f32 v[226:227], v[34:35], v[226:227]
	v_cvt_pk_bf16_f32 v158, v176, v177
	v_cvt_pk_bf16_f32 v159, v178, v179
	v_cvt_pk_bf16_f32 v118, v180, v181
	v_cvt_pk_bf16_f32 v119, v182, v183
	v_cvt_pk_bf16_f32 v110, v184, v185
	v_cvt_pk_bf16_f32 v111, v186, v187
	v_cvt_pk_bf16_f32 v102, v224, v225
	v_cvt_pk_bf16_f32 v103, v226, v227
	s_nop 1
	v_permlane16_swap_b32_e32 v156, v158
	v_permlane16_swap_b32_e32 v157, v159
	v_permlane16_swap_b32_e32 v116, v118
	v_permlane16_swap_b32_e32 v117, v119
	v_permlane16_swap_b32_e32 v108, v110
	v_permlane16_swap_b32_e32 v109, v111
	v_permlane16_swap_b32_e32 v100, v102
	v_permlane16_swap_b32_e32 v101, v103
	global_store_dwordx4 v173, v[156:159], s[0:1] sc1
	v_add_u32_e32 v175, 0x2c00, v173
	global_store_dwordx4 v175, v[116:119], s[0:1] sc1
	v_add_u32_e32 v175, 0x5800, v173
	global_store_dwordx4 v175, v[108:111], s[0:1] sc1
	v_add_u32_e32 v175, 0x8400, v173
; __device__ __forceinline__ void st_bf4(bf16_t* p, f32x4 v) { u32x2 w; w.x = pk2(v[0], v[1]); w.y = pk2(v[2], v[3]); *(u32x2*)p = w; }
; __device__ __forceinline__ float sigmoidf_(float x) { return __builtin_amdgcn_rcpf(1.f + __expf(-x)); }
; __device__ __forceinline__ float dpp_ror1(float v) { return __int_as_float(__builtin_amdgcn_update_dpp(0, __float_as_int(v), 0x121, 0xf, 0xf, false)); }
; __device__ __forceinline__ float dpp_rol1(float v) { return __int_as_float(__builtin_amdgcn_update_dpp(0, __float_as_int(v), 0x12F, 0xf, 0xf, false)); }
;     __device__ __forceinline__ void tile(const f32x4 (&acc)[2][2][4][2], const Unit& u, int wr, int wc, int fr, int fq) const {
; #pragma unroll
;         for (int n = 0; n < 2; ++n) {
;             const int cv = 128 * u.pn + 32 * wc + 16 * n + 4 * fq, cg = FF + cv;
;             const f32x4 wv0 = *(const f32x4*)(cw + cv), wv1 = *(const f32x4*)(cw + F2 + cv), wv2 = *(const f32x4*)(cw + 2 * F2 + cv), bv = *(const f32x4*)(cb + cv);
;             const f32x4 wg0 = *(const f32x4*)(cw + cg), wg1 = *(const f32x4*)(cw + F2 + cg), wg2 = *(const f32x4*)(cw + 2 * F2 + cg), bg = *(const f32x4*)(cb + cg);
; #pragma unroll
;             for (int ai = 0; ai < 2; ++ai)
; #pragma unroll
;                 for (int m = 0; m < 4; ++m) {
;                     f32x4 r;
; #pragma unroll
;                     for (int i = 0; i < 4; ++i) {
;                         const float xv = acc[ai][0][m][n][i], xg = acc[ai][1][m][n][i];
;                         const float uv = m > 0 ? acc[ai][0][m > 0 ? m - 1 : 0][n][i] : 0.f, ug = m > 0 ? acc[ai][1][m > 0 ? m - 1 : 0][n][i] : 0.f;
;                         const float dv = m < 3 ? acc[ai][0][m < 3 ? m + 1 : 3][n][i] : 0.f, dg = m < 3 ? acc[ai][1][m < 3 ? m + 1 : 3][n][i] : 0.f;
;                         const float pv = dpp_ror1(fr == 15 ? uv : xv), pg = dpp_ror1(fr == 15 ? ug : xg);
;                         const float nv = dpp_rol1(fr == 0 ? dv : xv), ng = dpp_rol1(fr == 0 ? dg : xg);
;                         const float yv = wv0[i] * pv + wv1[i] * xv + wv2[i] * nv + bv[i];
;                         const float yg = wg0[i] * pg + wg1[i] * xg + wg2[i] * ng + bg[i];
;                         r[i] = yg * sigmoidf_(yg) * yv;
;                     }
;                     st_bf4(ACT + (size_t)(u.pm * BM + ai * HALF + wr * 64 + m * 16 + fr) * FF + cv, r);
;                 }
;         }
	global_store_dwordx4 v175, v[100:103], s[0:1] sc1
	v_mov_b32_dpp v216, v64 row_shr:1 row_mask:0xf bank_mask:0xf bound_ctrl:1
	v_mov_b32_dpp v217, v65 row_shr:1 row_mask:0xf bank_mask:0xf bound_ctrl:1
	v_mov_b32_dpp v218, v66 row_shr:1 row_mask:0xf bank_mask:0xf bound_ctrl:1
	v_mov_b32_dpp v219, v67 row_shr:1 row_mask:0xf bank_mask:0xf bound_ctrl:1
	v_mov_b32_dpp v220, v88 row_shl:1 row_mask:0xf bank_mask:0xf bound_ctrl:1
	v_mov_b32_dpp v221, v89 row_shl:1 row_mask:0xf bank_mask:0xf bound_ctrl:1
	v_mov_b32_dpp v222, v90 row_shl:1 row_mask:0xf bank_mask:0xf bound_ctrl:1
	v_mov_b32_dpp v223, v91 row_shl:1 row_mask:0xf bank_mask:0xf bound_ctrl:1
	v_pk_mul_f32 v[176:177], v[88:89], v[234:235]
	v_pk_mul_f32 v[178:179], v[90:91], v[236:237]
	v_pk_mul_f32 v[180:181], v[80:81], v[234:235]
	v_pk_mul_f32 v[182:183], v[82:83], v[236:237]
	v_pk_mul_f32 v[184:185], v[72:73], v[234:235]
	v_pk_mul_f32 v[186:187], v[74:75], v[236:237]
	v_pk_mul_f32 v[224:225], v[64:65], v[234:235]
	v_pk_mul_f32 v[226:227], v[66:67], v[236:237]
	v_pk_fma_f32 v[176:177], v[230:231], v[216:217], v[176:177]
	v_pk_fma_f32 v[178:179], v[232:233], v[218:219], v[178:179]
	v_pk_fma_f32 v[180:181], v[230:231], v[88:89], v[180:181]
	v_pk_fma_f32 v[182:183], v[232:233], v[90:91], v[182:183]
	v_pk_fma_f32 v[184:185], v[230:231], v[80:81], v[184:185]
	v_pk_fma_f32 v[186:187], v[232:233], v[82:83], v[186:187]
	v_pk_fma_f32 v[224:225], v[230:231], v[72:73], v[224:225]
	v_pk_fma_f32 v[226:227], v[232:233], v[74:75], v[226:227]
	v_pk_fma_f32 v[176:177], v[238:239], v[80:81], v[176:177]
	v_pk_fma_f32 v[178:179], v[240:241], v[82:83], v[178:179]
	v_pk_fma_f32 v[180:181], v[238:239], v[72:73], v[180:181]
	v_pk_fma_f32 v[182:183], v[240:241], v[74:75], v[182:183]
	v_pk_fma_f32 v[184:185], v[238:239], v[64:65], v[184:185]
	v_pk_fma_f32 v[186:187], v[240:241], v[66:67], v[186:187]
	v_pk_fma_f32 v[224:225], v[238:239], v[220:221], v[224:225]
	v_pk_fma_f32 v[226:227], v[240:241], v[222:223], v[226:227]
	v_pk_add_f32 v[176:177], v[242:243], v[176:177]
	v_pk_add_f32 v[178:179], v[244:245], v[178:179]
	v_pk_add_f32 v[180:181], v[242:243], v[180:181]
	v_pk_add_f32 v[182:183], v[244:245], v[182:183]
	v_pk_add_f32 v[184:185], v[242:243], v[184:185]
	v_pk_add_f32 v[186:187], v[244:245], v[186:187]
	v_pk_add_f32 v[224:225], v[242:243], v[224:225]
	v_pk_add_f32 v[226:227], v[244:245], v[226:227]
	v_mov_b32_dpp v216, v68 row_shr:1 row_mask:0xf bank_mask:0xf bound_ctrl:1
	v_mov_b32_dpp v217, v69 row_shr:1 row_mask:0xf bank_mask:0xf bound_ctrl:1
	v_mov_b32_dpp v218, v70 row_shr:1 row_mask:0xf bank_mask:0xf bound_ctrl:1
	v_mov_b32_dpp v219, v71 row_shr:1 row_mask:0xf bank_mask:0xf bound_ctrl:1
	v_mov_b32_dpp v220, v92 row_shl:1 row_mask:0xf bank_mask:0xf bound_ctrl:1
	v_mov_b32_dpp v221, v93 row_shl:1 row_mask:0xf bank_mask:0xf bound_ctrl:1
	v_mov_b32_dpp v222, v94 row_shl:1 row_mask:0xf bank_mask:0xf bound_ctrl:1
	v_mov_b32_dpp v223, v95 row_shl:1 row_mask:0xf bank_mask:0xf bound_ctrl:1
	v_pk_mul_f32 v[88:89], v[92:93], v[250:251]
	v_pk_mul_f32 v[90:91], v[94:95], v[252:253]
	v_pk_mul_f32 v[80:81], v[84:85], v[250:251]
	v_pk_mul_f32 v[82:83], v[86:87], v[252:253]
	v_pk_mul_f32 v[72:73], v[76:77], v[250:251]
	v_pk_mul_f32 v[74:75], v[78:79], v[252:253]
	v_pk_mul_f32 v[64:65], v[68:69], v[250:251]
	v_pk_mul_f32 v[66:67], v[70:71], v[252:253]
	v_pk_fma_f32 v[88:89], v[246:247], v[216:217], v[88:89]
	v_pk_fma_f32 v[90:91], v[248:249], v[218:219], v[90:91]
	v_pk_fma_f32 v[80:81], v[246:247], v[92:93], v[80:81]
	v_pk_fma_f32 v[82:83], v[248:249], v[94:95], v[82:83]
	v_pk_fma_f32 v[72:73], v[246:247], v[84:85], v[72:73]
	v_pk_fma_f32 v[74:75], v[248:249], v[86:87], v[74:75]
	v_pk_fma_f32 v[64:65], v[246:247], v[76:77], v[64:65]
	v_pk_fma_f32 v[66:67], v[248:249], v[78:79], v[66:67]
	v_pk_fma_f32 v[88:89], v[120:121], v[84:85], v[88:89]
	v_pk_fma_f32 v[90:91], v[122:123], v[86:87], v[90:91]
	v_pk_fma_f32 v[80:81], v[120:121], v[76:77], v[80:81]
	v_pk_fma_f32 v[82:83], v[122:123], v[78:79], v[82:83]
	v_pk_fma_f32 v[72:73], v[120:121], v[68:69], v[72:73]
	v_pk_fma_f32 v[74:75], v[122:123], v[70:71], v[74:75]
	v_pk_fma_f32 v[64:65], v[120:121], v[220:221], v[64:65]
	v_pk_fma_f32 v[66:67], v[122:123], v[222:223], v[66:67]
	v_pk_add_f32 v[88:89], v[124:125], v[88:89]
	v_pk_add_f32 v[90:91], v[126:127], v[90:91]
	v_pk_add_f32 v[80:81], v[124:125], v[80:81]
	v_pk_add_f32 v[82:83], v[126:127], v[82:83]
	v_pk_add_f32 v[72:73], v[124:125], v[72:73]
	v_pk_add_f32 v[74:75], v[126:127], v[74:75]
	v_pk_add_f32 v[64:65], v[124:125], v[64:65]
	v_pk_add_f32 v[66:67], v[126:127], v[66:67]
	v_mul_f32_e32 v92, 0xbfb8aa3b, v176
	v_mul_f32_e32 v93, 0xbfb8aa3b, v177
	v_mul_f32_e32 v94, 0xbfb8aa3b, v178
	v_mul_f32_e32 v95, 0xbfb8aa3b, v179
	v_mul_f32_e32 v84, 0xbfb8aa3b, v180
	v_mul_f32_e32 v85, 0xbfb8aa3b, v181
	v_mul_f32_e32 v86, 0xbfb8aa3b, v182
	v_mul_f32_e32 v87, 0xbfb8aa3b, v183
	v_mul_f32_e32 v76, 0xbfb8aa3b, v184
	v_mul_f32_e32 v77, 0xbfb8aa3b, v185
	v_mul_f32_e32 v78, 0xbfb8aa3b, v186
	v_mul_f32_e32 v79, 0xbfb8aa3b, v187
	v_mul_f32_e32 v68, 0xbfb8aa3b, v224
	v_mul_f32_e32 v69, 0xbfb8aa3b, v225
	v_mul_f32_e32 v70, 0xbfb8aa3b, v226
	v_mul_f32_e32 v71, 0xbfb8aa3b, v227
	v_exp_f32_e32 v92, v92
	v_exp_f32_e32 v93, v93
	v_exp_f32_e32 v94, v94
	v_exp_f32_e32 v95, v95
	v_exp_f32_e32 v84, v84
	v_exp_f32_e32 v85, v85
	v_exp_f32_e32 v86, v86
	v_exp_f32_e32 v87, v87
	v_exp_f32_e32 v76, v76
	v_exp_f32_e32 v77, v77
	v_exp_f32_e32 v78, v78
	v_exp_f32_e32 v79, v79
	v_exp_f32_e32 v68, v68
	v_exp_f32_e32 v69, v69
	v_exp_f32_e32 v70, v70
	v_exp_f32_e32 v71, v71
	v_add_f32_e32 v92, 1.0, v92
	v_add_f32_e32 v93, 1.0, v93
	v_add_f32_e32 v94, 1.0, v94
; __device__ __forceinline__ void st_bf4(bf16_t* p, f32x4 v) { u32x2 w; w.x = pk2(v[0], v[1]); w.y = pk2(v[2], v[3]); *(u32x2*)p = w; }
; __device__ __forceinline__ float sigmoidf_(float x) { return __builtin_amdgcn_rcpf(1.f + __expf(-x)); }
; __device__ __forceinline__ float dpp_ror1(float v) { return __int_as_float(__builtin_amdgcn_update_dpp(0, __float_as_int(v), 0x121, 0xf, 0xf, false)); }
; __device__ __forceinline__ float dpp_rol1(float v) { return __int_as_float(__builtin_amdgcn_update_dpp(0, __float_as_int(v), 0x12F, 0xf, 0xf, false)); }
;     __device__ __forceinline__ void tile(const f32x4 (&acc)[2][2][4][2], const Unit& u, int wr, int wc, int fr, int fq) const {
; #pragma unroll
;         for (int n = 0; n < 2; ++n) {
;             const int cv = 128 * u.pn + 32 * wc + 16 * n + 4 * fq, cg = FF + cv;
;             const f32x4 wv0 = *(const f32x4*)(cw + cv), wv1 = *(const f32x4*)(cw + F2 + cv), wv2 = *(const f32x4*)(cw + 2 * F2 + cv), bv = *(const f32x4*)(cb + cv);
;             const f32x4 wg0 = *(const f32x4*)(cw + cg), wg1 = *(const f32x4*)(cw + F2 + cg), wg2 = *(const f32x4*)(cw + 2 * F2 + cg), bg = *(const f32x4*)(cb + cg);
; #pragma unroll
;             for (int ai = 0; ai < 2; ++ai)
; #pragma unroll
;                 for (int m = 0; m < 4; ++m) {
;                     f32x4 r;
; #pragma unroll
;                     for (int i = 0; i < 4; ++i) {
;                         const float xv = acc[ai][0][m][n][i], xg = acc[ai][1][m][n][i];
;                         const float uv = m > 0 ? acc[ai][0][m > 0 ? m - 1 : 0][n][i] : 0.f, ug = m > 0 ? acc[ai][1][m > 0 ? m - 1 : 0][n][i] : 0.f;
;                         const float dv = m < 3 ? acc[ai][0][m < 3 ? m + 1 : 3][n][i] : 0.f, dg = m < 3 ? acc[ai][1][m < 3 ? m + 1 : 3][n][i] : 0.f;
;                         const float pv = dpp_ror1(fr == 15 ? uv : xv), pg = dpp_ror1(fr == 15 ? ug : xg);
;                         const float nv = dpp_rol1(fr == 0 ? dv : xv), ng = dpp_rol1(fr == 0 ? dg : xg);
;                         const float yv = wv0[i] * pv + wv1[i] * xv + wv2[i] * nv + bv[i];
;                         const float yg = wg0[i] * pg + wg1[i] * xg + wg2[i] * ng + bg[i];
;                         r[i] = yg * sigmoidf_(yg) * yv;
;                     }
;                     st_bf4(ACT + (size_t)(u.pm * BM + ai * HALF + wr * 64 + m * 16 + fr) * FF + cv, r);
;                 }
;         }
	v_add_f32_e32 v95, 1.0, v95
	v_add_f32_e32 v84, 1.0, v84
	v_add_f32_e32 v85, 1.0, v85
	v_add_f32_e32 v86, 1.0, v86
	v_add_f32_e32 v87, 1.0, v87
	v_add_f32_e32 v76, 1.0, v76
	v_add_f32_e32 v77, 1.0, v77
	v_add_f32_e32 v78, 1.0, v78
	v_add_f32_e32 v79, 1.0, v79
	v_add_f32_e32 v68, 1.0, v68
	v_add_f32_e32 v69, 1.0, v69
	v_add_f32_e32 v70, 1.0, v70
	v_add_f32_e32 v71, 1.0, v71
	v_rcp_f32_e32 v92, v92
	v_rcp_f32_e32 v93, v93
	v_rcp_f32_e32 v94, v94
	v_rcp_f32_e32 v95, v95
	v_rcp_f32_e32 v84, v84
	v_rcp_f32_e32 v85, v85
	v_rcp_f32_e32 v86, v86
	v_rcp_f32_e32 v87, v87
	v_rcp_f32_e32 v76, v76
	v_rcp_f32_e32 v77, v77
	v_rcp_f32_e32 v78, v78
	v_rcp_f32_e32 v79, v79
	v_rcp_f32_e32 v68, v68
	v_rcp_f32_e32 v69, v69
	v_rcp_f32_e32 v70, v70
	v_rcp_f32_e32 v71, v71
	v_pk_mul_f32 v[176:177], v[176:177], v[92:93]
	v_pk_mul_f32 v[178:179], v[178:179], v[94:95]
	v_pk_mul_f32 v[180:181], v[180:181], v[84:85]
	v_pk_mul_f32 v[182:183], v[182:183], v[86:87]
	v_pk_mul_f32 v[184:185], v[184:185], v[76:77]
	v_pk_mul_f32 v[186:187], v[186:187], v[78:79]
	v_pk_mul_f32 v[224:225], v[224:225], v[68:69]
	v_pk_mul_f32 v[226:227], v[226:227], v[70:71]
	v_pk_mul_f32 v[176:177], v[88:89], v[176:177]
	v_pk_mul_f32 v[178:179], v[90:91], v[178:179]
	v_pk_mul_f32 v[180:181], v[80:81], v[180:181]
	v_pk_mul_f32 v[182:183], v[82:83], v[182:183]
	v_pk_mul_f32 v[184:185], v[72:73], v[184:185]
	v_pk_mul_f32 v[186:187], v[74:75], v[186:187]
	v_pk_mul_f32 v[224:225], v[64:65], v[224:225]
	v_pk_mul_f32 v[226:227], v[66:67], v[226:227]
	v_cvt_pk_bf16_f32 v92, v176, v177
	v_cvt_pk_bf16_f32 v93, v178, v179
	v_cvt_pk_bf16_f32 v84, v180, v181
	v_cvt_pk_bf16_f32 v85, v182, v183
	v_cvt_pk_bf16_f32 v76, v184, v185
	v_cvt_pk_bf16_f32 v77, v186, v187
	v_cvt_pk_bf16_f32 v68, v224, v225
	v_cvt_pk_bf16_f32 v69, v226, v227
	v_mov_b32_dpp v216, v0 row_shr:1 row_mask:0xf bank_mask:0xf bound_ctrl:1
	v_mov_b32_dpp v217, v1 row_shr:1 row_mask:0xf bank_mask:0xf bound_ctrl:1
	v_mov_b32_dpp v218, v2 row_shr:1 row_mask:0xf bank_mask:0xf bound_ctrl:1
	v_mov_b32_dpp v219, v3 row_shr:1 row_mask:0xf bank_mask:0xf bound_ctrl:1
	v_mov_b32_dpp v220, v24 row_shl:1 row_mask:0xf bank_mask:0xf bound_ctrl:1
	v_mov_b32_dpp v221, v25 row_shl:1 row_mask:0xf bank_mask:0xf bound_ctrl:1
	v_mov_b32_dpp v222, v26 row_shl:1 row_mask:0xf bank_mask:0xf bound_ctrl:1
	v_mov_b32_dpp v223, v27 row_shl:1 row_mask:0xf bank_mask:0xf bound_ctrl:1
	v_pk_mul_f32 v[176:177], v[24:25], v[132:133]
	v_pk_mul_f32 v[178:179], v[26:27], v[134:135]
	v_pk_mul_f32 v[180:181], v[16:17], v[132:133]
	v_pk_mul_f32 v[182:183], v[18:19], v[134:135]
	v_pk_mul_f32 v[184:185], v[8:9], v[132:133]
	v_pk_mul_f32 v[186:187], v[10:11], v[134:135]
	v_pk_mul_f32 v[224:225], v[0:1], v[132:133]
	v_pk_mul_f32 v[226:227], v[2:3], v[134:135]
	v_pk_fma_f32 v[176:177], v[128:129], v[216:217], v[176:177]
	v_pk_fma_f32 v[178:179], v[130:131], v[218:219], v[178:179]
	v_pk_fma_f32 v[180:181], v[128:129], v[24:25], v[180:181]
	v_pk_fma_f32 v[182:183], v[130:131], v[26:27], v[182:183]
	v_pk_fma_f32 v[184:185], v[128:129], v[16:17], v[184:185]
	v_pk_fma_f32 v[186:187], v[130:131], v[18:19], v[186:187]
	v_pk_fma_f32 v[224:225], v[128:129], v[8:9], v[224:225]
	v_pk_fma_f32 v[226:227], v[130:131], v[10:11], v[226:227]
	v_pk_fma_f32 v[176:177], v[136:137], v[16:17], v[176:177]
	v_pk_fma_f32 v[178:179], v[138:139], v[18:19], v[178:179]
	v_pk_fma_f32 v[180:181], v[136:137], v[8:9], v[180:181]
	v_pk_fma_f32 v[182:183], v[138:139], v[10:11], v[182:183]
	v_pk_fma_f32 v[184:185], v[136:137], v[0:1], v[184:185]
	v_pk_fma_f32 v[186:187], v[138:139], v[2:3], v[186:187]
	v_pk_fma_f32 v[224:225], v[136:137], v[220:221], v[224:225]
	v_pk_fma_f32 v[226:227], v[138:139], v[222:223], v[226:227]
	v_pk_add_f32 v[176:177], v[140:141], v[176:177]
	v_pk_add_f32 v[178:179], v[142:143], v[178:179]
	v_pk_add_f32 v[180:181], v[140:141], v[180:181]
	v_pk_add_f32 v[182:183], v[142:143], v[182:183]
	v_pk_add_f32 v[184:185], v[140:141], v[184:185]
	v_pk_add_f32 v[186:187], v[142:143], v[186:187]
	v_pk_add_f32 v[224:225], v[140:141], v[224:225]
	v_pk_add_f32 v[226:227], v[142:143], v[226:227]
	v_mov_b32_dpp v216, v4 row_shr:1 row_mask:0xf bank_mask:0xf bound_ctrl:1
	v_mov_b32_dpp v217, v5 row_shr:1 row_mask:0xf bank_mask:0xf bound_ctrl:1
	v_mov_b32_dpp v218, v6 row_shr:1 row_mask:0xf bank_mask:0xf bound_ctrl:1
	v_mov_b32_dpp v219, v7 row_shr:1 row_mask:0xf bank_mask:0xf bound_ctrl:1
	v_mov_b32_dpp v220, v28 row_shl:1 row_mask:0xf bank_mask:0xf bound_ctrl:1
	v_mov_b32_dpp v221, v29 row_shl:1 row_mask:0xf bank_mask:0xf bound_ctrl:1
	v_mov_b32_dpp v222, v30 row_shl:1 row_mask:0xf bank_mask:0xf bound_ctrl:1
	v_mov_b32_dpp v223, v31 row_shl:1 row_mask:0xf bank_mask:0xf bound_ctrl:1
	v_pk_mul_f32 v[24:25], v[28:29], v[148:149]
	v_pk_mul_f32 v[26:27], v[30:31], v[150:151]
	v_pk_mul_f32 v[16:17], v[20:21], v[148:149]
	v_pk_mul_f32 v[18:19], v[22:23], v[150:151]
	v_pk_mul_f32 v[8:9], v[12:13], v[148:149]
	v_pk_mul_f32 v[10:11], v[14:15], v[150:151]
	v_pk_mul_f32 v[0:1], v[4:5], v[148:149]
	v_pk_mul_f32 v[2:3], v[6:7], v[150:151]
	v_pk_fma_f32 v[24:25], v[144:145], v[216:217], v[24:25]
; __device__ __forceinline__ void st_bf4(bf16_t* p, f32x4 v) { u32x2 w; w.x = pk2(v[0], v[1]); w.y = pk2(v[2], v[3]); *(u32x2*)p = w; }
; __device__ __forceinline__ float sigmoidf_(float x) { return __builtin_amdgcn_rcpf(1.f + __expf(-x)); }
; __device__ __forceinline__ float dpp_ror1(float v) { return __int_as_float(__builtin_amdgcn_update_dpp(0, __float_as_int(v), 0x121, 0xf, 0xf, false)); }
; __device__ __forceinline__ float dpp_rol1(float v) { return __int_as_float(__builtin_amdgcn_update_dpp(0, __float_as_int(v), 0x12F, 0xf, 0xf, false)); }
;     __device__ __forceinline__ void tile(const f32x4 (&acc)[2][2][4][2], const Unit& u, int wr, int wc, int fr, int fq) const {
;     ...
;             const f32x4 wv0 = *(const f32x4*)(cw + cv), wv1 = *(const f32x4*)(cw + F2 + cv), wv2 = *(const f32x4*)(cw + 2 * F2 + cv), bv = *(const f32x4*)(cb + cv);
;             const f32x4 wg0 = *(const f32x4*)(cw + cg), wg1 = *(const f32x4*)(cw + F2 + cg), wg2 = *(const f32x4*)(cw + 2 * F2 + cg), bg = *(const f32x4*)(cb + cg);
; #pragma unroll
;             for (int ai = 0; ai < 2; ++ai)
; #pragma unroll
;                 for (int m = 0; m < 4; ++m) {
;                     f32x4 r;
; #pragma unroll
;                     for (int i = 0; i < 4; ++i) {
;                         const float xv = acc[ai][0][m][n][i], xg = acc[ai][1][m][n][i];
;                         const float uv = m > 0 ? acc[ai][0][m > 0 ? m - 1 : 0][n][i] : 0.f, ug = m > 0 ? acc[ai][1][m > 0 ? m - 1 : 0][n][i] : 0.f;
;                         const float dv = m < 3 ? acc[ai][0][m < 3 ? m + 1 : 3][n][i] : 0.f, dg = m < 3 ? acc[ai][1][m < 3 ? m + 1 : 3][n][i] : 0.f;
;                         const float pv = dpp_ror1(fr == 15 ? uv : xv), pg = dpp_ror1(fr == 15 ? ug : xg);
;                         const float nv = dpp_rol1(fr == 0 ? dv : xv), ng = dpp_rol1(fr == 0 ? dg : xg);
;                         const float yv = wv0[i] * pv + wv1[i] * xv + wv2[i] * nv + bv[i];
;                         const float yg = wg0[i] * pg + wg1[i] * xg + wg2[i] * ng + bg[i];
;                         r[i] = yg * sigmoidf_(yg) * yv;
;                     }
;                     st_bf4(ACT + (size_t)(u.pm * BM + ai * HALF + wr * 64 + m * 16 + fr) * FF + cv, r);
	v_pk_fma_f32 v[26:27], v[146:147], v[218:219], v[26:27]
	v_pk_fma_f32 v[16:17], v[144:145], v[28:29], v[16:17]
	v_pk_fma_f32 v[18:19], v[146:147], v[30:31], v[18:19]
	v_pk_fma_f32 v[8:9], v[144:145], v[20:21], v[8:9]
	v_pk_fma_f32 v[10:11], v[146:147], v[22:23], v[10:11]
	v_pk_fma_f32 v[0:1], v[144:145], v[12:13], v[0:1]
	v_pk_fma_f32 v[2:3], v[146:147], v[14:15], v[2:3]
	v_pk_fma_f32 v[24:25], v[208:209], v[20:21], v[24:25]
	v_pk_fma_f32 v[26:27], v[210:211], v[22:23], v[26:27]
	v_pk_fma_f32 v[16:17], v[208:209], v[12:13], v[16:17]
	v_pk_fma_f32 v[18:19], v[210:211], v[14:15], v[18:19]
	v_pk_fma_f32 v[8:9], v[208:209], v[4:5], v[8:9]
	v_pk_fma_f32 v[10:11], v[210:211], v[6:7], v[10:11]
	v_pk_fma_f32 v[0:1], v[208:209], v[220:221], v[0:1]
	v_pk_fma_f32 v[2:3], v[210:211], v[222:223], v[2:3]
	v_pk_add_f32 v[24:25], v[212:213], v[24:25]
	v_pk_add_f32 v[26:27], v[214:215], v[26:27]
	v_pk_add_f32 v[16:17], v[212:213], v[16:17]
	v_pk_add_f32 v[18:19], v[214:215], v[18:19]
	v_pk_add_f32 v[8:9], v[212:213], v[8:9]
	v_pk_add_f32 v[10:11], v[214:215], v[10:11]
	v_pk_add_f32 v[0:1], v[212:213], v[0:1]
	v_pk_add_f32 v[2:3], v[214:215], v[2:3]
	v_mul_f32_e32 v28, 0xbfb8aa3b, v176
	v_mul_f32_e32 v29, 0xbfb8aa3b, v177
	v_mul_f32_e32 v30, 0xbfb8aa3b, v178
	v_mul_f32_e32 v31, 0xbfb8aa3b, v179
	v_mul_f32_e32 v20, 0xbfb8aa3b, v180
	v_mul_f32_e32 v21, 0xbfb8aa3b, v181
	v_mul_f32_e32 v22, 0xbfb8aa3b, v182
	v_mul_f32_e32 v23, 0xbfb8aa3b, v183
	v_mul_f32_e32 v12, 0xbfb8aa3b, v184
	v_mul_f32_e32 v13, 0xbfb8aa3b, v185
	v_mul_f32_e32 v14, 0xbfb8aa3b, v186
	v_mul_f32_e32 v15, 0xbfb8aa3b, v187
	v_mul_f32_e32 v4, 0xbfb8aa3b, v224
	v_mul_f32_e32 v5, 0xbfb8aa3b, v225
	v_mul_f32_e32 v6, 0xbfb8aa3b, v226
	v_mul_f32_e32 v7, 0xbfb8aa3b, v227
	v_exp_f32_e32 v28, v28
	v_exp_f32_e32 v29, v29
	v_exp_f32_e32 v30, v30
	v_exp_f32_e32 v31, v31
	v_exp_f32_e32 v20, v20
	v_exp_f32_e32 v21, v21
	v_exp_f32_e32 v22, v22
	v_exp_f32_e32 v23, v23
	v_exp_f32_e32 v12, v12
	v_exp_f32_e32 v13, v13
	v_exp_f32_e32 v14, v14
	v_exp_f32_e32 v15, v15
	v_exp_f32_e32 v4, v4
	v_exp_f32_e32 v5, v5
	v_exp_f32_e32 v6, v6
	v_exp_f32_e32 v7, v7
	v_add_f32_e32 v28, 1.0, v28
	v_add_f32_e32 v29, 1.0, v29
	v_add_f32_e32 v30, 1.0, v30
	v_add_f32_e32 v31, 1.0, v31
	v_add_f32_e32 v20, 1.0, v20
	v_add_f32_e32 v21, 1.0, v21
	v_add_f32_e32 v22, 1.0, v22
	v_add_f32_e32 v23, 1.0, v23
	v_add_f32_e32 v12, 1.0, v12
	v_add_f32_e32 v13, 1.0, v13
	v_add_f32_e32 v14, 1.0, v14
	v_add_f32_e32 v15, 1.0, v15
	v_add_f32_e32 v4, 1.0, v4
	v_add_f32_e32 v5, 1.0, v5
	v_add_f32_e32 v6, 1.0, v6
	v_add_f32_e32 v7, 1.0, v7
	v_rcp_f32_e32 v28, v28
	v_rcp_f32_e32 v29, v29
	v_rcp_f32_e32 v30, v30
	v_rcp_f32_e32 v31, v31
	v_rcp_f32_e32 v20, v20
	v_rcp_f32_e32 v21, v21
	v_rcp_f32_e32 v22, v22
	v_rcp_f32_e32 v23, v23
	v_rcp_f32_e32 v12, v12
	v_rcp_f32_e32 v13, v13
	v_rcp_f32_e32 v14, v14
	v_rcp_f32_e32 v15, v15
	v_rcp_f32_e32 v4, v4
	v_rcp_f32_e32 v5, v5
	v_rcp_f32_e32 v6, v6
	v_rcp_f32_e32 v7, v7
	v_pk_mul_f32 v[176:177], v[176:177], v[28:29]
	v_pk_mul_f32 v[178:179], v[178:179], v[30:31]
	v_pk_mul_f32 v[180:181], v[180:181], v[20:21]
	v_pk_mul_f32 v[182:183], v[182:183], v[22:23]
	v_pk_mul_f32 v[184:185], v[184:185], v[12:13]
	v_pk_mul_f32 v[186:187], v[186:187], v[14:15]
	v_pk_mul_f32 v[224:225], v[224:225], v[4:5]
	v_pk_mul_f32 v[226:227], v[226:227], v[6:7]
	v_pk_mul_f32 v[176:177], v[24:25], v[176:177]
	v_pk_mul_f32 v[178:179], v[26:27], v[178:179]
	v_pk_mul_f32 v[180:181], v[16:17], v[180:181]
	v_pk_mul_f32 v[182:183], v[18:19], v[182:183]
	v_pk_mul_f32 v[184:185], v[8:9], v[184:185]
	v_pk_mul_f32 v[186:187], v[10:11], v[186:187]
	v_pk_mul_f32 v[224:225], v[0:1], v[224:225]
	v_pk_mul_f32 v[226:227], v[2:3], v[226:227]
	v_cvt_pk_bf16_f32 v94, v176, v177
	v_cvt_pk_bf16_f32 v95, v178, v179
	v_cvt_pk_bf16_f32 v86, v180, v181
	v_cvt_pk_bf16_f32 v87, v182, v183
	v_cvt_pk_bf16_f32 v78, v184, v185
	v_cvt_pk_bf16_f32 v79, v186, v187
	v_cvt_pk_bf16_f32 v70, v224, v225
	v_cvt_pk_bf16_f32 v71, v226, v227
	s_nop 1
	v_permlane16_swap_b32_e32 v92, v94
	v_permlane16_swap_b32_e32 v93, v95
	v_permlane16_swap_b32_e32 v84, v86
	v_permlane16_swap_b32_e32 v85, v87
	v_permlane16_swap_b32_e32 v76, v78
	v_permlane16_swap_b32_e32 v77, v79
	v_permlane16_swap_b32_e32 v68, v70
	v_permlane16_swap_b32_e32 v69, v71
	global_store_dwordx4 v174, v[92:95], s[0:1] sc1
	v_add_u32_e32 v175, 0x2c00, v174
	global_store_dwordx4 v175, v[84:87], s[0:1] sc1
	v_add_u32_e32 v175, 0x5800, v174
	global_store_dwordx4 v175, v[76:79], s[0:1] sc1
	v_add_u32_e32 v175, 0x8400, v174
	global_store_dwordx4 v175, v[68:71], s[0:1] sc1
	v_lshl_or_b32 v170, s16, 7, v204
	v_lshlrev_b32_e32 v171, 2, v170
	v_add_u32_e32 v172, 0x5800, v171
	global_load_dwordx4 v[230:233], v172, s[56:57]
	global_load_dwordx4 v[234:237], v172, s[12:13]
	global_load_dwordx4 v[238:241], v172, s[14:15]
	global_load_dwordx4 v[242:245], v172, s[58:59]
	global_load_dwordx4 v[246:249], v171, s[56:57]
	global_load_dwordx4 v[250:253], v171, s[12:13]
	s_mov_b32 s98, 1
	s_andn2_b64 vcc, exec, s[20:21]
	s_mov_b64 s[20:21], -1
	s_cbranch_vccnz .LBB0_1795
	s_andn2_b64 vcc, exec, s[2:3]
	s_cbranch_vccnz .LBB0_1794
	s_barrier
	s_branch .LBB0_1794

; __device__ __forceinline__ unsigned xb_add(unsigned* p, unsigned v) { return __hip_atomic_fetch_add(p, v, __ATOMIC_RELAXED, __HIP_MEMORY_SCOPE_AGENT); }
; __device__ __forceinline__ void xcd_barrier(const XcdBarrier& b) {
;     ...
;         if (old + 1u == (gen + 1u) * nloc) {
;             __builtin_amdgcn_fence(__ATOMIC_RELEASE, "agent");
;             asm volatile("s_waitcnt vmcnt(0)" ::: "memory");
;             const unsigned og = xb_add(&bar[XB_TOP], 1u);
.LBB0_1844:
	s_andn2_saveexec_b64 s[8:9], s[8:9]
	s_cbranch_execz .LBB0_1864
	s_mov_b64 s[8:9], exec
	s_waitcnt lgkmcnt(0)
	s_waitcnt vmcnt(0)
	v_mbcnt_lo_u32_b32 v1, s8, 0
	v_mbcnt_hi_u32_b32 v1, s9, v1
	v_cmp_eq_u32_e32 vcc, 0, v1
	s_and_saveexec_b64 s[10:11], vcc
	s_cbranch_execz .LBB0_1847
	s_bcnt1_i32_b64 s8, s[8:9]
	v_mov_b32_e32 v2, 0x7000
	v_mov_b32_e32 v3, s8
	global_atomic_add v2, v2, v3, s[66:67] offset:1024 sc0
